# v066 plus code placement: every compute-segment MFMA run in the GEMM loops made 8-byte aligned by s_nop pads placed ahead of the load segments closing waits
# speedup vs baseline: 1.0006x; 1.0006x over previous
.LBB0_490:
	s_ashr_i32 s11, s10, 31
	s_lshl_b64 s[12:13], s[10:11], 20
	v_readlane_b32 s14, v253, 25
	v_readlane_b32 s15, v253, 26
	s_add_u32 s12, s14, s12
	s_addc_u32 s13, s15, s13
	s_and_b64 s[14:15], s[34:35], exec
	s_cselect_b32 s11, s13, s17
	s_cselect_b32 s49, s12, s16
	s_ashr_i32 s9, s8, 31
	s_lshl_b64 s[14:15], s[8:9], 20
	s_add_u32 s14, s25, s14
	s_addc_u32 s15, s36, s15
	s_and_b64 s[20:21], s[34:35], exec
	s_cselect_b32 s9, s15, s19
	s_cselect_b32 s50, s14, s18
	s_add_u32 s16, s16, 0x80080
	s_addc_u32 s17, s17, 0
	s_add_u32 s51, s18, 0x100
	s_addc_u32 s52, s19, 0
	s_mov_b32 s53, -2
	s_add_u32 s18, s16, 0xfff80080
	s_addc_u32 s19, s17, -1
	s_add_i32 s54, 0, 0x10000
	s_cmp_eq_u32 s53, 28
	s_cselect_b32 s21, s11, s19
	s_cselect_b32 s20, s49, s18
	s_cselect_b32 s19, s9, s52
	s_cselect_b32 s18, s50, s51
	s_add_i32 s56, 0, 0x14000
	v_add_u32_e32 v156, s54, v141
	v_add_u32_e32 v172, s56, v141
	ds_read_b128 v[144:147], v156
	ds_read_b128 v[148:151], v156 offset:1024
	ds_read_b128 v[152:155], v156 offset:2048
	ds_read_b128 v[156:159], v156 offset:3072
	ds_read_b128 v[160:163], v172
	ds_read_b128 v[164:167], v172 offset:1024
	ds_read_b128 v[168:171], v172 offset:2048
	ds_read_b128 v[172:175], v172 offset:3072
	v_lshl_add_u64 v[208:209], s[16:17], 0, v[136:137]
	s_add_i32 m0, s39, 0xc000
	ds_read_b128 v[176:179], v143
	ds_read_b128 v[180:183], v143 offset:1024
	ds_read_b128 v[184:187], v143 offset:2048
	ds_read_b128 v[188:191], v143 offset:3072
	ds_read_b128 v[192:195], v143 offset:4096
	ds_read_b128 v[196:199], v143 offset:5120
	ds_read_b128 v[200:203], v143 offset:6144
	ds_read_b128 v[204:207], v143 offset:7168
	global_load_lds_dwordx4 v[208:209], off
	v_lshl_add_u64 v[208:209], s[16:17], 0, v[138:139]
	s_add_i32 m0, s39, 0xe000
	s_nop 0
	global_load_lds_dwordx4 v[208:209], off
	s_nop 0
	s_waitcnt vmcnt(8)
	s_waitcnt lgkmcnt(0)
	s_setprio 1
	s_barrier
	v_mfma_f32_16x16x32_bf16 v[126:129], v[144:147], v[176:179], 0
	v_mfma_f32_16x16x32_bf16 v[122:125], v[152:155], v[176:179], 0
	v_mfma_f32_16x16x32_bf16 v[118:121], v[144:147], v[184:187], 0
	v_mfma_f32_16x16x32_bf16 v[114:117], v[152:155], v[184:187], 0
	v_mfma_f32_16x16x32_bf16 v[102:105], v[144:147], v[192:195], 0
	v_mfma_f32_16x16x32_bf16 v[98:101], v[152:155], v[192:195], 0
	v_mfma_f32_16x16x32_bf16 v[86:89], v[144:147], v[200:203], 0
	v_mfma_f32_16x16x32_bf16 v[82:85], v[152:155], v[200:203], 0
	v_mfma_f32_16x16x32_bf16 v[126:129], v[148:151], v[180:183], v[126:129]
	v_mfma_f32_16x16x32_bf16 v[122:125], v[156:159], v[180:183], v[122:125]
	v_mfma_f32_16x16x32_bf16 v[118:121], v[148:151], v[188:191], v[118:121]
	v_mfma_f32_16x16x32_bf16 v[114:117], v[156:159], v[188:191], v[114:117]
	v_mfma_f32_16x16x32_bf16 v[102:105], v[148:151], v[196:199], v[102:105]
	v_mfma_f32_16x16x32_bf16 v[98:101], v[156:159], v[196:199], v[98:101]
	v_mfma_f32_16x16x32_bf16 v[86:89], v[148:151], v[204:207], v[86:89]
	v_mfma_f32_16x16x32_bf16 v[82:85], v[156:159], v[204:207], v[82:85]
	s_setprio 0
	s_setprio 1
	v_mfma_f32_16x16x32_bf16 v[110:113], v[160:163], v[176:179], 0
	v_mfma_f32_16x16x32_bf16 v[106:109], v[168:171], v[176:179], 0
	v_mfma_f32_16x16x32_bf16 v[94:97], v[160:163], v[184:187], 0
	v_mfma_f32_16x16x32_bf16 v[90:93], v[168:171], v[184:187], 0
	v_mfma_f32_16x16x32_bf16 v[78:81], v[160:163], v[192:195], 0
	v_mfma_f32_16x16x32_bf16 v[74:77], v[168:171], v[192:195], 0
	v_mfma_f32_16x16x32_bf16 v[70:73], v[160:163], v[200:203], 0
	v_mfma_f32_16x16x32_bf16 v[66:69], v[168:171], v[200:203], 0
	v_mfma_f32_16x16x32_bf16 v[110:113], v[164:167], v[180:183], v[110:113]
	v_mfma_f32_16x16x32_bf16 v[106:109], v[172:175], v[180:183], v[106:109]
	v_mfma_f32_16x16x32_bf16 v[94:97], v[164:167], v[188:191], v[94:97]
	v_mfma_f32_16x16x32_bf16 v[90:93], v[172:175], v[188:191], v[90:93]
	v_mfma_f32_16x16x32_bf16 v[78:81], v[164:167], v[196:199], v[78:81]
	v_mfma_f32_16x16x32_bf16 v[74:77], v[172:175], v[196:199], v[74:77]
	v_mfma_f32_16x16x32_bf16 v[70:73], v[164:167], v[204:207], v[70:73]
	v_mfma_f32_16x16x32_bf16 v[66:69], v[172:175], v[204:207], v[66:69]
	s_barrier
	s_setprio 0
	s_add_i32 s54, s54, s37
	v_lshl_add_u64 v[208:209], s[18:19], 0, v[0:1]
	s_mov_b32 m0, s54
	ds_read_b128 v[176:179], v143 offset:16384
	ds_read_b128 v[180:183], v143 offset:17408
	ds_read_b128 v[184:187], v143 offset:18432
	ds_read_b128 v[188:191], v143 offset:19456
	ds_read_b128 v[192:195], v143 offset:20480
	ds_read_b128 v[196:199], v143 offset:21504
	ds_read_b128 v[200:203], v143 offset:22528
	ds_read_b128 v[204:207], v143 offset:23552
	global_load_lds_dwordx4 v[208:209], off
	s_add_i32 m0, s54, 0x2000
	s_add_u32 s54, s18, 0x80000
	v_lshl_add_u64 v[220:221], s[18:19], 0, v[130:131]
	s_addc_u32 s55, s19, 0
	s_add_i32 s56, s56, s37
	global_load_lds_dwordx4 v[220:221], off
	v_lshl_add_u64 v[222:223], s[54:55], 0, v[0:1]
	s_mov_b32 m0, s56
	v_lshl_add_u64 v[224:225], s[20:21], 0, v[132:133]
	global_load_lds_dwordx4 v[222:223], off
	v_lshl_add_u64 v[222:223], s[54:55], 0, v[130:131]
	s_add_i32 m0, s56, 0x2000
	s_nop 0
	global_load_lds_dwordx4 v[222:223], off
	v_lshl_add_u64 v[222:223], s[20:21], 0, v[134:135]
	s_mov_b32 m0, s39
	s_nop 0
	global_load_lds_dwordx4 v[222:223], off
	s_mov_b32 m0, s40
	s_nop 0
	global_load_lds_dwordx4 v[224:225], off
	s_waitcnt vmcnt(8)
	s_waitcnt lgkmcnt(0)
	s_setprio 1
	s_barrier
	v_mfma_f32_16x16x32_bf16 v[62:65], v[144:147], v[176:179], 0
	v_mfma_f32_16x16x32_bf16 v[58:61], v[152:155], v[176:179], 0
	v_mfma_f32_16x16x32_bf16 v[54:57], v[144:147], v[184:187], 0
	v_mfma_f32_16x16x32_bf16 v[50:53], v[152:155], v[184:187], 0
	v_mfma_f32_16x16x32_bf16 v[38:41], v[144:147], v[192:195], 0
	v_mfma_f32_16x16x32_bf16 v[34:37], v[152:155], v[192:195], 0
	v_mfma_f32_16x16x32_bf16 v[22:25], v[144:147], v[200:203], 0
	v_mfma_f32_16x16x32_bf16 v[18:21], v[152:155], v[200:203], 0
	v_mfma_f32_16x16x32_bf16 v[62:65], v[148:151], v[180:183], v[62:65]
	v_mfma_f32_16x16x32_bf16 v[58:61], v[156:159], v[180:183], v[58:61]
	v_mfma_f32_16x16x32_bf16 v[54:57], v[148:151], v[188:191], v[54:57]
	v_mfma_f32_16x16x32_bf16 v[50:53], v[156:159], v[188:191], v[50:53]
	v_mfma_f32_16x16x32_bf16 v[38:41], v[148:151], v[196:199], v[38:41]
	v_mfma_f32_16x16x32_bf16 v[34:37], v[156:159], v[196:199], v[34:37]
	v_mfma_f32_16x16x32_bf16 v[22:25], v[148:151], v[204:207], v[22:25]
	v_mfma_f32_16x16x32_bf16 v[18:21], v[156:159], v[204:207], v[18:21]
	s_setprio 0
	s_setprio 1
	v_mfma_f32_16x16x32_bf16 v[46:49], v[160:163], v[176:179], 0
	v_mfma_f32_16x16x32_bf16 v[42:45], v[168:171], v[176:179], 0
	v_mfma_f32_16x16x32_bf16 v[30:33], v[160:163], v[184:187], 0
	v_mfma_f32_16x16x32_bf16 v[26:29], v[168:171], v[184:187], 0
	v_mfma_f32_16x16x32_bf16 v[14:17], v[160:163], v[192:195], 0
	v_mfma_f32_16x16x32_bf16 v[10:13], v[168:171], v[192:195], 0
	v_mfma_f32_16x16x32_bf16 v[6:9], v[160:163], v[200:203], 0
	v_mfma_f32_16x16x32_bf16 v[2:5], v[168:171], v[200:203], 0
	v_mfma_f32_16x16x32_bf16 v[46:49], v[164:167], v[180:183], v[46:49]
	v_mfma_f32_16x16x32_bf16 v[42:45], v[172:175], v[180:183], v[42:45]
	v_mfma_f32_16x16x32_bf16 v[30:33], v[164:167], v[188:191], v[30:33]
	v_mfma_f32_16x16x32_bf16 v[26:29], v[172:175], v[188:191], v[26:29]
	v_mfma_f32_16x16x32_bf16 v[14:17], v[164:167], v[196:199], v[14:17]
	v_mfma_f32_16x16x32_bf16 v[10:13], v[172:175], v[196:199], v[10:13]
	v_mfma_f32_16x16x32_bf16 v[6:9], v[164:167], v[204:207], v[6:9]
	v_mfma_f32_16x16x32_bf16 v[2:5], v[172:175], v[204:207], v[2:5]
	s_barrier
	s_setprio 0
	s_add_i32 s54, 0, 0x18000
	s_add_i32 s55, 0, 0x1c000
	v_add_u32_e32 v156, s54, v141
	v_add_u32_e32 v172, s55, v141
	ds_read_b128 v[144:147], v156
	ds_read_b128 v[148:151], v156 offset:1024
	ds_read_b128 v[152:155], v156 offset:2048
	ds_read_b128 v[156:159], v156 offset:3072
	ds_read_b128 v[160:163], v172
	ds_read_b128 v[164:167], v172 offset:1024
	ds_read_b128 v[168:171], v172 offset:2048
	ds_read_b128 v[172:175], v172 offset:3072
	s_add_u32 s20, s20, 0x80000
	s_addc_u32 s21, s21, 0
	s_mov_b32 m0, s41
	v_lshl_add_u64 v[226:227], s[20:21], 0, v[134:135]
	ds_read_b128 v[176:179], v143 offset:32768
	ds_read_b128 v[180:183], v143 offset:33792
	ds_read_b128 v[184:187], v143 offset:34816
	ds_read_b128 v[188:191], v143 offset:35840
	ds_read_b128 v[192:195], v143 offset:36864
	ds_read_b128 v[196:199], v143 offset:37888
	ds_read_b128 v[200:203], v143 offset:38912
	ds_read_b128 v[204:207], v143 offset:39936
	global_load_lds_dwordx4 v[226:227], off
	v_lshl_add_u64 v[226:227], s[20:21], 0, v[132:133]
	s_mov_b32 m0, s44
	s_nop 0
	global_load_lds_dwordx4 v[226:227], off
	s_waitcnt vmcnt(8)
	s_waitcnt lgkmcnt(0)
	s_setprio 1
	s_barrier
	v_mfma_f32_16x16x32_bf16 v[126:129], v[144:147], v[176:179], v[126:129]
	v_mfma_f32_16x16x32_bf16 v[122:125], v[152:155], v[176:179], v[122:125]
	v_mfma_f32_16x16x32_bf16 v[118:121], v[144:147], v[184:187], v[118:121]
	v_mfma_f32_16x16x32_bf16 v[114:117], v[152:155], v[184:187], v[114:117]
	v_mfma_f32_16x16x32_bf16 v[102:105], v[144:147], v[192:195], v[102:105]
	v_mfma_f32_16x16x32_bf16 v[98:101], v[152:155], v[192:195], v[98:101]
	v_mfma_f32_16x16x32_bf16 v[86:89], v[144:147], v[200:203], v[86:89]
	v_mfma_f32_16x16x32_bf16 v[82:85], v[152:155], v[200:203], v[82:85]
	v_mfma_f32_16x16x32_bf16 v[126:129], v[148:151], v[180:183], v[126:129]
	v_mfma_f32_16x16x32_bf16 v[122:125], v[156:159], v[180:183], v[122:125]
	v_mfma_f32_16x16x32_bf16 v[118:121], v[148:151], v[188:191], v[118:121]
	v_mfma_f32_16x16x32_bf16 v[114:117], v[156:159], v[188:191], v[114:117]
	v_mfma_f32_16x16x32_bf16 v[102:105], v[148:151], v[196:199], v[102:105]
	v_mfma_f32_16x16x32_bf16 v[98:101], v[156:159], v[196:199], v[98:101]
	v_mfma_f32_16x16x32_bf16 v[86:89], v[148:151], v[204:207], v[86:89]
	v_mfma_f32_16x16x32_bf16 v[82:85], v[156:159], v[204:207], v[82:85]
	s_setprio 0
	s_setprio 1
	v_mfma_f32_16x16x32_bf16 v[110:113], v[160:163], v[176:179], v[110:113]
	v_mfma_f32_16x16x32_bf16 v[106:109], v[168:171], v[176:179], v[106:109]
	v_mfma_f32_16x16x32_bf16 v[94:97], v[160:163], v[184:187], v[94:97]
	v_mfma_f32_16x16x32_bf16 v[90:93], v[168:171], v[184:187], v[90:93]
	v_mfma_f32_16x16x32_bf16 v[78:81], v[160:163], v[192:195], v[78:81]
	v_mfma_f32_16x16x32_bf16 v[74:77], v[168:171], v[192:195], v[74:77]
	v_mfma_f32_16x16x32_bf16 v[70:73], v[160:163], v[200:203], v[70:73]
	v_mfma_f32_16x16x32_bf16 v[66:69], v[168:171], v[200:203], v[66:69]
	v_mfma_f32_16x16x32_bf16 v[110:113], v[164:167], v[180:183], v[110:113]
	v_mfma_f32_16x16x32_bf16 v[106:109], v[172:175], v[180:183], v[106:109]
	v_mfma_f32_16x16x32_bf16 v[94:97], v[164:167], v[188:191], v[94:97]
	v_mfma_f32_16x16x32_bf16 v[90:93], v[172:175], v[188:191], v[90:93]
	v_mfma_f32_16x16x32_bf16 v[78:81], v[164:167], v[196:199], v[78:81]
	v_mfma_f32_16x16x32_bf16 v[74:77], v[172:175], v[196:199], v[74:77]
	v_mfma_f32_16x16x32_bf16 v[70:73], v[164:167], v[204:207], v[70:73]
	v_mfma_f32_16x16x32_bf16 v[66:69], v[172:175], v[204:207], v[66:69]
	s_barrier
	s_setprio 0
	s_add_i32 s20, s54, s37
	v_lshl_add_u64 v[208:209], v[208:209], 0, s[2:3]
	s_mov_b32 m0, s20
	ds_read_b128 v[176:179], v143 offset:49152
	ds_read_b128 v[180:183], v143 offset:50176
	ds_read_b128 v[184:187], v143 offset:51200
	ds_read_b128 v[188:191], v143 offset:52224
	ds_read_b128 v[192:195], v143 offset:53248
	ds_read_b128 v[196:199], v143 offset:54272
	ds_read_b128 v[200:203], v143 offset:55296
	ds_read_b128 v[204:207], v143 offset:56320
	global_load_lds_dwordx4 v[208:209], off
	s_add_i32 m0, s20, 0x2000
	s_add_u32 s18, s18, 0x80080
	v_lshl_add_u64 v[208:209], v[220:221], 0, s[2:3]
	s_addc_u32 s19, s19, 0
	s_add_i32 s20, s55, s37
	global_load_lds_dwordx4 v[208:209], off
	v_lshl_add_u64 v[208:209], s[18:19], 0, v[0:1]
	s_mov_b32 m0, s20
	s_nop 0
	global_load_lds_dwordx4 v[208:209], off
	v_lshl_add_u64 v[208:209], s[18:19], 0, v[130:131]
	s_add_i32 m0, s20, 0x2000
	s_nop 0
	global_load_lds_dwordx4 v[208:209], off
	v_lshl_add_u64 v[208:209], v[222:223], 0, s[2:3]
	s_mov_b32 m0, s45
	s_nop 0
	global_load_lds_dwordx4 v[208:209], off
	v_lshl_add_u64 v[208:209], v[224:225], 0, s[2:3]
	s_mov_b32 m0, s46
	s_nop 0
	global_load_lds_dwordx4 v[208:209], off
	s_nop 0
	s_waitcnt vmcnt(8)
	s_waitcnt lgkmcnt(0)
	s_setprio 1
	s_barrier
	v_mfma_f32_16x16x32_bf16 v[62:65], v[144:147], v[176:179], v[62:65]
	v_mfma_f32_16x16x32_bf16 v[58:61], v[152:155], v[176:179], v[58:61]
	v_mfma_f32_16x16x32_bf16 v[54:57], v[144:147], v[184:187], v[54:57]
	v_mfma_f32_16x16x32_bf16 v[50:53], v[152:155], v[184:187], v[50:53]
	v_mfma_f32_16x16x32_bf16 v[38:41], v[144:147], v[192:195], v[38:41]
	v_mfma_f32_16x16x32_bf16 v[34:37], v[152:155], v[192:195], v[34:37]
	v_mfma_f32_16x16x32_bf16 v[22:25], v[144:147], v[200:203], v[22:25]
	v_mfma_f32_16x16x32_bf16 v[18:21], v[152:155], v[200:203], v[18:21]
	v_mfma_f32_16x16x32_bf16 v[62:65], v[148:151], v[180:183], v[62:65]
	v_mfma_f32_16x16x32_bf16 v[58:61], v[156:159], v[180:183], v[58:61]
	v_mfma_f32_16x16x32_bf16 v[54:57], v[148:151], v[188:191], v[54:57]
	v_mfma_f32_16x16x32_bf16 v[50:53], v[156:159], v[188:191], v[50:53]
	v_mfma_f32_16x16x32_bf16 v[38:41], v[148:151], v[196:199], v[38:41]
	v_mfma_f32_16x16x32_bf16 v[34:37], v[156:159], v[196:199], v[34:37]
	v_mfma_f32_16x16x32_bf16 v[22:25], v[148:151], v[204:207], v[22:25]
	v_mfma_f32_16x16x32_bf16 v[18:21], v[156:159], v[204:207], v[18:21]
	s_setprio 0
	s_setprio 1
	v_mfma_f32_16x16x32_bf16 v[46:49], v[160:163], v[176:179], v[46:49]
	v_mfma_f32_16x16x32_bf16 v[42:45], v[168:171], v[176:179], v[42:45]
	v_mfma_f32_16x16x32_bf16 v[30:33], v[160:163], v[184:187], v[30:33]
	v_mfma_f32_16x16x32_bf16 v[26:29], v[168:171], v[184:187], v[26:29]
	v_mfma_f32_16x16x32_bf16 v[14:17], v[160:163], v[192:195], v[14:17]
	v_mfma_f32_16x16x32_bf16 v[10:13], v[168:171], v[192:195], v[10:13]
	v_mfma_f32_16x16x32_bf16 v[6:9], v[160:163], v[200:203], v[6:9]
	v_mfma_f32_16x16x32_bf16 v[2:5], v[168:171], v[200:203], v[2:5]
	v_mfma_f32_16x16x32_bf16 v[46:49], v[164:167], v[180:183], v[46:49]
	v_mfma_f32_16x16x32_bf16 v[42:45], v[172:175], v[180:183], v[42:45]
	v_mfma_f32_16x16x32_bf16 v[30:33], v[164:167], v[188:191], v[30:33]
	v_mfma_f32_16x16x32_bf16 v[26:29], v[172:175], v[188:191], v[26:29]
	v_mfma_f32_16x16x32_bf16 v[14:17], v[164:167], v[196:199], v[14:17]
	v_mfma_f32_16x16x32_bf16 v[10:13], v[172:175], v[196:199], v[10:13]
	v_mfma_f32_16x16x32_bf16 v[6:9], v[164:167], v[204:207], v[6:9]
	v_mfma_f32_16x16x32_bf16 v[2:5], v[172:175], v[204:207], v[2:5]
	s_barrier
	s_setprio 0
	s_add_i32 s53, s53, 2
	s_add_u32 s16, s16, 0x100
	s_addc_u32 s17, s17, 0
	s_add_u32 s51, s51, 0x100
	s_addc_u32 s52, s52, 0
	s_cmp_gt_u32 s53, 29
	s_cbranch_scc1 .Lpeel_done_0
.LBB0_491:
	s_add_u32 s18, s16, 0xfff80080
	s_addc_u32 s19, s17, -1
	s_add_i32 s54, 0, 0x10000
	s_cmp_eq_u32 s53, 28
	s_cselect_b32 s21, s11, s19
	s_cselect_b32 s20, s49, s18
	s_cselect_b32 s19, s9, s52
	s_cselect_b32 s18, s50, s51
	s_add_i32 s56, 0, 0x14000
	v_add_u32_e32 v156, s54, v141
	v_add_u32_e32 v172, s56, v141
	ds_read_b128 v[144:147], v156
	ds_read_b128 v[148:151], v156 offset:1024
	ds_read_b128 v[152:155], v156 offset:2048
	ds_read_b128 v[156:159], v156 offset:3072
	ds_read_b128 v[160:163], v172
	ds_read_b128 v[164:167], v172 offset:1024
	ds_read_b128 v[168:171], v172 offset:2048
	ds_read_b128 v[172:175], v172 offset:3072
	v_lshl_add_u64 v[208:209], s[16:17], 0, v[136:137]
	s_add_i32 m0, s39, 0xc000
	ds_read_b128 v[176:179], v143
	ds_read_b128 v[180:183], v143 offset:1024
	ds_read_b128 v[184:187], v143 offset:2048
	ds_read_b128 v[188:191], v143 offset:3072
	ds_read_b128 v[192:195], v143 offset:4096
	ds_read_b128 v[196:199], v143 offset:5120
	ds_read_b128 v[200:203], v143 offset:6144
	ds_read_b128 v[204:207], v143 offset:7168
	global_load_lds_dwordx4 v[208:209], off
	v_lshl_add_u64 v[208:209], s[16:17], 0, v[138:139]
	s_add_i32 m0, s39, 0xe000
	s_nop 0
	global_load_lds_dwordx4 v[208:209], off
	s_waitcnt vmcnt(8)
	s_waitcnt lgkmcnt(0)
	s_setprio 1
	s_barrier
	v_mfma_f32_16x16x32_bf16 v[126:129], v[144:147], v[176:179], v[126:129]
	v_mfma_f32_16x16x32_bf16 v[122:125], v[152:155], v[176:179], v[122:125]
	v_mfma_f32_16x16x32_bf16 v[118:121], v[144:147], v[184:187], v[118:121]
	v_mfma_f32_16x16x32_bf16 v[114:117], v[152:155], v[184:187], v[114:117]
	v_mfma_f32_16x16x32_bf16 v[102:105], v[144:147], v[192:195], v[102:105]
	v_mfma_f32_16x16x32_bf16 v[98:101], v[152:155], v[192:195], v[98:101]
	v_mfma_f32_16x16x32_bf16 v[86:89], v[144:147], v[200:203], v[86:89]
	v_mfma_f32_16x16x32_bf16 v[82:85], v[152:155], v[200:203], v[82:85]
	v_mfma_f32_16x16x32_bf16 v[126:129], v[148:151], v[180:183], v[126:129]
	v_mfma_f32_16x16x32_bf16 v[122:125], v[156:159], v[180:183], v[122:125]
	v_mfma_f32_16x16x32_bf16 v[118:121], v[148:151], v[188:191], v[118:121]
	v_mfma_f32_16x16x32_bf16 v[114:117], v[156:159], v[188:191], v[114:117]
	v_mfma_f32_16x16x32_bf16 v[102:105], v[148:151], v[196:199], v[102:105]
	v_mfma_f32_16x16x32_bf16 v[98:101], v[156:159], v[196:199], v[98:101]
	v_mfma_f32_16x16x32_bf16 v[86:89], v[148:151], v[204:207], v[86:89]
	v_mfma_f32_16x16x32_bf16 v[82:85], v[156:159], v[204:207], v[82:85]
	s_setprio 0
	s_setprio 1
	v_mfma_f32_16x16x32_bf16 v[110:113], v[160:163], v[176:179], v[110:113]
	v_mfma_f32_16x16x32_bf16 v[106:109], v[168:171], v[176:179], v[106:109]
	v_mfma_f32_16x16x32_bf16 v[94:97], v[160:163], v[184:187], v[94:97]
	v_mfma_f32_16x16x32_bf16 v[90:93], v[168:171], v[184:187], v[90:93]
	v_mfma_f32_16x16x32_bf16 v[78:81], v[160:163], v[192:195], v[78:81]
	v_mfma_f32_16x16x32_bf16 v[74:77], v[168:171], v[192:195], v[74:77]
	v_mfma_f32_16x16x32_bf16 v[70:73], v[160:163], v[200:203], v[70:73]
	v_mfma_f32_16x16x32_bf16 v[66:69], v[168:171], v[200:203], v[66:69]
	v_mfma_f32_16x16x32_bf16 v[110:113], v[164:167], v[180:183], v[110:113]
	v_mfma_f32_16x16x32_bf16 v[106:109], v[172:175], v[180:183], v[106:109]
	v_mfma_f32_16x16x32_bf16 v[94:97], v[164:167], v[188:191], v[94:97]
	v_mfma_f32_16x16x32_bf16 v[90:93], v[172:175], v[188:191], v[90:93]
	v_mfma_f32_16x16x32_bf16 v[78:81], v[164:167], v[196:199], v[78:81]
	v_mfma_f32_16x16x32_bf16 v[74:77], v[172:175], v[196:199], v[74:77]
	v_mfma_f32_16x16x32_bf16 v[70:73], v[164:167], v[204:207], v[70:73]
	v_mfma_f32_16x16x32_bf16 v[66:69], v[172:175], v[204:207], v[66:69]
	s_barrier
	s_setprio 0
	s_add_i32 s54, s54, s37
	v_lshl_add_u64 v[208:209], s[18:19], 0, v[0:1]
	s_mov_b32 m0, s54
	ds_read_b128 v[176:179], v143 offset:16384
	ds_read_b128 v[180:183], v143 offset:17408
	ds_read_b128 v[184:187], v143 offset:18432
	ds_read_b128 v[188:191], v143 offset:19456
	ds_read_b128 v[192:195], v143 offset:20480
	ds_read_b128 v[196:199], v143 offset:21504
	ds_read_b128 v[200:203], v143 offset:22528
	ds_read_b128 v[204:207], v143 offset:23552
	global_load_lds_dwordx4 v[208:209], off
	s_add_i32 m0, s54, 0x2000
	s_add_u32 s54, s18, 0x80000
	v_lshl_add_u64 v[220:221], s[18:19], 0, v[130:131]
	s_addc_u32 s55, s19, 0
	s_add_i32 s56, s56, s37
	global_load_lds_dwordx4 v[220:221], off
	v_lshl_add_u64 v[222:223], s[54:55], 0, v[0:1]
	s_mov_b32 m0, s56
	v_lshl_add_u64 v[224:225], s[20:21], 0, v[132:133]
	global_load_lds_dwordx4 v[222:223], off
	v_lshl_add_u64 v[222:223], s[54:55], 0, v[130:131]
	s_add_i32 m0, s56, 0x2000
	s_nop 0
	global_load_lds_dwordx4 v[222:223], off
	v_lshl_add_u64 v[222:223], s[20:21], 0, v[134:135]
	s_mov_b32 m0, s39
	s_nop 0
	global_load_lds_dwordx4 v[222:223], off
	s_mov_b32 m0, s40
	s_nop 0
	global_load_lds_dwordx4 v[224:225], off
	s_waitcnt vmcnt(8)
	s_waitcnt lgkmcnt(0)
	s_setprio 1
	s_barrier
	v_mfma_f32_16x16x32_bf16 v[62:65], v[144:147], v[176:179], v[62:65]
	v_mfma_f32_16x16x32_bf16 v[58:61], v[152:155], v[176:179], v[58:61]
	v_mfma_f32_16x16x32_bf16 v[54:57], v[144:147], v[184:187], v[54:57]
	v_mfma_f32_16x16x32_bf16 v[50:53], v[152:155], v[184:187], v[50:53]
	v_mfma_f32_16x16x32_bf16 v[38:41], v[144:147], v[192:195], v[38:41]
	v_mfma_f32_16x16x32_bf16 v[34:37], v[152:155], v[192:195], v[34:37]
	v_mfma_f32_16x16x32_bf16 v[22:25], v[144:147], v[200:203], v[22:25]
	v_mfma_f32_16x16x32_bf16 v[18:21], v[152:155], v[200:203], v[18:21]
	v_mfma_f32_16x16x32_bf16 v[62:65], v[148:151], v[180:183], v[62:65]
	v_mfma_f32_16x16x32_bf16 v[58:61], v[156:159], v[180:183], v[58:61]
	v_mfma_f32_16x16x32_bf16 v[54:57], v[148:151], v[188:191], v[54:57]
	v_mfma_f32_16x16x32_bf16 v[50:53], v[156:159], v[188:191], v[50:53]
	v_mfma_f32_16x16x32_bf16 v[38:41], v[148:151], v[196:199], v[38:41]
	v_mfma_f32_16x16x32_bf16 v[34:37], v[156:159], v[196:199], v[34:37]
	v_mfma_f32_16x16x32_bf16 v[22:25], v[148:151], v[204:207], v[22:25]
	v_mfma_f32_16x16x32_bf16 v[18:21], v[156:159], v[204:207], v[18:21]
	s_setprio 0
	s_setprio 1
	v_mfma_f32_16x16x32_bf16 v[46:49], v[160:163], v[176:179], v[46:49]
	v_mfma_f32_16x16x32_bf16 v[42:45], v[168:171], v[176:179], v[42:45]
	v_mfma_f32_16x16x32_bf16 v[30:33], v[160:163], v[184:187], v[30:33]
	v_mfma_f32_16x16x32_bf16 v[26:29], v[168:171], v[184:187], v[26:29]
	v_mfma_f32_16x16x32_bf16 v[14:17], v[160:163], v[192:195], v[14:17]
	v_mfma_f32_16x16x32_bf16 v[10:13], v[168:171], v[192:195], v[10:13]
	v_mfma_f32_16x16x32_bf16 v[6:9], v[160:163], v[200:203], v[6:9]
	v_mfma_f32_16x16x32_bf16 v[2:5], v[168:171], v[200:203], v[2:5]
	v_mfma_f32_16x16x32_bf16 v[46:49], v[164:167], v[180:183], v[46:49]
	v_mfma_f32_16x16x32_bf16 v[42:45], v[172:175], v[180:183], v[42:45]
	v_mfma_f32_16x16x32_bf16 v[30:33], v[164:167], v[188:191], v[30:33]
	v_mfma_f32_16x16x32_bf16 v[26:29], v[172:175], v[188:191], v[26:29]
	v_mfma_f32_16x16x32_bf16 v[14:17], v[164:167], v[196:199], v[14:17]
	v_mfma_f32_16x16x32_bf16 v[10:13], v[172:175], v[196:199], v[10:13]
	v_mfma_f32_16x16x32_bf16 v[6:9], v[164:167], v[204:207], v[6:9]
	v_mfma_f32_16x16x32_bf16 v[2:5], v[172:175], v[204:207], v[2:5]
	s_barrier
	s_setprio 0
	s_add_i32 s54, 0, 0x18000
	s_add_i32 s55, 0, 0x1c000
	v_add_u32_e32 v156, s54, v141
	v_add_u32_e32 v172, s55, v141
	ds_read_b128 v[144:147], v156
	ds_read_b128 v[148:151], v156 offset:1024
	ds_read_b128 v[152:155], v156 offset:2048
	ds_read_b128 v[156:159], v156 offset:3072
	ds_read_b128 v[160:163], v172
	ds_read_b128 v[164:167], v172 offset:1024
	ds_read_b128 v[168:171], v172 offset:2048
	ds_read_b128 v[172:175], v172 offset:3072
	s_add_u32 s20, s20, 0x80000
	s_addc_u32 s21, s21, 0
	s_mov_b32 m0, s41
	v_lshl_add_u64 v[226:227], s[20:21], 0, v[134:135]
	ds_read_b128 v[176:179], v143 offset:32768
	ds_read_b128 v[180:183], v143 offset:33792
	ds_read_b128 v[184:187], v143 offset:34816
	ds_read_b128 v[188:191], v143 offset:35840
	ds_read_b128 v[192:195], v143 offset:36864
	ds_read_b128 v[196:199], v143 offset:37888
	ds_read_b128 v[200:203], v143 offset:38912
	ds_read_b128 v[204:207], v143 offset:39936
	global_load_lds_dwordx4 v[226:227], off
	v_lshl_add_u64 v[226:227], s[20:21], 0, v[132:133]
	s_mov_b32 m0, s44
	s_nop 0
	global_load_lds_dwordx4 v[226:227], off
	s_waitcnt vmcnt(8)
	s_waitcnt lgkmcnt(0)
	s_setprio 1
	s_barrier
	v_mfma_f32_16x16x32_bf16 v[126:129], v[144:147], v[176:179], v[126:129]
	v_mfma_f32_16x16x32_bf16 v[122:125], v[152:155], v[176:179], v[122:125]
	v_mfma_f32_16x16x32_bf16 v[118:121], v[144:147], v[184:187], v[118:121]
	v_mfma_f32_16x16x32_bf16 v[114:117], v[152:155], v[184:187], v[114:117]
	v_mfma_f32_16x16x32_bf16 v[102:105], v[144:147], v[192:195], v[102:105]
	v_mfma_f32_16x16x32_bf16 v[98:101], v[152:155], v[192:195], v[98:101]
	v_mfma_f32_16x16x32_bf16 v[86:89], v[144:147], v[200:203], v[86:89]
	v_mfma_f32_16x16x32_bf16 v[82:85], v[152:155], v[200:203], v[82:85]
	v_mfma_f32_16x16x32_bf16 v[126:129], v[148:151], v[180:183], v[126:129]
	v_mfma_f32_16x16x32_bf16 v[122:125], v[156:159], v[180:183], v[122:125]
	v_mfma_f32_16x16x32_bf16 v[118:121], v[148:151], v[188:191], v[118:121]
	v_mfma_f32_16x16x32_bf16 v[114:117], v[156:159], v[188:191], v[114:117]
	v_mfma_f32_16x16x32_bf16 v[102:105], v[148:151], v[196:199], v[102:105]
	v_mfma_f32_16x16x32_bf16 v[98:101], v[156:159], v[196:199], v[98:101]
	v_mfma_f32_16x16x32_bf16 v[86:89], v[148:151], v[204:207], v[86:89]
	v_mfma_f32_16x16x32_bf16 v[82:85], v[156:159], v[204:207], v[82:85]
	s_setprio 0
	s_setprio 1
	v_mfma_f32_16x16x32_bf16 v[110:113], v[160:163], v[176:179], v[110:113]
	v_mfma_f32_16x16x32_bf16 v[106:109], v[168:171], v[176:179], v[106:109]
	v_mfma_f32_16x16x32_bf16 v[94:97], v[160:163], v[184:187], v[94:97]
	v_mfma_f32_16x16x32_bf16 v[90:93], v[168:171], v[184:187], v[90:93]
	v_mfma_f32_16x16x32_bf16 v[78:81], v[160:163], v[192:195], v[78:81]
	v_mfma_f32_16x16x32_bf16 v[74:77], v[168:171], v[192:195], v[74:77]
	v_mfma_f32_16x16x32_bf16 v[70:73], v[160:163], v[200:203], v[70:73]
	v_mfma_f32_16x16x32_bf16 v[66:69], v[168:171], v[200:203], v[66:69]
	v_mfma_f32_16x16x32_bf16 v[110:113], v[164:167], v[180:183], v[110:113]
	v_mfma_f32_16x16x32_bf16 v[106:109], v[172:175], v[180:183], v[106:109]
	v_mfma_f32_16x16x32_bf16 v[94:97], v[164:167], v[188:191], v[94:97]
	v_mfma_f32_16x16x32_bf16 v[90:93], v[172:175], v[188:191], v[90:93]
	v_mfma_f32_16x16x32_bf16 v[78:81], v[164:167], v[196:199], v[78:81]
	v_mfma_f32_16x16x32_bf16 v[74:77], v[172:175], v[196:199], v[74:77]
	v_mfma_f32_16x16x32_bf16 v[70:73], v[164:167], v[204:207], v[70:73]
	v_mfma_f32_16x16x32_bf16 v[66:69], v[172:175], v[204:207], v[66:69]
	s_barrier
	s_setprio 0
	s_add_i32 s20, s54, s37
	v_lshl_add_u64 v[208:209], v[208:209], 0, s[2:3]
	s_mov_b32 m0, s20
	ds_read_b128 v[176:179], v143 offset:49152
	ds_read_b128 v[180:183], v143 offset:50176
	ds_read_b128 v[184:187], v143 offset:51200
	ds_read_b128 v[188:191], v143 offset:52224
	ds_read_b128 v[192:195], v143 offset:53248
	ds_read_b128 v[196:199], v143 offset:54272
	ds_read_b128 v[200:203], v143 offset:55296
	ds_read_b128 v[204:207], v143 offset:56320
	global_load_lds_dwordx4 v[208:209], off
	s_add_i32 m0, s20, 0x2000
	s_add_u32 s18, s18, 0x80080
	v_lshl_add_u64 v[208:209], v[220:221], 0, s[2:3]
	s_addc_u32 s19, s19, 0
	s_add_i32 s20, s55, s37
	global_load_lds_dwordx4 v[208:209], off
	v_lshl_add_u64 v[208:209], s[18:19], 0, v[0:1]
	s_mov_b32 m0, s20
	s_nop 0
	global_load_lds_dwordx4 v[208:209], off
	v_lshl_add_u64 v[208:209], s[18:19], 0, v[130:131]
	s_add_i32 m0, s20, 0x2000
	s_nop 0
	global_load_lds_dwordx4 v[208:209], off
	v_lshl_add_u64 v[208:209], v[222:223], 0, s[2:3]
	s_mov_b32 m0, s45
	s_nop 0
	global_load_lds_dwordx4 v[208:209], off
	v_lshl_add_u64 v[208:209], v[224:225], 0, s[2:3]
	s_mov_b32 m0, s46
	s_nop 0
	global_load_lds_dwordx4 v[208:209], off
	s_nop 0
	s_waitcnt vmcnt(8)
	s_waitcnt lgkmcnt(0)
	s_setprio 1
	s_barrier
	v_mfma_f32_16x16x32_bf16 v[62:65], v[144:147], v[176:179], v[62:65]
	v_mfma_f32_16x16x32_bf16 v[58:61], v[152:155], v[176:179], v[58:61]
	v_mfma_f32_16x16x32_bf16 v[54:57], v[144:147], v[184:187], v[54:57]
	v_mfma_f32_16x16x32_bf16 v[50:53], v[152:155], v[184:187], v[50:53]
	v_mfma_f32_16x16x32_bf16 v[38:41], v[144:147], v[192:195], v[38:41]
	v_mfma_f32_16x16x32_bf16 v[34:37], v[152:155], v[192:195], v[34:37]
	v_mfma_f32_16x16x32_bf16 v[22:25], v[144:147], v[200:203], v[22:25]
	v_mfma_f32_16x16x32_bf16 v[18:21], v[152:155], v[200:203], v[18:21]
	v_mfma_f32_16x16x32_bf16 v[62:65], v[148:151], v[180:183], v[62:65]
	v_mfma_f32_16x16x32_bf16 v[58:61], v[156:159], v[180:183], v[58:61]
	v_mfma_f32_16x16x32_bf16 v[54:57], v[148:151], v[188:191], v[54:57]
	v_mfma_f32_16x16x32_bf16 v[50:53], v[156:159], v[188:191], v[50:53]
	v_mfma_f32_16x16x32_bf16 v[38:41], v[148:151], v[196:199], v[38:41]
	v_mfma_f32_16x16x32_bf16 v[34:37], v[156:159], v[196:199], v[34:37]
	v_mfma_f32_16x16x32_bf16 v[22:25], v[148:151], v[204:207], v[22:25]
	v_mfma_f32_16x16x32_bf16 v[18:21], v[156:159], v[204:207], v[18:21]
	s_setprio 0
	s_setprio 1
	v_mfma_f32_16x16x32_bf16 v[46:49], v[160:163], v[176:179], v[46:49]
	v_mfma_f32_16x16x32_bf16 v[42:45], v[168:171], v[176:179], v[42:45]
	v_mfma_f32_16x16x32_bf16 v[30:33], v[160:163], v[184:187], v[30:33]
	v_mfma_f32_16x16x32_bf16 v[26:29], v[168:171], v[184:187], v[26:29]
	v_mfma_f32_16x16x32_bf16 v[14:17], v[160:163], v[192:195], v[14:17]
	v_mfma_f32_16x16x32_bf16 v[10:13], v[168:171], v[192:195], v[10:13]
	v_mfma_f32_16x16x32_bf16 v[6:9], v[160:163], v[200:203], v[6:9]
	v_mfma_f32_16x16x32_bf16 v[2:5], v[168:171], v[200:203], v[2:5]
	v_mfma_f32_16x16x32_bf16 v[46:49], v[164:167], v[180:183], v[46:49]
	v_mfma_f32_16x16x32_bf16 v[42:45], v[172:175], v[180:183], v[42:45]
	v_mfma_f32_16x16x32_bf16 v[30:33], v[164:167], v[188:191], v[30:33]
	v_mfma_f32_16x16x32_bf16 v[26:29], v[172:175], v[188:191], v[26:29]
	v_mfma_f32_16x16x32_bf16 v[14:17], v[164:167], v[196:199], v[14:17]
	v_mfma_f32_16x16x32_bf16 v[10:13], v[172:175], v[196:199], v[10:13]
	v_mfma_f32_16x16x32_bf16 v[6:9], v[164:167], v[204:207], v[6:9]
	v_mfma_f32_16x16x32_bf16 v[2:5], v[172:175], v[204:207], v[2:5]
	s_barrier
	s_setprio 0
	s_add_i32 s53, s53, 2
	s_add_u32 s16, s16, 0x100
	s_addc_u32 s17, s17, 0
	s_add_u32 s51, s51, 0x100
	s_addc_u32 s52, s52, 0
	s_cmp_gt_u32 s53, 29
	s_cbranch_scc0 .LBB0_491

.LBB0_882:
	s_add_u32 s38, s22, 0x80080
	s_addc_u32 s39, s23, 0
	s_add_u32 s15, s42, 0x100
	s_addc_u32 s21, s43, 0
	s_mov_b32 s22, 0
	s_add_i32 s41, s22, 2
	s_add_u32 s42, s38, 0xfff80080
	s_addc_u32 s23, s39, -1
	s_add_i32 s44, 0, 0x10000
	s_cmp_eq_u32 s63, s22
	s_cselect_b32 s23, s17, s23
	s_cselect_b32 s22, s16, s42
	v_add_u32_e32 v0, s44, v224
	s_cselect_b32 s43, s19, s21
	s_cselect_b32 s42, s18, s15
	s_add_i32 s45, 0, 0x14000
	ds_read_b128 v[30:33], v0
	ds_read_b128 v[134:137], v0 offset:1024
	ds_read_b128 v[138:141], v0 offset:2048
	ds_read_b128 v[142:145], v0 offset:3072
	v_add_u32_e32 v0, s45, v224
	ds_read_b128 v[146:149], v0
	ds_read_b128 v[150:153], v0 offset:1024
	ds_read_b128 v[154:157], v0 offset:2048
	ds_read_b128 v[158:161], v0 offset:3072
	v_lshl_add_u64 v[206:207], s[38:39], 0, v[202:203]
	s_add_i32 m0, s52, 0xc000
	ds_read_b128 v[162:165], v225
	ds_read_b128 v[166:169], v225 offset:1024
	ds_read_b128 v[170:173], v225 offset:2048
	ds_read_b128 v[174:177], v225 offset:3072
	ds_read_b128 v[178:181], v225 offset:4096
	ds_read_b128 v[182:185], v225 offset:5120
	ds_read_b128 v[186:189], v225 offset:6144
	ds_read_b128 v[190:193], v225 offset:7168
	global_load_lds_dwordx4 v[206:207], off
	v_lshl_add_u64 v[206:207], s[38:39], 0, v[204:205]
	s_add_i32 m0, s52, 0xe000
	s_nop 0
	global_load_lds_dwordx4 v[206:207], off
	s_waitcnt vmcnt(8)
	s_waitcnt lgkmcnt(0)
	s_setprio 1
	s_barrier
	v_mfma_f32_16x16x32_bf16 v[26:29], v[30:33], v[162:165], 0
	v_mfma_f32_16x16x32_bf16 v[22:25], v[138:141], v[162:165], 0
	v_mfma_f32_16x16x32_bf16 v[62:65], v[30:33], v[170:173], 0
	v_mfma_f32_16x16x32_bf16 v[14:17], v[138:141], v[170:173], 0
	v_mfma_f32_16x16x32_bf16 v[58:61], v[30:33], v[178:181], 0
	v_mfma_f32_16x16x32_bf16 v[54:57], v[138:141], v[178:181], 0
	v_mfma_f32_16x16x32_bf16 v[94:97], v[30:33], v[186:189], 0
	v_mfma_f32_16x16x32_bf16 v[46:49], v[138:141], v[186:189], 0
	v_mfma_f32_16x16x32_bf16 v[26:29], v[134:137], v[166:169], v[26:29]
	v_mfma_f32_16x16x32_bf16 v[22:25], v[142:145], v[166:169], v[22:25]
	v_mfma_f32_16x16x32_bf16 v[62:65], v[134:137], v[174:177], v[62:65]
	v_mfma_f32_16x16x32_bf16 v[14:17], v[142:145], v[174:177], v[14:17]
	v_mfma_f32_16x16x32_bf16 v[58:61], v[134:137], v[182:185], v[58:61]
	v_mfma_f32_16x16x32_bf16 v[54:57], v[142:145], v[182:185], v[54:57]
	v_mfma_f32_16x16x32_bf16 v[94:97], v[134:137], v[190:193], v[94:97]
	v_mfma_f32_16x16x32_bf16 v[46:49], v[142:145], v[190:193], v[46:49]
	s_setprio 0
	s_setprio 1
	v_mfma_f32_16x16x32_bf16 v[18:21], v[146:149], v[162:165], 0
	v_mfma_f32_16x16x32_bf16 v[10:13], v[154:157], v[162:165], 0
	v_mfma_f32_16x16x32_bf16 v[2:5], v[146:149], v[170:173], 0
	v_mfma_f32_16x16x32_bf16 v[6:9], v[154:157], v[170:173], 0
	v_mfma_f32_16x16x32_bf16 v[50:53], v[146:149], v[178:181], 0
	v_mfma_f32_16x16x32_bf16 v[42:45], v[154:157], v[178:181], 0
	v_mfma_f32_16x16x32_bf16 v[34:37], v[146:149], v[186:189], 0
	v_mfma_f32_16x16x32_bf16 v[38:41], v[154:157], v[186:189], 0
	v_mfma_f32_16x16x32_bf16 v[18:21], v[150:153], v[166:169], v[18:21]
	v_mfma_f32_16x16x32_bf16 v[10:13], v[158:161], v[166:169], v[10:13]
	v_mfma_f32_16x16x32_bf16 v[2:5], v[150:153], v[174:177], v[2:5]
	v_mfma_f32_16x16x32_bf16 v[6:9], v[158:161], v[174:177], v[6:9]
	v_mfma_f32_16x16x32_bf16 v[50:53], v[150:153], v[182:185], v[50:53]
	v_mfma_f32_16x16x32_bf16 v[42:45], v[158:161], v[182:185], v[42:45]
	v_mfma_f32_16x16x32_bf16 v[34:37], v[150:153], v[190:193], v[34:37]
	v_mfma_f32_16x16x32_bf16 v[38:41], v[158:161], v[190:193], v[38:41]
	s_barrier
	s_setprio 0
	s_add_i32 s44, s44, s49
	v_lshl_add_u64 v[206:207], s[42:43], 0, v[196:197]
	s_mov_b32 m0, s44
	ds_read_b128 v[162:165], v225 offset:16384
	ds_read_b128 v[166:169], v225 offset:17408
	ds_read_b128 v[170:173], v225 offset:18432
	ds_read_b128 v[174:177], v225 offset:19456
	ds_read_b128 v[178:181], v225 offset:20480
	ds_read_b128 v[182:185], v225 offset:21504
	ds_read_b128 v[186:189], v225 offset:22528
	ds_read_b128 v[190:193], v225 offset:23552
	global_load_lds_dwordx4 v[206:207], off
	s_add_i32 m0, s44, 0x2000
	v_lshl_add_u64 v[208:209], s[42:43], 0, v[200:201]
	s_add_u32 s42, s42, s50
	s_addc_u32 s43, s43, 0
	s_add_i32 s44, s45, s49
	global_load_lds_dwordx4 v[208:209], off
	v_lshl_add_u64 v[220:221], s[42:43], 0, v[196:197]
	s_mov_b32 m0, s44
	v_lshl_add_u64 v[226:227], s[42:43], 0, v[200:201]
	global_load_lds_dwordx4 v[220:221], off
	s_add_i32 m0, s44, 0x2000
	v_lshl_add_u64 v[228:229], s[22:23], 0, v[194:195]
	global_load_lds_dwordx4 v[226:227], off
	s_mov_b32 m0, s52
	v_lshl_add_u64 v[230:231], s[22:23], 0, v[198:199]
	global_load_lds_dwordx4 v[228:229], off
	s_mov_b32 m0, s53
	s_nop 0
	global_load_lds_dwordx4 v[230:231], off
	s_nop 0
	s_waitcnt vmcnt(8)
	s_waitcnt lgkmcnt(0)
	s_setprio 1
	s_barrier
	v_mfma_f32_16x16x32_bf16 v[90:93], v[30:33], v[162:165], 0
	v_mfma_f32_16x16x32_bf16 v[86:89], v[138:141], v[162:165], 0
	v_mfma_f32_16x16x32_bf16 v[130:133], v[30:33], v[170:173], 0
	v_mfma_f32_16x16x32_bf16 v[78:81], v[138:141], v[170:173], 0
	v_mfma_f32_16x16x32_bf16 v[126:129], v[30:33], v[178:181], 0
	v_mfma_f32_16x16x32_bf16 v[118:121], v[138:141], v[178:181], 0
	v_mfma_f32_16x16x32_bf16 v[110:113], v[138:141], v[186:189], 0
	v_mfma_f32_16x16x32_bf16 v[90:93], v[134:137], v[166:169], v[90:93]
	v_mfma_f32_16x16x32_bf16 v[86:89], v[142:145], v[166:169], v[86:89]
	v_mfma_f32_16x16x32_bf16 v[130:133], v[134:137], v[174:177], v[130:133]
	v_mfma_f32_16x16x32_bf16 v[78:81], v[142:145], v[174:177], v[78:81]
	v_mfma_f32_16x16x32_bf16 v[126:129], v[134:137], v[182:185], v[126:129]
	v_mfma_f32_16x16x32_bf16 v[118:121], v[142:145], v[182:185], v[118:121]
	v_mfma_f32_16x16x32_bf16 v[30:33], v[30:33], v[186:189], 0
	v_mfma_f32_16x16x32_bf16 v[110:113], v[142:145], v[190:193], v[110:113]
	v_mfma_f32_16x16x32_bf16 v[30:33], v[134:137], v[190:193], v[30:33]
	s_setprio 0
	s_setprio 1
	v_mfma_f32_16x16x32_bf16 v[82:85], v[146:149], v[162:165], 0
	v_mfma_f32_16x16x32_bf16 v[74:77], v[154:157], v[162:165], 0
	v_mfma_f32_16x16x32_bf16 v[66:69], v[146:149], v[170:173], 0
	v_mfma_f32_16x16x32_bf16 v[70:73], v[154:157], v[170:173], 0
	v_mfma_f32_16x16x32_bf16 v[114:117], v[146:149], v[178:181], 0
	v_mfma_f32_16x16x32_bf16 v[106:109], v[154:157], v[178:181], 0
	v_mfma_f32_16x16x32_bf16 v[98:101], v[146:149], v[186:189], 0
	v_mfma_f32_16x16x32_bf16 v[102:105], v[154:157], v[186:189], 0
	v_mfma_f32_16x16x32_bf16 v[82:85], v[150:153], v[166:169], v[82:85]
	v_mfma_f32_16x16x32_bf16 v[74:77], v[158:161], v[166:169], v[74:77]
	v_mfma_f32_16x16x32_bf16 v[66:69], v[150:153], v[174:177], v[66:69]
	v_mfma_f32_16x16x32_bf16 v[70:73], v[158:161], v[174:177], v[70:73]
	v_mfma_f32_16x16x32_bf16 v[114:117], v[150:153], v[182:185], v[114:117]
	v_mfma_f32_16x16x32_bf16 v[106:109], v[158:161], v[182:185], v[106:109]
	v_mfma_f32_16x16x32_bf16 v[98:101], v[150:153], v[190:193], v[98:101]
	v_mfma_f32_16x16x32_bf16 v[102:105], v[158:161], v[190:193], v[102:105]
	s_barrier
	s_setprio 0
	s_add_i32 s42, 0, 0x18000
	v_add_u32_e32 v0, s42, v224
	s_add_i32 s43, 0, 0x1c000
	ds_read_b128 v[122:125], v0
	ds_read_b128 v[134:137], v0 offset:1024
	ds_read_b128 v[138:141], v0 offset:2048
	ds_read_b128 v[142:145], v0 offset:3072
	v_add_u32_e32 v0, s43, v224
	ds_read_b128 v[146:149], v0
	ds_read_b128 v[150:153], v0 offset:1024
	ds_read_b128 v[154:157], v0 offset:2048
	ds_read_b128 v[158:161], v0 offset:3072
	s_add_u32 s22, s22, 0x80000
	s_addc_u32 s23, s23, 0
	s_mov_b32 m0, s54
	v_lshl_add_u64 v[232:233], s[22:23], 0, v[194:195]
	ds_read_b128 v[162:165], v225 offset:32768
	ds_read_b128 v[166:169], v225 offset:33792
	ds_read_b128 v[170:173], v225 offset:34816
	ds_read_b128 v[174:177], v225 offset:35840
	ds_read_b128 v[178:181], v225 offset:36864
	ds_read_b128 v[182:185], v225 offset:37888
	ds_read_b128 v[186:189], v225 offset:38912
	ds_read_b128 v[190:193], v225 offset:39936
	global_load_lds_dwordx4 v[232:233], off
	v_lshl_add_u64 v[232:233], s[22:23], 0, v[198:199]
	s_mov_b32 m0, s55
	s_nop 0
	global_load_lds_dwordx4 v[232:233], off
	s_waitcnt vmcnt(8)
	s_waitcnt lgkmcnt(0)
	s_setprio 1
	s_barrier
	v_mfma_f32_16x16x32_bf16 v[26:29], v[122:125], v[162:165], v[26:29]
	v_mfma_f32_16x16x32_bf16 v[22:25], v[138:141], v[162:165], v[22:25]
	v_mfma_f32_16x16x32_bf16 v[62:65], v[122:125], v[170:173], v[62:65]
	v_mfma_f32_16x16x32_bf16 v[14:17], v[138:141], v[170:173], v[14:17]
	v_mfma_f32_16x16x32_bf16 v[58:61], v[122:125], v[178:181], v[58:61]
	v_mfma_f32_16x16x32_bf16 v[54:57], v[138:141], v[178:181], v[54:57]
	v_mfma_f32_16x16x32_bf16 v[94:97], v[122:125], v[186:189], v[94:97]
	v_mfma_f32_16x16x32_bf16 v[46:49], v[138:141], v[186:189], v[46:49]
	v_mfma_f32_16x16x32_bf16 v[26:29], v[134:137], v[166:169], v[26:29]
	v_mfma_f32_16x16x32_bf16 v[22:25], v[142:145], v[166:169], v[22:25]
	v_mfma_f32_16x16x32_bf16 v[62:65], v[134:137], v[174:177], v[62:65]
	v_mfma_f32_16x16x32_bf16 v[14:17], v[142:145], v[174:177], v[14:17]
	v_mfma_f32_16x16x32_bf16 v[58:61], v[134:137], v[182:185], v[58:61]
	v_mfma_f32_16x16x32_bf16 v[54:57], v[142:145], v[182:185], v[54:57]
	v_mfma_f32_16x16x32_bf16 v[94:97], v[134:137], v[190:193], v[94:97]
	v_mfma_f32_16x16x32_bf16 v[46:49], v[142:145], v[190:193], v[46:49]
	s_setprio 0
	s_setprio 1
	v_mfma_f32_16x16x32_bf16 v[18:21], v[146:149], v[162:165], v[18:21]
	v_mfma_f32_16x16x32_bf16 v[10:13], v[154:157], v[162:165], v[10:13]
	v_mfma_f32_16x16x32_bf16 v[2:5], v[146:149], v[170:173], v[2:5]
	v_mfma_f32_16x16x32_bf16 v[6:9], v[154:157], v[170:173], v[6:9]
	v_mfma_f32_16x16x32_bf16 v[50:53], v[146:149], v[178:181], v[50:53]
	v_mfma_f32_16x16x32_bf16 v[42:45], v[154:157], v[178:181], v[42:45]
	v_mfma_f32_16x16x32_bf16 v[34:37], v[146:149], v[186:189], v[34:37]
	v_mfma_f32_16x16x32_bf16 v[38:41], v[154:157], v[186:189], v[38:41]
	v_mfma_f32_16x16x32_bf16 v[18:21], v[150:153], v[166:169], v[18:21]
	v_mfma_f32_16x16x32_bf16 v[10:13], v[158:161], v[166:169], v[10:13]
	v_mfma_f32_16x16x32_bf16 v[2:5], v[150:153], v[174:177], v[2:5]
	v_mfma_f32_16x16x32_bf16 v[6:9], v[158:161], v[174:177], v[6:9]
	v_mfma_f32_16x16x32_bf16 v[50:53], v[150:153], v[182:185], v[50:53]
	v_mfma_f32_16x16x32_bf16 v[42:45], v[158:161], v[182:185], v[42:45]
	v_mfma_f32_16x16x32_bf16 v[34:37], v[150:153], v[190:193], v[34:37]
	v_mfma_f32_16x16x32_bf16 v[38:41], v[158:161], v[190:193], v[38:41]
	s_barrier
	s_setprio 0
	s_add_i32 s22, s42, s49
	v_lshl_add_u64 v[206:207], v[206:207], 0, s[2:3]
	s_mov_b32 m0, s22
	ds_read_b128 v[162:165], v225 offset:49152
	ds_read_b128 v[166:169], v225 offset:50176
	ds_read_b128 v[170:173], v225 offset:51200
	ds_read_b128 v[174:177], v225 offset:52224
	ds_read_b128 v[178:181], v225 offset:53248
	ds_read_b128 v[182:185], v225 offset:54272
	ds_read_b128 v[186:189], v225 offset:55296
	ds_read_b128 v[190:193], v225 offset:56320
	global_load_lds_dwordx4 v[206:207], off
	v_lshl_add_u64 v[206:207], v[208:209], 0, s[2:3]
	s_add_i32 m0, s22, 0x2000
	s_add_i32 s22, s43, s49
	global_load_lds_dwordx4 v[206:207], off
	v_lshl_add_u64 v[206:207], v[220:221], 0, s[2:3]
	s_mov_b32 m0, s22
	s_nop 0
	global_load_lds_dwordx4 v[206:207], off
	v_lshl_add_u64 v[206:207], v[226:227], 0, s[2:3]
	s_add_i32 m0, s22, 0x2000
	s_nop 0
	global_load_lds_dwordx4 v[206:207], off
	v_lshl_add_u64 v[206:207], v[228:229], 0, s[2:3]
	s_mov_b32 m0, s61
	s_nop 0
	global_load_lds_dwordx4 v[206:207], off
	v_lshl_add_u64 v[206:207], v[230:231], 0, s[2:3]
	s_mov_b32 m0, s62
	s_nop 0
	global_load_lds_dwordx4 v[206:207], off
	s_waitcnt vmcnt(8)
	s_waitcnt lgkmcnt(0)
	s_setprio 1
	s_barrier
	v_mfma_f32_16x16x32_bf16 v[30:33], v[122:125], v[186:189], v[30:33]
	v_mfma_f32_16x16x32_bf16 v[90:93], v[122:125], v[162:165], v[90:93]
	v_mfma_f32_16x16x32_bf16 v[86:89], v[138:141], v[162:165], v[86:89]
	v_mfma_f32_16x16x32_bf16 v[130:133], v[122:125], v[170:173], v[130:133]
	v_mfma_f32_16x16x32_bf16 v[78:81], v[138:141], v[170:173], v[78:81]
	v_mfma_f32_16x16x32_bf16 v[126:129], v[122:125], v[178:181], v[126:129]
	v_mfma_f32_16x16x32_bf16 v[118:121], v[138:141], v[178:181], v[118:121]
	v_mfma_f32_16x16x32_bf16 v[122:125], v[134:137], v[190:193], v[30:33]
	v_mfma_f32_16x16x32_bf16 v[30:33], v[138:141], v[186:189], v[110:113]
	v_mfma_f32_16x16x32_bf16 v[90:93], v[134:137], v[166:169], v[90:93]
	v_mfma_f32_16x16x32_bf16 v[86:89], v[142:145], v[166:169], v[86:89]
	v_mfma_f32_16x16x32_bf16 v[130:133], v[134:137], v[174:177], v[130:133]
	v_mfma_f32_16x16x32_bf16 v[78:81], v[142:145], v[174:177], v[78:81]
	v_mfma_f32_16x16x32_bf16 v[126:129], v[134:137], v[182:185], v[126:129]
	v_mfma_f32_16x16x32_bf16 v[118:121], v[142:145], v[182:185], v[118:121]
	v_mfma_f32_16x16x32_bf16 v[110:113], v[142:145], v[190:193], v[30:33]
	s_setprio 0
	s_setprio 1
	v_mfma_f32_16x16x32_bf16 v[30:33], v[146:149], v[162:165], v[82:85]
	v_mfma_f32_16x16x32_bf16 v[82:85], v[150:153], v[166:169], v[30:33]
	v_mfma_f32_16x16x32_bf16 v[30:33], v[154:157], v[162:165], v[74:77]
	v_mfma_f32_16x16x32_bf16 v[74:77], v[158:161], v[166:169], v[30:33]
	v_mfma_f32_16x16x32_bf16 v[30:33], v[146:149], v[170:173], v[66:69]
	v_mfma_f32_16x16x32_bf16 v[66:69], v[150:153], v[174:177], v[30:33]
	v_mfma_f32_16x16x32_bf16 v[30:33], v[154:157], v[170:173], v[70:73]
	v_mfma_f32_16x16x32_bf16 v[70:73], v[158:161], v[174:177], v[30:33]
	v_mfma_f32_16x16x32_bf16 v[30:33], v[146:149], v[178:181], v[114:117]
	v_mfma_f32_16x16x32_bf16 v[114:117], v[150:153], v[182:185], v[30:33]
	v_mfma_f32_16x16x32_bf16 v[30:33], v[154:157], v[178:181], v[106:109]
	v_mfma_f32_16x16x32_bf16 v[106:109], v[158:161], v[182:185], v[30:33]
	v_mfma_f32_16x16x32_bf16 v[30:33], v[146:149], v[186:189], v[98:101]
	v_mfma_f32_16x16x32_bf16 v[98:101], v[150:153], v[190:193], v[30:33]
	v_mfma_f32_16x16x32_bf16 v[30:33], v[154:157], v[186:189], v[102:105]
	v_mfma_f32_16x16x32_bf16 v[102:105], v[158:161], v[190:193], v[30:33]
	s_barrier
	s_setprio 0
	s_add_u32 s38, s38, 0x100
	s_addc_u32 s39, s39, 0
	s_add_u32 s15, s15, 0x100
	s_addc_u32 s21, s21, 0
	s_cmp_ge_u32 s41, s56
	s_mov_b32 s22, s41
	s_cbranch_scc1 .Lpeel_done_1
.LBB0_883:
	s_add_i32 s41, s22, 2
	s_add_u32 s42, s38, 0xfff80080
	s_addc_u32 s23, s39, -1
	s_add_i32 s44, 0, 0x10000
	s_cmp_eq_u32 s63, s22
	s_cselect_b32 s23, s17, s23
	s_cselect_b32 s22, s16, s42
	v_add_u32_e32 v0, s44, v224
	s_cselect_b32 s43, s19, s21
	s_cselect_b32 s42, s18, s15
	s_add_i32 s45, 0, 0x14000
	ds_read_b128 v[30:33], v0
	ds_read_b128 v[134:137], v0 offset:1024
	ds_read_b128 v[138:141], v0 offset:2048
	ds_read_b128 v[142:145], v0 offset:3072
	v_add_u32_e32 v0, s45, v224
	ds_read_b128 v[146:149], v0
	ds_read_b128 v[150:153], v0 offset:1024
	ds_read_b128 v[154:157], v0 offset:2048
	ds_read_b128 v[158:161], v0 offset:3072
	v_lshl_add_u64 v[206:207], s[38:39], 0, v[202:203]
	s_add_i32 m0, s52, 0xc000
	ds_read_b128 v[162:165], v225
	ds_read_b128 v[166:169], v225 offset:1024
	ds_read_b128 v[170:173], v225 offset:2048
	ds_read_b128 v[174:177], v225 offset:3072
	ds_read_b128 v[178:181], v225 offset:4096
	ds_read_b128 v[182:185], v225 offset:5120
	ds_read_b128 v[186:189], v225 offset:6144
	ds_read_b128 v[190:193], v225 offset:7168
	global_load_lds_dwordx4 v[206:207], off
	v_lshl_add_u64 v[206:207], s[38:39], 0, v[204:205]
	s_add_i32 m0, s52, 0xe000
	s_nop 0
	global_load_lds_dwordx4 v[206:207], off
	s_nop 0
	s_waitcnt vmcnt(8)
	s_waitcnt lgkmcnt(0)
	s_setprio 1
	s_barrier
	v_mfma_f32_16x16x32_bf16 v[26:29], v[30:33], v[162:165], v[26:29]
	v_mfma_f32_16x16x32_bf16 v[22:25], v[138:141], v[162:165], v[22:25]
	v_mfma_f32_16x16x32_bf16 v[62:65], v[30:33], v[170:173], v[62:65]
	v_mfma_f32_16x16x32_bf16 v[14:17], v[138:141], v[170:173], v[14:17]
	v_mfma_f32_16x16x32_bf16 v[58:61], v[30:33], v[178:181], v[58:61]
	v_mfma_f32_16x16x32_bf16 v[54:57], v[138:141], v[178:181], v[54:57]
	v_mfma_f32_16x16x32_bf16 v[94:97], v[30:33], v[186:189], v[94:97]
	v_mfma_f32_16x16x32_bf16 v[46:49], v[138:141], v[186:189], v[46:49]
	v_mfma_f32_16x16x32_bf16 v[26:29], v[134:137], v[166:169], v[26:29]
	v_mfma_f32_16x16x32_bf16 v[22:25], v[142:145], v[166:169], v[22:25]
	v_mfma_f32_16x16x32_bf16 v[62:65], v[134:137], v[174:177], v[62:65]
	v_mfma_f32_16x16x32_bf16 v[14:17], v[142:145], v[174:177], v[14:17]
	v_mfma_f32_16x16x32_bf16 v[58:61], v[134:137], v[182:185], v[58:61]
	v_mfma_f32_16x16x32_bf16 v[54:57], v[142:145], v[182:185], v[54:57]
	v_mfma_f32_16x16x32_bf16 v[94:97], v[134:137], v[190:193], v[94:97]
	v_mfma_f32_16x16x32_bf16 v[46:49], v[142:145], v[190:193], v[46:49]
	s_setprio 0
	s_setprio 1
	v_mfma_f32_16x16x32_bf16 v[18:21], v[146:149], v[162:165], v[18:21]
	v_mfma_f32_16x16x32_bf16 v[10:13], v[154:157], v[162:165], v[10:13]
	v_mfma_f32_16x16x32_bf16 v[2:5], v[146:149], v[170:173], v[2:5]
	v_mfma_f32_16x16x32_bf16 v[6:9], v[154:157], v[170:173], v[6:9]
	v_mfma_f32_16x16x32_bf16 v[50:53], v[146:149], v[178:181], v[50:53]
	v_mfma_f32_16x16x32_bf16 v[42:45], v[154:157], v[178:181], v[42:45]
	v_mfma_f32_16x16x32_bf16 v[34:37], v[146:149], v[186:189], v[34:37]
	v_mfma_f32_16x16x32_bf16 v[38:41], v[154:157], v[186:189], v[38:41]
	v_mfma_f32_16x16x32_bf16 v[18:21], v[150:153], v[166:169], v[18:21]
	v_mfma_f32_16x16x32_bf16 v[10:13], v[158:161], v[166:169], v[10:13]
	v_mfma_f32_16x16x32_bf16 v[2:5], v[150:153], v[174:177], v[2:5]
	v_mfma_f32_16x16x32_bf16 v[6:9], v[158:161], v[174:177], v[6:9]
	v_mfma_f32_16x16x32_bf16 v[50:53], v[150:153], v[182:185], v[50:53]
	v_mfma_f32_16x16x32_bf16 v[42:45], v[158:161], v[182:185], v[42:45]
	v_mfma_f32_16x16x32_bf16 v[34:37], v[150:153], v[190:193], v[34:37]
	v_mfma_f32_16x16x32_bf16 v[38:41], v[158:161], v[190:193], v[38:41]
	s_barrier
	s_setprio 0
	s_add_i32 s44, s44, s49
	v_lshl_add_u64 v[206:207], s[42:43], 0, v[196:197]
	s_mov_b32 m0, s44
	ds_read_b128 v[162:165], v225 offset:16384
	ds_read_b128 v[166:169], v225 offset:17408
	ds_read_b128 v[170:173], v225 offset:18432
	ds_read_b128 v[174:177], v225 offset:19456
	ds_read_b128 v[178:181], v225 offset:20480
	ds_read_b128 v[182:185], v225 offset:21504
	ds_read_b128 v[186:189], v225 offset:22528
	ds_read_b128 v[190:193], v225 offset:23552
	global_load_lds_dwordx4 v[206:207], off
	s_add_i32 m0, s44, 0x2000
	v_lshl_add_u64 v[208:209], s[42:43], 0, v[200:201]
	s_add_u32 s42, s42, s50
	s_addc_u32 s43, s43, 0
	s_add_i32 s44, s45, s49
	global_load_lds_dwordx4 v[208:209], off
	v_lshl_add_u64 v[220:221], s[42:43], 0, v[196:197]
	s_mov_b32 m0, s44
	v_lshl_add_u64 v[226:227], s[42:43], 0, v[200:201]
	global_load_lds_dwordx4 v[220:221], off
	s_add_i32 m0, s44, 0x2000
	v_lshl_add_u64 v[228:229], s[22:23], 0, v[194:195]
	global_load_lds_dwordx4 v[226:227], off
	s_mov_b32 m0, s52
	v_lshl_add_u64 v[230:231], s[22:23], 0, v[198:199]
	global_load_lds_dwordx4 v[228:229], off
	s_mov_b32 m0, s53
	s_nop 0
	global_load_lds_dwordx4 v[230:231], off
	s_nop 0
	s_waitcnt vmcnt(8)
	s_waitcnt lgkmcnt(0)
	s_setprio 1
	s_barrier
	v_mfma_f32_16x16x32_bf16 v[90:93], v[30:33], v[162:165], v[90:93]
	v_mfma_f32_16x16x32_bf16 v[86:89], v[138:141], v[162:165], v[86:89]
	v_mfma_f32_16x16x32_bf16 v[130:133], v[30:33], v[170:173], v[130:133]
	v_mfma_f32_16x16x32_bf16 v[78:81], v[138:141], v[170:173], v[78:81]
	v_mfma_f32_16x16x32_bf16 v[126:129], v[30:33], v[178:181], v[126:129]
	v_mfma_f32_16x16x32_bf16 v[118:121], v[138:141], v[178:181], v[118:121]
	v_mfma_f32_16x16x32_bf16 v[110:113], v[138:141], v[186:189], v[110:113]
	v_mfma_f32_16x16x32_bf16 v[90:93], v[134:137], v[166:169], v[90:93]
	v_mfma_f32_16x16x32_bf16 v[86:89], v[142:145], v[166:169], v[86:89]
	v_mfma_f32_16x16x32_bf16 v[130:133], v[134:137], v[174:177], v[130:133]
	v_mfma_f32_16x16x32_bf16 v[78:81], v[142:145], v[174:177], v[78:81]
	v_mfma_f32_16x16x32_bf16 v[126:129], v[134:137], v[182:185], v[126:129]
	v_mfma_f32_16x16x32_bf16 v[118:121], v[142:145], v[182:185], v[118:121]
	v_mfma_f32_16x16x32_bf16 v[30:33], v[30:33], v[186:189], v[122:125]
	v_mfma_f32_16x16x32_bf16 v[110:113], v[142:145], v[190:193], v[110:113]
	v_mfma_f32_16x16x32_bf16 v[30:33], v[134:137], v[190:193], v[30:33]
	s_setprio 0
	s_setprio 1
	v_mfma_f32_16x16x32_bf16 v[82:85], v[146:149], v[162:165], v[82:85]
	v_mfma_f32_16x16x32_bf16 v[74:77], v[154:157], v[162:165], v[74:77]
	v_mfma_f32_16x16x32_bf16 v[66:69], v[146:149], v[170:173], v[66:69]
	v_mfma_f32_16x16x32_bf16 v[70:73], v[154:157], v[170:173], v[70:73]
	v_mfma_f32_16x16x32_bf16 v[114:117], v[146:149], v[178:181], v[114:117]
	v_mfma_f32_16x16x32_bf16 v[106:109], v[154:157], v[178:181], v[106:109]
	v_mfma_f32_16x16x32_bf16 v[98:101], v[146:149], v[186:189], v[98:101]
	v_mfma_f32_16x16x32_bf16 v[102:105], v[154:157], v[186:189], v[102:105]
	v_mfma_f32_16x16x32_bf16 v[82:85], v[150:153], v[166:169], v[82:85]
	v_mfma_f32_16x16x32_bf16 v[74:77], v[158:161], v[166:169], v[74:77]
	v_mfma_f32_16x16x32_bf16 v[66:69], v[150:153], v[174:177], v[66:69]
	v_mfma_f32_16x16x32_bf16 v[70:73], v[158:161], v[174:177], v[70:73]
	v_mfma_f32_16x16x32_bf16 v[114:117], v[150:153], v[182:185], v[114:117]
	v_mfma_f32_16x16x32_bf16 v[106:109], v[158:161], v[182:185], v[106:109]
	v_mfma_f32_16x16x32_bf16 v[98:101], v[150:153], v[190:193], v[98:101]
	v_mfma_f32_16x16x32_bf16 v[102:105], v[158:161], v[190:193], v[102:105]
	s_barrier
	s_setprio 0
	s_add_i32 s42, 0, 0x18000
	v_add_u32_e32 v0, s42, v224
	s_add_i32 s43, 0, 0x1c000
	ds_read_b128 v[122:125], v0
	ds_read_b128 v[134:137], v0 offset:1024
	ds_read_b128 v[138:141], v0 offset:2048
	ds_read_b128 v[142:145], v0 offset:3072
	v_add_u32_e32 v0, s43, v224
	ds_read_b128 v[146:149], v0
	ds_read_b128 v[150:153], v0 offset:1024
	ds_read_b128 v[154:157], v0 offset:2048
	ds_read_b128 v[158:161], v0 offset:3072
	s_add_u32 s22, s22, 0x80000
	s_addc_u32 s23, s23, 0
	s_mov_b32 m0, s54
	v_lshl_add_u64 v[232:233], s[22:23], 0, v[194:195]
	ds_read_b128 v[162:165], v225 offset:32768
	ds_read_b128 v[166:169], v225 offset:33792
	ds_read_b128 v[170:173], v225 offset:34816
	ds_read_b128 v[174:177], v225 offset:35840
	ds_read_b128 v[178:181], v225 offset:36864
	ds_read_b128 v[182:185], v225 offset:37888
	ds_read_b128 v[186:189], v225 offset:38912
	ds_read_b128 v[190:193], v225 offset:39936
	global_load_lds_dwordx4 v[232:233], off
	v_lshl_add_u64 v[232:233], s[22:23], 0, v[198:199]
	s_mov_b32 m0, s55
	s_nop 0
	global_load_lds_dwordx4 v[232:233], off
	s_waitcnt vmcnt(8)
	s_waitcnt lgkmcnt(0)
	s_setprio 1
	s_barrier
	v_mfma_f32_16x16x32_bf16 v[26:29], v[122:125], v[162:165], v[26:29]
	v_mfma_f32_16x16x32_bf16 v[22:25], v[138:141], v[162:165], v[22:25]
	v_mfma_f32_16x16x32_bf16 v[62:65], v[122:125], v[170:173], v[62:65]
	v_mfma_f32_16x16x32_bf16 v[14:17], v[138:141], v[170:173], v[14:17]
	v_mfma_f32_16x16x32_bf16 v[58:61], v[122:125], v[178:181], v[58:61]
	v_mfma_f32_16x16x32_bf16 v[54:57], v[138:141], v[178:181], v[54:57]
	v_mfma_f32_16x16x32_bf16 v[94:97], v[122:125], v[186:189], v[94:97]
	v_mfma_f32_16x16x32_bf16 v[46:49], v[138:141], v[186:189], v[46:49]
	v_mfma_f32_16x16x32_bf16 v[26:29], v[134:137], v[166:169], v[26:29]
	v_mfma_f32_16x16x32_bf16 v[22:25], v[142:145], v[166:169], v[22:25]
	v_mfma_f32_16x16x32_bf16 v[62:65], v[134:137], v[174:177], v[62:65]
	v_mfma_f32_16x16x32_bf16 v[14:17], v[142:145], v[174:177], v[14:17]
	v_mfma_f32_16x16x32_bf16 v[58:61], v[134:137], v[182:185], v[58:61]
	v_mfma_f32_16x16x32_bf16 v[54:57], v[142:145], v[182:185], v[54:57]
	v_mfma_f32_16x16x32_bf16 v[94:97], v[134:137], v[190:193], v[94:97]
	v_mfma_f32_16x16x32_bf16 v[46:49], v[142:145], v[190:193], v[46:49]
	s_setprio 0
	s_setprio 1
	v_mfma_f32_16x16x32_bf16 v[18:21], v[146:149], v[162:165], v[18:21]
	v_mfma_f32_16x16x32_bf16 v[10:13], v[154:157], v[162:165], v[10:13]
	v_mfma_f32_16x16x32_bf16 v[2:5], v[146:149], v[170:173], v[2:5]
	v_mfma_f32_16x16x32_bf16 v[6:9], v[154:157], v[170:173], v[6:9]
	v_mfma_f32_16x16x32_bf16 v[50:53], v[146:149], v[178:181], v[50:53]
	v_mfma_f32_16x16x32_bf16 v[42:45], v[154:157], v[178:181], v[42:45]
	v_mfma_f32_16x16x32_bf16 v[34:37], v[146:149], v[186:189], v[34:37]
	v_mfma_f32_16x16x32_bf16 v[38:41], v[154:157], v[186:189], v[38:41]
	v_mfma_f32_16x16x32_bf16 v[18:21], v[150:153], v[166:169], v[18:21]
	v_mfma_f32_16x16x32_bf16 v[10:13], v[158:161], v[166:169], v[10:13]
	v_mfma_f32_16x16x32_bf16 v[2:5], v[150:153], v[174:177], v[2:5]
	v_mfma_f32_16x16x32_bf16 v[6:9], v[158:161], v[174:177], v[6:9]
	v_mfma_f32_16x16x32_bf16 v[50:53], v[150:153], v[182:185], v[50:53]
	v_mfma_f32_16x16x32_bf16 v[42:45], v[158:161], v[182:185], v[42:45]
	v_mfma_f32_16x16x32_bf16 v[34:37], v[150:153], v[190:193], v[34:37]
	v_mfma_f32_16x16x32_bf16 v[38:41], v[158:161], v[190:193], v[38:41]
	s_barrier
	s_setprio 0
	s_add_i32 s22, s42, s49
	v_lshl_add_u64 v[206:207], v[206:207], 0, s[2:3]
	s_mov_b32 m0, s22
	ds_read_b128 v[162:165], v225 offset:49152
	ds_read_b128 v[166:169], v225 offset:50176
	ds_read_b128 v[170:173], v225 offset:51200
	ds_read_b128 v[174:177], v225 offset:52224
	ds_read_b128 v[178:181], v225 offset:53248
	ds_read_b128 v[182:185], v225 offset:54272
	ds_read_b128 v[186:189], v225 offset:55296
	ds_read_b128 v[190:193], v225 offset:56320
	global_load_lds_dwordx4 v[206:207], off
	v_lshl_add_u64 v[206:207], v[208:209], 0, s[2:3]
	s_add_i32 m0, s22, 0x2000
	s_add_i32 s22, s43, s49
	global_load_lds_dwordx4 v[206:207], off
	v_lshl_add_u64 v[206:207], v[220:221], 0, s[2:3]
	s_mov_b32 m0, s22
	s_nop 0
	global_load_lds_dwordx4 v[206:207], off
	v_lshl_add_u64 v[206:207], v[226:227], 0, s[2:3]
	s_add_i32 m0, s22, 0x2000
	s_nop 0
	global_load_lds_dwordx4 v[206:207], off
	v_lshl_add_u64 v[206:207], v[228:229], 0, s[2:3]
	s_mov_b32 m0, s61
	s_nop 0
	global_load_lds_dwordx4 v[206:207], off
	v_lshl_add_u64 v[206:207], v[230:231], 0, s[2:3]
	s_mov_b32 m0, s62
	s_nop 0
	global_load_lds_dwordx4 v[206:207], off
	s_waitcnt vmcnt(8)
	s_waitcnt lgkmcnt(0)
	s_setprio 1
	s_barrier
	v_mfma_f32_16x16x32_bf16 v[30:33], v[122:125], v[186:189], v[30:33]
	v_mfma_f32_16x16x32_bf16 v[90:93], v[122:125], v[162:165], v[90:93]
	v_mfma_f32_16x16x32_bf16 v[86:89], v[138:141], v[162:165], v[86:89]
	v_mfma_f32_16x16x32_bf16 v[130:133], v[122:125], v[170:173], v[130:133]
	v_mfma_f32_16x16x32_bf16 v[78:81], v[138:141], v[170:173], v[78:81]
	v_mfma_f32_16x16x32_bf16 v[126:129], v[122:125], v[178:181], v[126:129]
	v_mfma_f32_16x16x32_bf16 v[118:121], v[138:141], v[178:181], v[118:121]
	v_mfma_f32_16x16x32_bf16 v[122:125], v[134:137], v[190:193], v[30:33]
	v_mfma_f32_16x16x32_bf16 v[30:33], v[138:141], v[186:189], v[110:113]
	v_mfma_f32_16x16x32_bf16 v[90:93], v[134:137], v[166:169], v[90:93]
	v_mfma_f32_16x16x32_bf16 v[86:89], v[142:145], v[166:169], v[86:89]
	v_mfma_f32_16x16x32_bf16 v[130:133], v[134:137], v[174:177], v[130:133]
	v_mfma_f32_16x16x32_bf16 v[78:81], v[142:145], v[174:177], v[78:81]
	v_mfma_f32_16x16x32_bf16 v[126:129], v[134:137], v[182:185], v[126:129]
	v_mfma_f32_16x16x32_bf16 v[118:121], v[142:145], v[182:185], v[118:121]
	v_mfma_f32_16x16x32_bf16 v[110:113], v[142:145], v[190:193], v[30:33]
	s_setprio 0
	s_setprio 1
	v_mfma_f32_16x16x32_bf16 v[30:33], v[146:149], v[162:165], v[82:85]
	v_mfma_f32_16x16x32_bf16 v[82:85], v[150:153], v[166:169], v[30:33]
	v_mfma_f32_16x16x32_bf16 v[30:33], v[154:157], v[162:165], v[74:77]
	v_mfma_f32_16x16x32_bf16 v[74:77], v[158:161], v[166:169], v[30:33]
	v_mfma_f32_16x16x32_bf16 v[30:33], v[146:149], v[170:173], v[66:69]
	v_mfma_f32_16x16x32_bf16 v[66:69], v[150:153], v[174:177], v[30:33]
	v_mfma_f32_16x16x32_bf16 v[30:33], v[154:157], v[170:173], v[70:73]
	v_mfma_f32_16x16x32_bf16 v[70:73], v[158:161], v[174:177], v[30:33]
	v_mfma_f32_16x16x32_bf16 v[30:33], v[146:149], v[178:181], v[114:117]
	v_mfma_f32_16x16x32_bf16 v[114:117], v[150:153], v[182:185], v[30:33]
	v_mfma_f32_16x16x32_bf16 v[30:33], v[154:157], v[178:181], v[106:109]
	v_mfma_f32_16x16x32_bf16 v[106:109], v[158:161], v[182:185], v[30:33]
	v_mfma_f32_16x16x32_bf16 v[30:33], v[146:149], v[186:189], v[98:101]
	v_mfma_f32_16x16x32_bf16 v[98:101], v[150:153], v[190:193], v[30:33]
	v_mfma_f32_16x16x32_bf16 v[30:33], v[154:157], v[186:189], v[102:105]
	v_mfma_f32_16x16x32_bf16 v[102:105], v[158:161], v[190:193], v[30:33]
	s_barrier
	s_setprio 0
	s_add_u32 s38, s38, 0x100
	s_addc_u32 s39, s39, 0
	s_add_u32 s15, s15, 0x100
	s_addc_u32 s21, s21, 0
	s_cmp_ge_u32 s41, s56
	s_mov_b32 s22, s41
	s_cbranch_scc0 .LBB0_883

.LBB0_989:
	s_add_u32 s36, s38, 0x80080
	s_addc_u32 s37, s39, 0
	s_add_u32 s5, s22, 0x100
	s_addc_u32 s13, s23, 0
	s_mov_b32 s15, -2
	s_add_u32 s17, s36, 0xfff80080
	s_addc_u32 s22, s37, -1
	s_add_i32 s48, 0, 0x10000
	s_cmp_eq_u32 s15, 4
	s_cselect_b32 s39, s19, s22
	s_cselect_b32 s38, s18, s17
	s_cselect_b32 s23, s21, s13
	s_cselect_b32 s22, s20, s5
	s_add_i32 s17, 0, 0x14000
	v_add_u32_e32 v156, s48, v140
	v_add_u32_e32 v172, s17, v140
	ds_read_b128 v[144:147], v156
	ds_read_b128 v[148:151], v156 offset:1024
	ds_read_b128 v[152:155], v156 offset:2048
	ds_read_b128 v[156:159], v156 offset:3072
	ds_read_b128 v[160:163], v172
	ds_read_b128 v[164:167], v172 offset:1024
	ds_read_b128 v[168:171], v172 offset:2048
	ds_read_b128 v[172:175], v172 offset:3072
	v_lshl_add_u64 v[208:209], s[36:37], 0, v[136:137]
	s_add_i32 m0, s7, 0xc000
	ds_read_b128 v[176:179], v143
	ds_read_b128 v[180:183], v143 offset:1024
	ds_read_b128 v[184:187], v143 offset:2048
	ds_read_b128 v[188:191], v143 offset:3072
	ds_read_b128 v[192:195], v143 offset:4096
	ds_read_b128 v[196:199], v143 offset:5120
	ds_read_b128 v[200:203], v143 offset:6144
	ds_read_b128 v[204:207], v143 offset:7168
	global_load_lds_dwordx4 v[208:209], off
	v_lshl_add_u64 v[208:209], s[36:37], 0, v[138:139]
	s_add_i32 m0, s7, 0xe000
	s_nop 0
	global_load_lds_dwordx4 v[208:209], off
	s_waitcnt vmcnt(8)
	s_waitcnt lgkmcnt(0)
	s_setprio 1
	s_barrier
	v_mfma_f32_16x16x32_bf16 v[126:129], v[144:147], v[176:179], 0
	v_mfma_f32_16x16x32_bf16 v[122:125], v[152:155], v[176:179], 0
	v_mfma_f32_16x16x32_bf16 v[118:121], v[144:147], v[184:187], 0
	v_mfma_f32_16x16x32_bf16 v[114:117], v[152:155], v[184:187], 0
	v_mfma_f32_16x16x32_bf16 v[102:105], v[144:147], v[192:195], 0
	v_mfma_f32_16x16x32_bf16 v[98:101], v[152:155], v[192:195], 0
	v_mfma_f32_16x16x32_bf16 v[86:89], v[144:147], v[200:203], 0
	v_mfma_f32_16x16x32_bf16 v[82:85], v[152:155], v[200:203], 0
	v_mfma_f32_16x16x32_bf16 v[126:129], v[148:151], v[180:183], v[126:129]
	v_mfma_f32_16x16x32_bf16 v[122:125], v[156:159], v[180:183], v[122:125]
	v_mfma_f32_16x16x32_bf16 v[118:121], v[148:151], v[188:191], v[118:121]
	v_mfma_f32_16x16x32_bf16 v[114:117], v[156:159], v[188:191], v[114:117]
	v_mfma_f32_16x16x32_bf16 v[102:105], v[148:151], v[196:199], v[102:105]
	v_mfma_f32_16x16x32_bf16 v[98:101], v[156:159], v[196:199], v[98:101]
	v_mfma_f32_16x16x32_bf16 v[86:89], v[148:151], v[204:207], v[86:89]
	v_mfma_f32_16x16x32_bf16 v[82:85], v[156:159], v[204:207], v[82:85]
	s_setprio 0
	s_setprio 1
	v_mfma_f32_16x16x32_bf16 v[110:113], v[160:163], v[176:179], 0
	v_mfma_f32_16x16x32_bf16 v[106:109], v[168:171], v[176:179], 0
	v_mfma_f32_16x16x32_bf16 v[94:97], v[160:163], v[184:187], 0
	v_mfma_f32_16x16x32_bf16 v[90:93], v[168:171], v[184:187], 0
	v_mfma_f32_16x16x32_bf16 v[78:81], v[160:163], v[192:195], 0
	v_mfma_f32_16x16x32_bf16 v[74:77], v[168:171], v[192:195], 0
	v_mfma_f32_16x16x32_bf16 v[70:73], v[160:163], v[200:203], 0
	v_mfma_f32_16x16x32_bf16 v[66:69], v[168:171], v[200:203], 0
	v_mfma_f32_16x16x32_bf16 v[110:113], v[164:167], v[180:183], v[110:113]
	v_mfma_f32_16x16x32_bf16 v[106:109], v[172:175], v[180:183], v[106:109]
	v_mfma_f32_16x16x32_bf16 v[94:97], v[164:167], v[188:191], v[94:97]
	v_mfma_f32_16x16x32_bf16 v[90:93], v[172:175], v[188:191], v[90:93]
	v_mfma_f32_16x16x32_bf16 v[78:81], v[164:167], v[196:199], v[78:81]
	v_mfma_f32_16x16x32_bf16 v[74:77], v[172:175], v[196:199], v[74:77]
	v_mfma_f32_16x16x32_bf16 v[70:73], v[164:167], v[204:207], v[70:73]
	v_mfma_f32_16x16x32_bf16 v[66:69], v[172:175], v[204:207], v[66:69]
	s_barrier
	s_setprio 0
	s_add_i32 s48, s48, s40
	v_lshl_add_u64 v[208:209], s[22:23], 0, v[0:1]
	s_mov_b32 m0, s48
	ds_read_b128 v[176:179], v143 offset:16384
	ds_read_b128 v[180:183], v143 offset:17408
	ds_read_b128 v[184:187], v143 offset:18432
	ds_read_b128 v[188:191], v143 offset:19456
	ds_read_b128 v[192:195], v143 offset:20480
	ds_read_b128 v[196:199], v143 offset:21504
	ds_read_b128 v[200:203], v143 offset:22528
	ds_read_b128 v[204:207], v143 offset:23552
	global_load_lds_dwordx4 v[208:209], off
	s_add_i32 m0, s48, 0x2000
	s_add_u32 s48, s22, 0x80000
	v_lshl_add_u64 v[216:217], s[22:23], 0, v[130:131]
	s_addc_u32 s49, s23, 0
	s_add_i32 s17, s17, s40
	global_load_lds_dwordx4 v[216:217], off
	v_lshl_add_u64 v[220:221], s[48:49], 0, v[0:1]
	s_mov_b32 m0, s17
	v_lshl_add_u64 v[222:223], s[38:39], 0, v[132:133]
	global_load_lds_dwordx4 v[220:221], off
	v_lshl_add_u64 v[220:221], s[48:49], 0, v[130:131]
	s_add_i32 m0, s17, 0x2000
	s_nop 0
	global_load_lds_dwordx4 v[220:221], off
	v_lshl_add_u64 v[220:221], s[38:39], 0, v[134:135]
	s_mov_b32 m0, s7
	s_nop 0
	global_load_lds_dwordx4 v[220:221], off
	s_mov_b32 m0, s9
	s_nop 0
	global_load_lds_dwordx4 v[222:223], off
	s_waitcnt vmcnt(8)
	s_waitcnt lgkmcnt(0)
	s_setprio 1
	s_barrier
	v_mfma_f32_16x16x32_bf16 v[62:65], v[144:147], v[176:179], 0
	v_mfma_f32_16x16x32_bf16 v[58:61], v[152:155], v[176:179], 0
	v_mfma_f32_16x16x32_bf16 v[54:57], v[144:147], v[184:187], 0
	v_mfma_f32_16x16x32_bf16 v[50:53], v[152:155], v[184:187], 0
	v_mfma_f32_16x16x32_bf16 v[38:41], v[144:147], v[192:195], 0
	v_mfma_f32_16x16x32_bf16 v[34:37], v[152:155], v[192:195], 0
	v_mfma_f32_16x16x32_bf16 v[22:25], v[144:147], v[200:203], 0
	v_mfma_f32_16x16x32_bf16 v[18:21], v[152:155], v[200:203], 0
	v_mfma_f32_16x16x32_bf16 v[62:65], v[148:151], v[180:183], v[62:65]
	v_mfma_f32_16x16x32_bf16 v[58:61], v[156:159], v[180:183], v[58:61]
	v_mfma_f32_16x16x32_bf16 v[54:57], v[148:151], v[188:191], v[54:57]
	v_mfma_f32_16x16x32_bf16 v[50:53], v[156:159], v[188:191], v[50:53]
	v_mfma_f32_16x16x32_bf16 v[38:41], v[148:151], v[196:199], v[38:41]
	v_mfma_f32_16x16x32_bf16 v[34:37], v[156:159], v[196:199], v[34:37]
	v_mfma_f32_16x16x32_bf16 v[22:25], v[148:151], v[204:207], v[22:25]
	v_mfma_f32_16x16x32_bf16 v[18:21], v[156:159], v[204:207], v[18:21]
	s_setprio 0
	s_setprio 1
	v_mfma_f32_16x16x32_bf16 v[46:49], v[160:163], v[176:179], 0
	v_mfma_f32_16x16x32_bf16 v[42:45], v[168:171], v[176:179], 0
	v_mfma_f32_16x16x32_bf16 v[30:33], v[160:163], v[184:187], 0
	v_mfma_f32_16x16x32_bf16 v[26:29], v[168:171], v[184:187], 0
	v_mfma_f32_16x16x32_bf16 v[14:17], v[160:163], v[192:195], 0
	v_mfma_f32_16x16x32_bf16 v[10:13], v[168:171], v[192:195], 0
	v_mfma_f32_16x16x32_bf16 v[6:9], v[160:163], v[200:203], 0
	v_mfma_f32_16x16x32_bf16 v[2:5], v[168:171], v[200:203], 0
	v_mfma_f32_16x16x32_bf16 v[46:49], v[164:167], v[180:183], v[46:49]
	v_mfma_f32_16x16x32_bf16 v[42:45], v[172:175], v[180:183], v[42:45]
	v_mfma_f32_16x16x32_bf16 v[30:33], v[164:167], v[188:191], v[30:33]
	v_mfma_f32_16x16x32_bf16 v[26:29], v[172:175], v[188:191], v[26:29]
	v_mfma_f32_16x16x32_bf16 v[14:17], v[164:167], v[196:199], v[14:17]
	v_mfma_f32_16x16x32_bf16 v[10:13], v[172:175], v[196:199], v[10:13]
	v_mfma_f32_16x16x32_bf16 v[6:9], v[164:167], v[204:207], v[6:9]
	v_mfma_f32_16x16x32_bf16 v[2:5], v[172:175], v[204:207], v[2:5]
	s_barrier
	s_setprio 0
	s_add_i32 s17, 0, 0x18000
	s_add_i32 s48, 0, 0x1c000
	v_add_u32_e32 v156, s17, v140
	v_add_u32_e32 v172, s48, v140
	ds_read_b128 v[144:147], v156
	ds_read_b128 v[148:151], v156 offset:1024
	ds_read_b128 v[152:155], v156 offset:2048
	ds_read_b128 v[156:159], v156 offset:3072
	ds_read_b128 v[160:163], v172
	ds_read_b128 v[164:167], v172 offset:1024
	ds_read_b128 v[168:171], v172 offset:2048
	ds_read_b128 v[172:175], v172 offset:3072
	s_add_u32 s38, s38, 0x80000
	s_addc_u32 s39, s39, 0
	s_mov_b32 m0, s42
	v_lshl_add_u64 v[224:225], s[38:39], 0, v[134:135]
	ds_read_b128 v[176:179], v143 offset:32768
	ds_read_b128 v[180:183], v143 offset:33792
	ds_read_b128 v[184:187], v143 offset:34816
	ds_read_b128 v[188:191], v143 offset:35840
	ds_read_b128 v[192:195], v143 offset:36864
	ds_read_b128 v[196:199], v143 offset:37888
	ds_read_b128 v[200:203], v143 offset:38912
	ds_read_b128 v[204:207], v143 offset:39936
	global_load_lds_dwordx4 v[224:225], off
	v_lshl_add_u64 v[224:225], s[38:39], 0, v[132:133]
	s_mov_b32 m0, s43
	s_nop 0
	global_load_lds_dwordx4 v[224:225], off
	s_waitcnt vmcnt(8)
	s_waitcnt lgkmcnt(0)
	s_setprio 1
	s_barrier
	v_mfma_f32_16x16x32_bf16 v[126:129], v[144:147], v[176:179], v[126:129]
	v_mfma_f32_16x16x32_bf16 v[122:125], v[152:155], v[176:179], v[122:125]
	v_mfma_f32_16x16x32_bf16 v[118:121], v[144:147], v[184:187], v[118:121]
	v_mfma_f32_16x16x32_bf16 v[114:117], v[152:155], v[184:187], v[114:117]
	v_mfma_f32_16x16x32_bf16 v[102:105], v[144:147], v[192:195], v[102:105]
	v_mfma_f32_16x16x32_bf16 v[98:101], v[152:155], v[192:195], v[98:101]
	v_mfma_f32_16x16x32_bf16 v[86:89], v[144:147], v[200:203], v[86:89]
	v_mfma_f32_16x16x32_bf16 v[82:85], v[152:155], v[200:203], v[82:85]
	v_mfma_f32_16x16x32_bf16 v[126:129], v[148:151], v[180:183], v[126:129]
	v_mfma_f32_16x16x32_bf16 v[122:125], v[156:159], v[180:183], v[122:125]
	v_mfma_f32_16x16x32_bf16 v[118:121], v[148:151], v[188:191], v[118:121]
	v_mfma_f32_16x16x32_bf16 v[114:117], v[156:159], v[188:191], v[114:117]
	v_mfma_f32_16x16x32_bf16 v[102:105], v[148:151], v[196:199], v[102:105]
	v_mfma_f32_16x16x32_bf16 v[98:101], v[156:159], v[196:199], v[98:101]
	v_mfma_f32_16x16x32_bf16 v[86:89], v[148:151], v[204:207], v[86:89]
	v_mfma_f32_16x16x32_bf16 v[82:85], v[156:159], v[204:207], v[82:85]
	s_setprio 0
	s_setprio 1
	v_mfma_f32_16x16x32_bf16 v[110:113], v[160:163], v[176:179], v[110:113]
	v_mfma_f32_16x16x32_bf16 v[106:109], v[168:171], v[176:179], v[106:109]
	v_mfma_f32_16x16x32_bf16 v[94:97], v[160:163], v[184:187], v[94:97]
	v_mfma_f32_16x16x32_bf16 v[90:93], v[168:171], v[184:187], v[90:93]
	v_mfma_f32_16x16x32_bf16 v[78:81], v[160:163], v[192:195], v[78:81]
	v_mfma_f32_16x16x32_bf16 v[74:77], v[168:171], v[192:195], v[74:77]
	v_mfma_f32_16x16x32_bf16 v[70:73], v[160:163], v[200:203], v[70:73]
	v_mfma_f32_16x16x32_bf16 v[66:69], v[168:171], v[200:203], v[66:69]
	v_mfma_f32_16x16x32_bf16 v[110:113], v[164:167], v[180:183], v[110:113]
	v_mfma_f32_16x16x32_bf16 v[106:109], v[172:175], v[180:183], v[106:109]
	v_mfma_f32_16x16x32_bf16 v[94:97], v[164:167], v[188:191], v[94:97]
	v_mfma_f32_16x16x32_bf16 v[90:93], v[172:175], v[188:191], v[90:93]
	v_mfma_f32_16x16x32_bf16 v[78:81], v[164:167], v[196:199], v[78:81]
	v_mfma_f32_16x16x32_bf16 v[74:77], v[172:175], v[196:199], v[74:77]
	v_mfma_f32_16x16x32_bf16 v[70:73], v[164:167], v[204:207], v[70:73]
	v_mfma_f32_16x16x32_bf16 v[66:69], v[172:175], v[204:207], v[66:69]
	s_barrier
	s_setprio 0
	s_add_i32 s17, s17, s40
	v_lshl_add_u64 v[208:209], v[208:209], 0, s[2:3]
	s_mov_b32 m0, s17
	ds_read_b128 v[176:179], v143 offset:49152
	ds_read_b128 v[180:183], v143 offset:50176
	ds_read_b128 v[184:187], v143 offset:51200
	ds_read_b128 v[188:191], v143 offset:52224
	ds_read_b128 v[192:195], v143 offset:53248
	ds_read_b128 v[196:199], v143 offset:54272
	ds_read_b128 v[200:203], v143 offset:55296
	ds_read_b128 v[204:207], v143 offset:56320
	global_load_lds_dwordx4 v[208:209], off
	s_add_i32 m0, s17, 0x2000
	s_add_u32 s22, s22, 0x80080
	v_lshl_add_u64 v[208:209], v[216:217], 0, s[2:3]
	s_addc_u32 s23, s23, 0
	s_add_i32 s17, s48, s40
	global_load_lds_dwordx4 v[208:209], off
	v_lshl_add_u64 v[208:209], s[22:23], 0, v[0:1]
	s_mov_b32 m0, s17
	s_nop 0
	global_load_lds_dwordx4 v[208:209], off
	v_lshl_add_u64 v[208:209], s[22:23], 0, v[130:131]
	s_add_i32 m0, s17, 0x2000
	s_nop 0
	global_load_lds_dwordx4 v[208:209], off
	v_lshl_add_u64 v[208:209], v[220:221], 0, s[2:3]
	s_mov_b32 m0, s44
	s_nop 0
	global_load_lds_dwordx4 v[208:209], off
	v_lshl_add_u64 v[208:209], v[222:223], 0, s[2:3]
	s_mov_b32 m0, s45
	s_nop 0
	global_load_lds_dwordx4 v[208:209], off
	s_nop 0
	s_waitcnt vmcnt(8)
	s_waitcnt lgkmcnt(0)
	s_setprio 1
	s_barrier
	v_mfma_f32_16x16x32_bf16 v[62:65], v[144:147], v[176:179], v[62:65]
	v_mfma_f32_16x16x32_bf16 v[58:61], v[152:155], v[176:179], v[58:61]
	v_mfma_f32_16x16x32_bf16 v[54:57], v[144:147], v[184:187], v[54:57]
	v_mfma_f32_16x16x32_bf16 v[50:53], v[152:155], v[184:187], v[50:53]
	v_mfma_f32_16x16x32_bf16 v[38:41], v[144:147], v[192:195], v[38:41]
	v_mfma_f32_16x16x32_bf16 v[34:37], v[152:155], v[192:195], v[34:37]
	v_mfma_f32_16x16x32_bf16 v[22:25], v[144:147], v[200:203], v[22:25]
	v_mfma_f32_16x16x32_bf16 v[18:21], v[152:155], v[200:203], v[18:21]
	v_mfma_f32_16x16x32_bf16 v[62:65], v[148:151], v[180:183], v[62:65]
	v_mfma_f32_16x16x32_bf16 v[58:61], v[156:159], v[180:183], v[58:61]
	v_mfma_f32_16x16x32_bf16 v[54:57], v[148:151], v[188:191], v[54:57]
	v_mfma_f32_16x16x32_bf16 v[50:53], v[156:159], v[188:191], v[50:53]
	v_mfma_f32_16x16x32_bf16 v[38:41], v[148:151], v[196:199], v[38:41]
	v_mfma_f32_16x16x32_bf16 v[34:37], v[156:159], v[196:199], v[34:37]
	v_mfma_f32_16x16x32_bf16 v[22:25], v[148:151], v[204:207], v[22:25]
	v_mfma_f32_16x16x32_bf16 v[18:21], v[156:159], v[204:207], v[18:21]
	s_setprio 0
	s_setprio 1
	v_mfma_f32_16x16x32_bf16 v[46:49], v[160:163], v[176:179], v[46:49]
	v_mfma_f32_16x16x32_bf16 v[42:45], v[168:171], v[176:179], v[42:45]
	v_mfma_f32_16x16x32_bf16 v[30:33], v[160:163], v[184:187], v[30:33]
	v_mfma_f32_16x16x32_bf16 v[26:29], v[168:171], v[184:187], v[26:29]
	v_mfma_f32_16x16x32_bf16 v[14:17], v[160:163], v[192:195], v[14:17]
	v_mfma_f32_16x16x32_bf16 v[10:13], v[168:171], v[192:195], v[10:13]
	v_mfma_f32_16x16x32_bf16 v[6:9], v[160:163], v[200:203], v[6:9]
	v_mfma_f32_16x16x32_bf16 v[2:5], v[168:171], v[200:203], v[2:5]
	v_mfma_f32_16x16x32_bf16 v[46:49], v[164:167], v[180:183], v[46:49]
	v_mfma_f32_16x16x32_bf16 v[42:45], v[172:175], v[180:183], v[42:45]
	v_mfma_f32_16x16x32_bf16 v[30:33], v[164:167], v[188:191], v[30:33]
	v_mfma_f32_16x16x32_bf16 v[26:29], v[172:175], v[188:191], v[26:29]
	v_mfma_f32_16x16x32_bf16 v[14:17], v[164:167], v[196:199], v[14:17]
	v_mfma_f32_16x16x32_bf16 v[10:13], v[172:175], v[196:199], v[10:13]
	v_mfma_f32_16x16x32_bf16 v[6:9], v[164:167], v[204:207], v[6:9]
	v_mfma_f32_16x16x32_bf16 v[2:5], v[172:175], v[204:207], v[2:5]
	s_barrier
	s_setprio 0
	s_add_i32 s15, s15, 2
	s_add_u32 s36, s36, 0x100
	s_addc_u32 s37, s37, 0
	s_add_u32 s5, s5, 0x100
	s_addc_u32 s13, s13, 0
	s_cmp_gt_u32 s15, 5
	s_cbranch_scc1 .Lpeel_done_2
.LBB0_990:
	s_add_u32 s17, s36, 0xfff80080
	s_addc_u32 s22, s37, -1
	s_add_i32 s48, 0, 0x10000
	s_cmp_eq_u32 s15, 4
	s_cselect_b32 s39, s19, s22
	s_cselect_b32 s38, s18, s17
	s_cselect_b32 s23, s21, s13
	s_cselect_b32 s22, s20, s5
	s_add_i32 s17, 0, 0x14000
	v_add_u32_e32 v156, s48, v140
	v_add_u32_e32 v172, s17, v140
	ds_read_b128 v[144:147], v156
	ds_read_b128 v[148:151], v156 offset:1024
	ds_read_b128 v[152:155], v156 offset:2048
	ds_read_b128 v[156:159], v156 offset:3072
	ds_read_b128 v[160:163], v172
	ds_read_b128 v[164:167], v172 offset:1024
	ds_read_b128 v[168:171], v172 offset:2048
	ds_read_b128 v[172:175], v172 offset:3072
	v_lshl_add_u64 v[208:209], s[36:37], 0, v[136:137]
	s_add_i32 m0, s7, 0xc000
	ds_read_b128 v[176:179], v143
	ds_read_b128 v[180:183], v143 offset:1024
	ds_read_b128 v[184:187], v143 offset:2048
	ds_read_b128 v[188:191], v143 offset:3072
	ds_read_b128 v[192:195], v143 offset:4096
	ds_read_b128 v[196:199], v143 offset:5120
	ds_read_b128 v[200:203], v143 offset:6144
	ds_read_b128 v[204:207], v143 offset:7168
	global_load_lds_dwordx4 v[208:209], off
	v_lshl_add_u64 v[208:209], s[36:37], 0, v[138:139]
	s_add_i32 m0, s7, 0xe000
	s_nop 0
	global_load_lds_dwordx4 v[208:209], off
	s_waitcnt vmcnt(8)
	s_waitcnt lgkmcnt(0)
	s_setprio 1
	s_barrier
	v_mfma_f32_16x16x32_bf16 v[126:129], v[144:147], v[176:179], v[126:129]
	v_mfma_f32_16x16x32_bf16 v[122:125], v[152:155], v[176:179], v[122:125]
	v_mfma_f32_16x16x32_bf16 v[118:121], v[144:147], v[184:187], v[118:121]
	v_mfma_f32_16x16x32_bf16 v[114:117], v[152:155], v[184:187], v[114:117]
	v_mfma_f32_16x16x32_bf16 v[102:105], v[144:147], v[192:195], v[102:105]
	v_mfma_f32_16x16x32_bf16 v[98:101], v[152:155], v[192:195], v[98:101]
	v_mfma_f32_16x16x32_bf16 v[86:89], v[144:147], v[200:203], v[86:89]
	v_mfma_f32_16x16x32_bf16 v[82:85], v[152:155], v[200:203], v[82:85]
	v_mfma_f32_16x16x32_bf16 v[126:129], v[148:151], v[180:183], v[126:129]
	v_mfma_f32_16x16x32_bf16 v[122:125], v[156:159], v[180:183], v[122:125]
	v_mfma_f32_16x16x32_bf16 v[118:121], v[148:151], v[188:191], v[118:121]
	v_mfma_f32_16x16x32_bf16 v[114:117], v[156:159], v[188:191], v[114:117]
	v_mfma_f32_16x16x32_bf16 v[102:105], v[148:151], v[196:199], v[102:105]
	v_mfma_f32_16x16x32_bf16 v[98:101], v[156:159], v[196:199], v[98:101]
	v_mfma_f32_16x16x32_bf16 v[86:89], v[148:151], v[204:207], v[86:89]
	v_mfma_f32_16x16x32_bf16 v[82:85], v[156:159], v[204:207], v[82:85]
	s_setprio 0
	s_setprio 1
	v_mfma_f32_16x16x32_bf16 v[110:113], v[160:163], v[176:179], v[110:113]
	v_mfma_f32_16x16x32_bf16 v[106:109], v[168:171], v[176:179], v[106:109]
	v_mfma_f32_16x16x32_bf16 v[94:97], v[160:163], v[184:187], v[94:97]
	v_mfma_f32_16x16x32_bf16 v[90:93], v[168:171], v[184:187], v[90:93]
	v_mfma_f32_16x16x32_bf16 v[78:81], v[160:163], v[192:195], v[78:81]
	v_mfma_f32_16x16x32_bf16 v[74:77], v[168:171], v[192:195], v[74:77]
	v_mfma_f32_16x16x32_bf16 v[70:73], v[160:163], v[200:203], v[70:73]
	v_mfma_f32_16x16x32_bf16 v[66:69], v[168:171], v[200:203], v[66:69]
	v_mfma_f32_16x16x32_bf16 v[110:113], v[164:167], v[180:183], v[110:113]
	v_mfma_f32_16x16x32_bf16 v[106:109], v[172:175], v[180:183], v[106:109]
	v_mfma_f32_16x16x32_bf16 v[94:97], v[164:167], v[188:191], v[94:97]
	v_mfma_f32_16x16x32_bf16 v[90:93], v[172:175], v[188:191], v[90:93]
	v_mfma_f32_16x16x32_bf16 v[78:81], v[164:167], v[196:199], v[78:81]
	v_mfma_f32_16x16x32_bf16 v[74:77], v[172:175], v[196:199], v[74:77]
	v_mfma_f32_16x16x32_bf16 v[70:73], v[164:167], v[204:207], v[70:73]
	v_mfma_f32_16x16x32_bf16 v[66:69], v[172:175], v[204:207], v[66:69]
	s_barrier
	s_setprio 0
	s_add_i32 s48, s48, s40
	v_lshl_add_u64 v[208:209], s[22:23], 0, v[0:1]
	s_mov_b32 m0, s48
	ds_read_b128 v[176:179], v143 offset:16384
	ds_read_b128 v[180:183], v143 offset:17408
	ds_read_b128 v[184:187], v143 offset:18432
	ds_read_b128 v[188:191], v143 offset:19456
	ds_read_b128 v[192:195], v143 offset:20480
	ds_read_b128 v[196:199], v143 offset:21504
	ds_read_b128 v[200:203], v143 offset:22528
	ds_read_b128 v[204:207], v143 offset:23552
	global_load_lds_dwordx4 v[208:209], off
	s_add_i32 m0, s48, 0x2000
	s_add_u32 s48, s22, 0x80000
	v_lshl_add_u64 v[216:217], s[22:23], 0, v[130:131]
	s_addc_u32 s49, s23, 0
	s_add_i32 s17, s17, s40
	global_load_lds_dwordx4 v[216:217], off
	v_lshl_add_u64 v[220:221], s[48:49], 0, v[0:1]
	s_mov_b32 m0, s17
	v_lshl_add_u64 v[222:223], s[38:39], 0, v[132:133]
	global_load_lds_dwordx4 v[220:221], off
	v_lshl_add_u64 v[220:221], s[48:49], 0, v[130:131]
	s_add_i32 m0, s17, 0x2000
	s_nop 0
	global_load_lds_dwordx4 v[220:221], off
	v_lshl_add_u64 v[220:221], s[38:39], 0, v[134:135]
	s_mov_b32 m0, s7
	s_nop 0
	global_load_lds_dwordx4 v[220:221], off
	s_mov_b32 m0, s9
	s_nop 0
	global_load_lds_dwordx4 v[222:223], off
	s_waitcnt vmcnt(8)
	s_waitcnt lgkmcnt(0)
	s_setprio 1
	s_barrier
	v_mfma_f32_16x16x32_bf16 v[62:65], v[144:147], v[176:179], v[62:65]
	v_mfma_f32_16x16x32_bf16 v[58:61], v[152:155], v[176:179], v[58:61]
	v_mfma_f32_16x16x32_bf16 v[54:57], v[144:147], v[184:187], v[54:57]
	v_mfma_f32_16x16x32_bf16 v[50:53], v[152:155], v[184:187], v[50:53]
	v_mfma_f32_16x16x32_bf16 v[38:41], v[144:147], v[192:195], v[38:41]
	v_mfma_f32_16x16x32_bf16 v[34:37], v[152:155], v[192:195], v[34:37]
	v_mfma_f32_16x16x32_bf16 v[22:25], v[144:147], v[200:203], v[22:25]
	v_mfma_f32_16x16x32_bf16 v[18:21], v[152:155], v[200:203], v[18:21]
	v_mfma_f32_16x16x32_bf16 v[62:65], v[148:151], v[180:183], v[62:65]
	v_mfma_f32_16x16x32_bf16 v[58:61], v[156:159], v[180:183], v[58:61]
	v_mfma_f32_16x16x32_bf16 v[54:57], v[148:151], v[188:191], v[54:57]
	v_mfma_f32_16x16x32_bf16 v[50:53], v[156:159], v[188:191], v[50:53]
	v_mfma_f32_16x16x32_bf16 v[38:41], v[148:151], v[196:199], v[38:41]
	v_mfma_f32_16x16x32_bf16 v[34:37], v[156:159], v[196:199], v[34:37]
	v_mfma_f32_16x16x32_bf16 v[22:25], v[148:151], v[204:207], v[22:25]
	v_mfma_f32_16x16x32_bf16 v[18:21], v[156:159], v[204:207], v[18:21]
	s_setprio 0
	s_setprio 1
	v_mfma_f32_16x16x32_bf16 v[46:49], v[160:163], v[176:179], v[46:49]
	v_mfma_f32_16x16x32_bf16 v[42:45], v[168:171], v[176:179], v[42:45]
	v_mfma_f32_16x16x32_bf16 v[30:33], v[160:163], v[184:187], v[30:33]
	v_mfma_f32_16x16x32_bf16 v[26:29], v[168:171], v[184:187], v[26:29]
	v_mfma_f32_16x16x32_bf16 v[14:17], v[160:163], v[192:195], v[14:17]
	v_mfma_f32_16x16x32_bf16 v[10:13], v[168:171], v[192:195], v[10:13]
	v_mfma_f32_16x16x32_bf16 v[6:9], v[160:163], v[200:203], v[6:9]
	v_mfma_f32_16x16x32_bf16 v[2:5], v[168:171], v[200:203], v[2:5]
	v_mfma_f32_16x16x32_bf16 v[46:49], v[164:167], v[180:183], v[46:49]
	v_mfma_f32_16x16x32_bf16 v[42:45], v[172:175], v[180:183], v[42:45]
	v_mfma_f32_16x16x32_bf16 v[30:33], v[164:167], v[188:191], v[30:33]
	v_mfma_f32_16x16x32_bf16 v[26:29], v[172:175], v[188:191], v[26:29]
	v_mfma_f32_16x16x32_bf16 v[14:17], v[164:167], v[196:199], v[14:17]
	v_mfma_f32_16x16x32_bf16 v[10:13], v[172:175], v[196:199], v[10:13]
	v_mfma_f32_16x16x32_bf16 v[6:9], v[164:167], v[204:207], v[6:9]
	v_mfma_f32_16x16x32_bf16 v[2:5], v[172:175], v[204:207], v[2:5]
	s_barrier
	s_setprio 0
	s_add_i32 s17, 0, 0x18000
	s_add_i32 s48, 0, 0x1c000
	v_add_u32_e32 v156, s17, v140
	v_add_u32_e32 v172, s48, v140
	ds_read_b128 v[144:147], v156
	ds_read_b128 v[148:151], v156 offset:1024
	ds_read_b128 v[152:155], v156 offset:2048
	ds_read_b128 v[156:159], v156 offset:3072
	ds_read_b128 v[160:163], v172
	ds_read_b128 v[164:167], v172 offset:1024
	ds_read_b128 v[168:171], v172 offset:2048
	ds_read_b128 v[172:175], v172 offset:3072
	s_add_u32 s38, s38, 0x80000
	s_addc_u32 s39, s39, 0
	s_mov_b32 m0, s42
	v_lshl_add_u64 v[224:225], s[38:39], 0, v[134:135]
	ds_read_b128 v[176:179], v143 offset:32768
	ds_read_b128 v[180:183], v143 offset:33792
	ds_read_b128 v[184:187], v143 offset:34816
	ds_read_b128 v[188:191], v143 offset:35840
	ds_read_b128 v[192:195], v143 offset:36864
	ds_read_b128 v[196:199], v143 offset:37888
	ds_read_b128 v[200:203], v143 offset:38912
	ds_read_b128 v[204:207], v143 offset:39936
	global_load_lds_dwordx4 v[224:225], off
	v_lshl_add_u64 v[224:225], s[38:39], 0, v[132:133]
	s_mov_b32 m0, s43
	s_nop 0
	global_load_lds_dwordx4 v[224:225], off
	s_waitcnt vmcnt(8)
	s_waitcnt lgkmcnt(0)
	s_setprio 1
	s_barrier
	v_mfma_f32_16x16x32_bf16 v[126:129], v[144:147], v[176:179], v[126:129]
	v_mfma_f32_16x16x32_bf16 v[122:125], v[152:155], v[176:179], v[122:125]
	v_mfma_f32_16x16x32_bf16 v[118:121], v[144:147], v[184:187], v[118:121]
	v_mfma_f32_16x16x32_bf16 v[114:117], v[152:155], v[184:187], v[114:117]
	v_mfma_f32_16x16x32_bf16 v[102:105], v[144:147], v[192:195], v[102:105]
	v_mfma_f32_16x16x32_bf16 v[98:101], v[152:155], v[192:195], v[98:101]
	v_mfma_f32_16x16x32_bf16 v[86:89], v[144:147], v[200:203], v[86:89]
	v_mfma_f32_16x16x32_bf16 v[82:85], v[152:155], v[200:203], v[82:85]
	v_mfma_f32_16x16x32_bf16 v[126:129], v[148:151], v[180:183], v[126:129]
	v_mfma_f32_16x16x32_bf16 v[122:125], v[156:159], v[180:183], v[122:125]
	v_mfma_f32_16x16x32_bf16 v[118:121], v[148:151], v[188:191], v[118:121]
	v_mfma_f32_16x16x32_bf16 v[114:117], v[156:159], v[188:191], v[114:117]
	v_mfma_f32_16x16x32_bf16 v[102:105], v[148:151], v[196:199], v[102:105]
	v_mfma_f32_16x16x32_bf16 v[98:101], v[156:159], v[196:199], v[98:101]
	v_mfma_f32_16x16x32_bf16 v[86:89], v[148:151], v[204:207], v[86:89]
	v_mfma_f32_16x16x32_bf16 v[82:85], v[156:159], v[204:207], v[82:85]
	s_setprio 0
	s_setprio 1
	v_mfma_f32_16x16x32_bf16 v[110:113], v[160:163], v[176:179], v[110:113]
	v_mfma_f32_16x16x32_bf16 v[106:109], v[168:171], v[176:179], v[106:109]
	v_mfma_f32_16x16x32_bf16 v[94:97], v[160:163], v[184:187], v[94:97]
	v_mfma_f32_16x16x32_bf16 v[90:93], v[168:171], v[184:187], v[90:93]
	v_mfma_f32_16x16x32_bf16 v[78:81], v[160:163], v[192:195], v[78:81]
	v_mfma_f32_16x16x32_bf16 v[74:77], v[168:171], v[192:195], v[74:77]
	v_mfma_f32_16x16x32_bf16 v[70:73], v[160:163], v[200:203], v[70:73]
	v_mfma_f32_16x16x32_bf16 v[66:69], v[168:171], v[200:203], v[66:69]
	v_mfma_f32_16x16x32_bf16 v[110:113], v[164:167], v[180:183], v[110:113]
	v_mfma_f32_16x16x32_bf16 v[106:109], v[172:175], v[180:183], v[106:109]
	v_mfma_f32_16x16x32_bf16 v[94:97], v[164:167], v[188:191], v[94:97]
	v_mfma_f32_16x16x32_bf16 v[90:93], v[172:175], v[188:191], v[90:93]
	v_mfma_f32_16x16x32_bf16 v[78:81], v[164:167], v[196:199], v[78:81]
	v_mfma_f32_16x16x32_bf16 v[74:77], v[172:175], v[196:199], v[74:77]
	v_mfma_f32_16x16x32_bf16 v[70:73], v[164:167], v[204:207], v[70:73]
	v_mfma_f32_16x16x32_bf16 v[66:69], v[172:175], v[204:207], v[66:69]
	s_barrier
	s_setprio 0
	s_add_i32 s17, s17, s40
	v_lshl_add_u64 v[208:209], v[208:209], 0, s[2:3]
	s_mov_b32 m0, s17
	ds_read_b128 v[176:179], v143 offset:49152
	ds_read_b128 v[180:183], v143 offset:50176
	ds_read_b128 v[184:187], v143 offset:51200
	ds_read_b128 v[188:191], v143 offset:52224
	ds_read_b128 v[192:195], v143 offset:53248
	ds_read_b128 v[196:199], v143 offset:54272
	ds_read_b128 v[200:203], v143 offset:55296
	ds_read_b128 v[204:207], v143 offset:56320
	global_load_lds_dwordx4 v[208:209], off
	s_add_i32 m0, s17, 0x2000
	s_add_u32 s22, s22, 0x80080
	v_lshl_add_u64 v[208:209], v[216:217], 0, s[2:3]
	s_addc_u32 s23, s23, 0
	s_add_i32 s17, s48, s40
	global_load_lds_dwordx4 v[208:209], off
	v_lshl_add_u64 v[208:209], s[22:23], 0, v[0:1]
	s_mov_b32 m0, s17
	s_nop 0
	global_load_lds_dwordx4 v[208:209], off
	v_lshl_add_u64 v[208:209], s[22:23], 0, v[130:131]
	s_add_i32 m0, s17, 0x2000
	s_nop 0
	global_load_lds_dwordx4 v[208:209], off
	v_lshl_add_u64 v[208:209], v[220:221], 0, s[2:3]
	s_mov_b32 m0, s44
	s_nop 0
	global_load_lds_dwordx4 v[208:209], off
	v_lshl_add_u64 v[208:209], v[222:223], 0, s[2:3]
	s_mov_b32 m0, s45
	s_nop 0
	global_load_lds_dwordx4 v[208:209], off
	s_nop 0
	s_waitcnt vmcnt(8)
	s_waitcnt lgkmcnt(0)
	s_setprio 1
	s_barrier
	v_mfma_f32_16x16x32_bf16 v[62:65], v[144:147], v[176:179], v[62:65]
	v_mfma_f32_16x16x32_bf16 v[58:61], v[152:155], v[176:179], v[58:61]
	v_mfma_f32_16x16x32_bf16 v[54:57], v[144:147], v[184:187], v[54:57]
	v_mfma_f32_16x16x32_bf16 v[50:53], v[152:155], v[184:187], v[50:53]
	v_mfma_f32_16x16x32_bf16 v[38:41], v[144:147], v[192:195], v[38:41]
	v_mfma_f32_16x16x32_bf16 v[34:37], v[152:155], v[192:195], v[34:37]
	v_mfma_f32_16x16x32_bf16 v[22:25], v[144:147], v[200:203], v[22:25]
	v_mfma_f32_16x16x32_bf16 v[18:21], v[152:155], v[200:203], v[18:21]
	v_mfma_f32_16x16x32_bf16 v[62:65], v[148:151], v[180:183], v[62:65]
	v_mfma_f32_16x16x32_bf16 v[58:61], v[156:159], v[180:183], v[58:61]
	v_mfma_f32_16x16x32_bf16 v[54:57], v[148:151], v[188:191], v[54:57]
	v_mfma_f32_16x16x32_bf16 v[50:53], v[156:159], v[188:191], v[50:53]
	v_mfma_f32_16x16x32_bf16 v[38:41], v[148:151], v[196:199], v[38:41]
	v_mfma_f32_16x16x32_bf16 v[34:37], v[156:159], v[196:199], v[34:37]
	v_mfma_f32_16x16x32_bf16 v[22:25], v[148:151], v[204:207], v[22:25]
	v_mfma_f32_16x16x32_bf16 v[18:21], v[156:159], v[204:207], v[18:21]
	s_setprio 0
	s_setprio 1
	v_mfma_f32_16x16x32_bf16 v[46:49], v[160:163], v[176:179], v[46:49]
	v_mfma_f32_16x16x32_bf16 v[42:45], v[168:171], v[176:179], v[42:45]
	v_mfma_f32_16x16x32_bf16 v[30:33], v[160:163], v[184:187], v[30:33]
	v_mfma_f32_16x16x32_bf16 v[26:29], v[168:171], v[184:187], v[26:29]
	v_mfma_f32_16x16x32_bf16 v[14:17], v[160:163], v[192:195], v[14:17]
	v_mfma_f32_16x16x32_bf16 v[10:13], v[168:171], v[192:195], v[10:13]
	v_mfma_f32_16x16x32_bf16 v[6:9], v[160:163], v[200:203], v[6:9]
	v_mfma_f32_16x16x32_bf16 v[2:5], v[168:171], v[200:203], v[2:5]
	v_mfma_f32_16x16x32_bf16 v[46:49], v[164:167], v[180:183], v[46:49]
	v_mfma_f32_16x16x32_bf16 v[42:45], v[172:175], v[180:183], v[42:45]
	v_mfma_f32_16x16x32_bf16 v[30:33], v[164:167], v[188:191], v[30:33]
	v_mfma_f32_16x16x32_bf16 v[26:29], v[172:175], v[188:191], v[26:29]
	v_mfma_f32_16x16x32_bf16 v[14:17], v[164:167], v[196:199], v[14:17]
	v_mfma_f32_16x16x32_bf16 v[10:13], v[172:175], v[196:199], v[10:13]
	v_mfma_f32_16x16x32_bf16 v[6:9], v[164:167], v[204:207], v[6:9]
	v_mfma_f32_16x16x32_bf16 v[2:5], v[172:175], v[204:207], v[2:5]
	s_barrier
	s_setprio 0
	s_add_i32 s15, s15, 2
	s_add_u32 s36, s36, 0x100
	s_addc_u32 s37, s37, 0
	s_add_u32 s5, s5, 0x100
	s_addc_u32 s13, s13, 0
	s_cmp_gt_u32 s15, 5
	s_cbranch_scc0 .LBB0_990

.LBB0_1200:
	s_ashr_i32 s7, s6, 31
	s_lshl_b64 s[12:13], s[6:7], 18
	s_add_u32 s12, s78, s12
	v_readlane_b32 s7, v254, 37
	s_addc_u32 s13, s7, s13
	s_and_b64 s[22:23], s[22:23], exec
	s_cselect_b32 s7, s13, s21
	s_cselect_b32 s9, s12, s20
	s_add_u32 s18, s18, 0x80080
	s_addc_u32 s19, s19, 0
	s_add_u32 s15, s20, 0x100
	s_addc_u32 s36, s21, 0
	s_mov_b32 s37, -2
	s_add_u32 s20, s18, 0xfff80080
	s_addc_u32 s21, s19, -1
	s_add_i32 s47, 0, 0x10000
	s_cmp_eq_u32 s37, 4
	s_cselect_b32 s23, s11, s21
	s_cselect_b32 s22, s10, s20
	s_cselect_b32 s21, s7, s36
	s_cselect_b32 s20, s9, s15
	s_add_i32 s50, 0, 0x14000
	v_add_u32_e32 v142, s47, v171
	v_add_u32_e32 v168, s50, v171
	ds_read_b128 v[130:133], v142
	ds_read_b128 v[134:137], v142 offset:1024
	ds_read_b128 v[138:141], v142 offset:2048
	ds_read_b128 v[142:145], v142 offset:3072
	ds_read_b128 v[156:159], v168
	ds_read_b128 v[160:163], v168 offset:1024
	ds_read_b128 v[164:167], v168 offset:2048
	ds_read_b128 v[174:177], v168 offset:3072
	v_lshl_add_u64 v[168:169], s[18:19], 0, v[152:153]
	s_add_i32 m0, s17, 0xc000
	ds_read_b128 v[178:181], v173
	ds_read_b128 v[182:185], v173 offset:1024
	ds_read_b128 v[186:189], v173 offset:2048
	ds_read_b128 v[190:193], v173 offset:3072
	ds_read_b128 v[194:197], v173 offset:4096
	ds_read_b128 v[198:201], v173 offset:5120
	ds_read_b128 v[202:205], v173 offset:6144
	ds_read_b128 v[206:209], v173 offset:7168
	global_load_lds_dwordx4 v[168:169], off
	v_lshl_add_u64 v[168:169], s[18:19], 0, v[154:155]
	s_add_i32 m0, s17, 0xe000
	s_nop 0
	global_load_lds_dwordx4 v[168:169], off
	s_nop 0
	s_waitcnt vmcnt(8)
	s_waitcnt lgkmcnt(0)
	s_setprio 1
	s_barrier
	v_mfma_f32_16x16x32_bf16 v[126:129], v[130:133], v[178:181], 0
	v_mfma_f32_16x16x32_bf16 v[122:125], v[138:141], v[178:181], 0
	v_mfma_f32_16x16x32_bf16 v[118:121], v[130:133], v[186:189], 0
	v_mfma_f32_16x16x32_bf16 v[106:109], v[138:141], v[186:189], 0
	v_mfma_f32_16x16x32_bf16 v[98:101], v[130:133], v[194:197], 0
	v_mfma_f32_16x16x32_bf16 v[90:93], v[138:141], v[194:197], 0
	v_mfma_f32_16x16x32_bf16 v[82:85], v[130:133], v[202:205], 0
	v_mfma_f32_16x16x32_bf16 v[74:77], v[138:141], v[202:205], 0
	v_mfma_f32_16x16x32_bf16 v[126:129], v[134:137], v[182:185], v[126:129]
	v_mfma_f32_16x16x32_bf16 v[122:125], v[142:145], v[182:185], v[122:125]
	v_mfma_f32_16x16x32_bf16 v[118:121], v[134:137], v[190:193], v[118:121]
	v_mfma_f32_16x16x32_bf16 v[106:109], v[142:145], v[190:193], v[106:109]
	v_mfma_f32_16x16x32_bf16 v[98:101], v[134:137], v[198:201], v[98:101]
	v_mfma_f32_16x16x32_bf16 v[90:93], v[142:145], v[198:201], v[90:93]
	v_mfma_f32_16x16x32_bf16 v[82:85], v[134:137], v[206:209], v[82:85]
	v_mfma_f32_16x16x32_bf16 v[74:77], v[142:145], v[206:209], v[74:77]
	s_setprio 0
	s_setprio 1
	v_mfma_f32_16x16x32_bf16 v[114:117], v[156:159], v[178:181], 0
	v_mfma_f32_16x16x32_bf16 v[110:113], v[164:167], v[178:181], 0
	v_mfma_f32_16x16x32_bf16 v[102:105], v[156:159], v[186:189], 0
	v_mfma_f32_16x16x32_bf16 v[94:97], v[164:167], v[186:189], 0
	v_mfma_f32_16x16x32_bf16 v[86:89], v[156:159], v[194:197], 0
	v_mfma_f32_16x16x32_bf16 v[78:81], v[164:167], v[194:197], 0
	v_mfma_f32_16x16x32_bf16 v[70:73], v[156:159], v[202:205], 0
	v_mfma_f32_16x16x32_bf16 v[66:69], v[164:167], v[202:205], 0
	v_mfma_f32_16x16x32_bf16 v[114:117], v[160:163], v[182:185], v[114:117]
	v_mfma_f32_16x16x32_bf16 v[110:113], v[174:177], v[182:185], v[110:113]
	v_mfma_f32_16x16x32_bf16 v[102:105], v[160:163], v[190:193], v[102:105]
	v_mfma_f32_16x16x32_bf16 v[94:97], v[174:177], v[190:193], v[94:97]
	v_mfma_f32_16x16x32_bf16 v[86:89], v[160:163], v[198:201], v[86:89]
	v_mfma_f32_16x16x32_bf16 v[78:81], v[174:177], v[198:201], v[78:81]
	v_mfma_f32_16x16x32_bf16 v[70:73], v[160:163], v[206:209], v[70:73]
	v_mfma_f32_16x16x32_bf16 v[66:69], v[174:177], v[206:209], v[66:69]
	s_barrier
	s_setprio 0
	s_add_i32 s47, s47, s38
	v_lshl_add_u64 v[168:169], s[20:21], 0, v[0:1]
	s_mov_b32 m0, s47
	ds_read_b128 v[178:181], v173 offset:16384
	ds_read_b128 v[182:185], v173 offset:17408
	ds_read_b128 v[186:189], v173 offset:18432
	ds_read_b128 v[190:193], v173 offset:19456
	ds_read_b128 v[194:197], v173 offset:20480
	ds_read_b128 v[198:201], v173 offset:21504
	ds_read_b128 v[202:205], v173 offset:22528
	ds_read_b128 v[206:209], v173 offset:23552
	global_load_lds_dwordx4 v[168:169], off
	s_add_i32 m0, s47, 0x2000
	s_add_u32 s48, s20, 0x20000
	v_lshl_add_u64 v[216:217], s[20:21], 0, v[146:147]
	s_addc_u32 s49, s21, 0
	s_add_i32 s47, s50, s38
	global_load_lds_dwordx4 v[216:217], off
	v_lshl_add_u64 v[220:221], s[48:49], 0, v[0:1]
	s_mov_b32 m0, s47
	v_lshl_add_u64 v[222:223], s[22:23], 0, v[148:149]
	global_load_lds_dwordx4 v[220:221], off
	v_lshl_add_u64 v[220:221], s[48:49], 0, v[146:147]
	s_add_i32 m0, s47, 0x2000
	s_nop 0
	global_load_lds_dwordx4 v[220:221], off
	v_lshl_add_u64 v[220:221], s[22:23], 0, v[150:151]
	s_mov_b32 m0, s17
	s_nop 0
	global_load_lds_dwordx4 v[220:221], off
	s_mov_b32 m0, s40
	s_nop 0
	global_load_lds_dwordx4 v[222:223], off
	s_waitcnt vmcnt(8)
	s_waitcnt lgkmcnt(0)
	s_setprio 1
	s_barrier
	v_mfma_f32_16x16x32_bf16 v[62:65], v[130:133], v[178:181], 0
	v_mfma_f32_16x16x32_bf16 v[58:61], v[138:141], v[178:181], 0
	v_mfma_f32_16x16x32_bf16 v[50:53], v[130:133], v[186:189], 0
	v_mfma_f32_16x16x32_bf16 v[42:45], v[138:141], v[186:189], 0
	v_mfma_f32_16x16x32_bf16 v[34:37], v[130:133], v[194:197], 0
	v_mfma_f32_16x16x32_bf16 v[26:29], v[138:141], v[194:197], 0
	v_mfma_f32_16x16x32_bf16 v[18:21], v[130:133], v[202:205], 0
	v_mfma_f32_16x16x32_bf16 v[10:13], v[138:141], v[202:205], 0
	v_mfma_f32_16x16x32_bf16 v[62:65], v[134:137], v[182:185], v[62:65]
	v_mfma_f32_16x16x32_bf16 v[58:61], v[142:145], v[182:185], v[58:61]
	v_mfma_f32_16x16x32_bf16 v[50:53], v[134:137], v[190:193], v[50:53]
	v_mfma_f32_16x16x32_bf16 v[42:45], v[142:145], v[190:193], v[42:45]
	v_mfma_f32_16x16x32_bf16 v[34:37], v[134:137], v[198:201], v[34:37]
	v_mfma_f32_16x16x32_bf16 v[26:29], v[142:145], v[198:201], v[26:29]
	v_mfma_f32_16x16x32_bf16 v[18:21], v[134:137], v[206:209], v[18:21]
	v_mfma_f32_16x16x32_bf16 v[10:13], v[142:145], v[206:209], v[10:13]
	s_setprio 0
	s_setprio 1
	v_mfma_f32_16x16x32_bf16 v[54:57], v[156:159], v[178:181], 0
	v_mfma_f32_16x16x32_bf16 v[46:49], v[164:167], v[178:181], 0
	v_mfma_f32_16x16x32_bf16 v[38:41], v[156:159], v[186:189], 0
	v_mfma_f32_16x16x32_bf16 v[30:33], v[164:167], v[186:189], 0
	v_mfma_f32_16x16x32_bf16 v[22:25], v[156:159], v[194:197], 0
	v_mfma_f32_16x16x32_bf16 v[14:17], v[164:167], v[194:197], 0
	v_mfma_f32_16x16x32_bf16 v[6:9], v[156:159], v[202:205], 0
	v_mfma_f32_16x16x32_bf16 v[2:5], v[164:167], v[202:205], 0
	v_mfma_f32_16x16x32_bf16 v[54:57], v[160:163], v[182:185], v[54:57]
	v_mfma_f32_16x16x32_bf16 v[46:49], v[174:177], v[182:185], v[46:49]
	v_mfma_f32_16x16x32_bf16 v[38:41], v[160:163], v[190:193], v[38:41]
	v_mfma_f32_16x16x32_bf16 v[30:33], v[174:177], v[190:193], v[30:33]
	v_mfma_f32_16x16x32_bf16 v[22:25], v[160:163], v[198:201], v[22:25]
	v_mfma_f32_16x16x32_bf16 v[14:17], v[174:177], v[198:201], v[14:17]
	v_mfma_f32_16x16x32_bf16 v[6:9], v[160:163], v[206:209], v[6:9]
	v_mfma_f32_16x16x32_bf16 v[2:5], v[174:177], v[206:209], v[2:5]
	s_barrier
	s_setprio 0
	s_add_i32 s47, 0, 0x18000
	s_add_i32 s48, 0, 0x1c000
	v_add_u32_e32 v142, s47, v171
	v_add_u32_e32 v174, s48, v171
	ds_read_b128 v[130:133], v142
	ds_read_b128 v[134:137], v142 offset:1024
	ds_read_b128 v[138:141], v142 offset:2048
	ds_read_b128 v[142:145], v142 offset:3072
	ds_read_b128 v[156:159], v174
	ds_read_b128 v[160:163], v174 offset:1024
	ds_read_b128 v[164:167], v174 offset:2048
	ds_read_b128 v[174:177], v174 offset:3072
	s_add_u32 s22, s22, 0x80000
	s_addc_u32 s23, s23, 0
	s_mov_b32 m0, s41
	v_lshl_add_u64 v[224:225], s[22:23], 0, v[150:151]
	ds_read_b128 v[178:181], v173 offset:32768
	ds_read_b128 v[182:185], v173 offset:33792
	ds_read_b128 v[186:189], v173 offset:34816
	ds_read_b128 v[190:193], v173 offset:35840
	ds_read_b128 v[194:197], v173 offset:36864
	ds_read_b128 v[198:201], v173 offset:37888
	ds_read_b128 v[202:205], v173 offset:38912
	ds_read_b128 v[206:209], v173 offset:39936
	global_load_lds_dwordx4 v[224:225], off
	v_lshl_add_u64 v[224:225], s[22:23], 0, v[148:149]
	s_mov_b32 m0, s42
	s_nop 0
	global_load_lds_dwordx4 v[224:225], off
	s_waitcnt vmcnt(8)
	s_waitcnt lgkmcnt(0)
	s_setprio 1
	s_barrier
	v_mfma_f32_16x16x32_bf16 v[126:129], v[130:133], v[178:181], v[126:129]
	v_mfma_f32_16x16x32_bf16 v[122:125], v[138:141], v[178:181], v[122:125]
	v_mfma_f32_16x16x32_bf16 v[118:121], v[130:133], v[186:189], v[118:121]
	v_mfma_f32_16x16x32_bf16 v[106:109], v[138:141], v[186:189], v[106:109]
	v_mfma_f32_16x16x32_bf16 v[98:101], v[130:133], v[194:197], v[98:101]
	v_mfma_f32_16x16x32_bf16 v[90:93], v[138:141], v[194:197], v[90:93]
	v_mfma_f32_16x16x32_bf16 v[82:85], v[130:133], v[202:205], v[82:85]
	v_mfma_f32_16x16x32_bf16 v[74:77], v[138:141], v[202:205], v[74:77]
	v_mfma_f32_16x16x32_bf16 v[126:129], v[134:137], v[182:185], v[126:129]
	v_mfma_f32_16x16x32_bf16 v[122:125], v[142:145], v[182:185], v[122:125]
	v_mfma_f32_16x16x32_bf16 v[118:121], v[134:137], v[190:193], v[118:121]
	v_mfma_f32_16x16x32_bf16 v[106:109], v[142:145], v[190:193], v[106:109]
	v_mfma_f32_16x16x32_bf16 v[98:101], v[134:137], v[198:201], v[98:101]
	v_mfma_f32_16x16x32_bf16 v[90:93], v[142:145], v[198:201], v[90:93]
	v_mfma_f32_16x16x32_bf16 v[82:85], v[134:137], v[206:209], v[82:85]
	v_mfma_f32_16x16x32_bf16 v[74:77], v[142:145], v[206:209], v[74:77]
	s_setprio 0
	s_setprio 1
	v_mfma_f32_16x16x32_bf16 v[114:117], v[156:159], v[178:181], v[114:117]
	v_mfma_f32_16x16x32_bf16 v[110:113], v[164:167], v[178:181], v[110:113]
	v_mfma_f32_16x16x32_bf16 v[102:105], v[156:159], v[186:189], v[102:105]
	v_mfma_f32_16x16x32_bf16 v[94:97], v[164:167], v[186:189], v[94:97]
	v_mfma_f32_16x16x32_bf16 v[86:89], v[156:159], v[194:197], v[86:89]
	v_mfma_f32_16x16x32_bf16 v[78:81], v[164:167], v[194:197], v[78:81]
	v_mfma_f32_16x16x32_bf16 v[70:73], v[156:159], v[202:205], v[70:73]
	v_mfma_f32_16x16x32_bf16 v[66:69], v[164:167], v[202:205], v[66:69]
	v_mfma_f32_16x16x32_bf16 v[114:117], v[160:163], v[182:185], v[114:117]
	v_mfma_f32_16x16x32_bf16 v[110:113], v[174:177], v[182:185], v[110:113]
	v_mfma_f32_16x16x32_bf16 v[102:105], v[160:163], v[190:193], v[102:105]
	v_mfma_f32_16x16x32_bf16 v[94:97], v[174:177], v[190:193], v[94:97]
	v_mfma_f32_16x16x32_bf16 v[86:89], v[160:163], v[198:201], v[86:89]
	v_mfma_f32_16x16x32_bf16 v[78:81], v[174:177], v[198:201], v[78:81]
	v_mfma_f32_16x16x32_bf16 v[70:73], v[160:163], v[206:209], v[70:73]
	v_mfma_f32_16x16x32_bf16 v[66:69], v[174:177], v[206:209], v[66:69]
	s_barrier
	s_setprio 0
	s_add_i32 s22, s47, s38
	v_lshl_add_u64 v[168:169], v[168:169], 0, s[2:3]
	s_mov_b32 m0, s22
	ds_read_b128 v[178:181], v173 offset:49152
	ds_read_b128 v[182:185], v173 offset:50176
	ds_read_b128 v[186:189], v173 offset:51200
	ds_read_b128 v[190:193], v173 offset:52224
	ds_read_b128 v[194:197], v173 offset:53248
	ds_read_b128 v[198:201], v173 offset:54272
	ds_read_b128 v[202:205], v173 offset:55296
	ds_read_b128 v[206:209], v173 offset:56320
	global_load_lds_dwordx4 v[168:169], off
	s_add_i32 m0, s22, 0x2000
	s_add_u32 s20, s20, 0x20080
	v_lshl_add_u64 v[168:169], v[216:217], 0, s[2:3]
	s_addc_u32 s21, s21, 0
	s_add_i32 s22, s48, s38
	global_load_lds_dwordx4 v[168:169], off
	v_lshl_add_u64 v[168:169], s[20:21], 0, v[0:1]
	s_mov_b32 m0, s22
	s_nop 0
	global_load_lds_dwordx4 v[168:169], off
	v_lshl_add_u64 v[168:169], s[20:21], 0, v[146:147]
	s_add_i32 m0, s22, 0x2000
	s_nop 0
	global_load_lds_dwordx4 v[168:169], off
	v_lshl_add_u64 v[168:169], v[220:221], 0, s[2:3]
	s_mov_b32 m0, s43
	s_nop 0
	global_load_lds_dwordx4 v[168:169], off
	v_lshl_add_u64 v[168:169], v[222:223], 0, s[2:3]
	s_mov_b32 m0, s44
	s_nop 0
	global_load_lds_dwordx4 v[168:169], off
	s_nop 0
	s_waitcnt vmcnt(8)
	s_waitcnt lgkmcnt(0)
	s_setprio 1
	s_barrier
	v_mfma_f32_16x16x32_bf16 v[62:65], v[130:133], v[178:181], v[62:65]
	v_mfma_f32_16x16x32_bf16 v[58:61], v[138:141], v[178:181], v[58:61]
	v_mfma_f32_16x16x32_bf16 v[50:53], v[130:133], v[186:189], v[50:53]
	v_mfma_f32_16x16x32_bf16 v[42:45], v[138:141], v[186:189], v[42:45]
	v_mfma_f32_16x16x32_bf16 v[34:37], v[130:133], v[194:197], v[34:37]
	v_mfma_f32_16x16x32_bf16 v[26:29], v[138:141], v[194:197], v[26:29]
	v_mfma_f32_16x16x32_bf16 v[18:21], v[130:133], v[202:205], v[18:21]
	v_mfma_f32_16x16x32_bf16 v[10:13], v[138:141], v[202:205], v[10:13]
	v_mfma_f32_16x16x32_bf16 v[62:65], v[134:137], v[182:185], v[62:65]
	v_mfma_f32_16x16x32_bf16 v[58:61], v[142:145], v[182:185], v[58:61]
	v_mfma_f32_16x16x32_bf16 v[50:53], v[134:137], v[190:193], v[50:53]
	v_mfma_f32_16x16x32_bf16 v[42:45], v[142:145], v[190:193], v[42:45]
	v_mfma_f32_16x16x32_bf16 v[34:37], v[134:137], v[198:201], v[34:37]
	v_mfma_f32_16x16x32_bf16 v[26:29], v[142:145], v[198:201], v[26:29]
	v_mfma_f32_16x16x32_bf16 v[18:21], v[134:137], v[206:209], v[18:21]
	v_mfma_f32_16x16x32_bf16 v[10:13], v[142:145], v[206:209], v[10:13]
	s_setprio 0
	s_setprio 1
	v_mfma_f32_16x16x32_bf16 v[54:57], v[156:159], v[178:181], v[54:57]
	v_mfma_f32_16x16x32_bf16 v[46:49], v[164:167], v[178:181], v[46:49]
	v_mfma_f32_16x16x32_bf16 v[38:41], v[156:159], v[186:189], v[38:41]
	v_mfma_f32_16x16x32_bf16 v[30:33], v[164:167], v[186:189], v[30:33]
	v_mfma_f32_16x16x32_bf16 v[22:25], v[156:159], v[194:197], v[22:25]
	v_mfma_f32_16x16x32_bf16 v[14:17], v[164:167], v[194:197], v[14:17]
	v_mfma_f32_16x16x32_bf16 v[6:9], v[156:159], v[202:205], v[6:9]
	v_mfma_f32_16x16x32_bf16 v[2:5], v[164:167], v[202:205], v[2:5]
	v_mfma_f32_16x16x32_bf16 v[54:57], v[160:163], v[182:185], v[54:57]
	v_mfma_f32_16x16x32_bf16 v[46:49], v[174:177], v[182:185], v[46:49]
	v_mfma_f32_16x16x32_bf16 v[38:41], v[160:163], v[190:193], v[38:41]
	v_mfma_f32_16x16x32_bf16 v[30:33], v[174:177], v[190:193], v[30:33]
	v_mfma_f32_16x16x32_bf16 v[22:25], v[160:163], v[198:201], v[22:25]
	v_mfma_f32_16x16x32_bf16 v[14:17], v[174:177], v[198:201], v[14:17]
	v_mfma_f32_16x16x32_bf16 v[6:9], v[160:163], v[206:209], v[6:9]
	v_mfma_f32_16x16x32_bf16 v[2:5], v[174:177], v[206:209], v[2:5]
	s_barrier
	s_setprio 0
	s_add_i32 s37, s37, 2
	s_add_u32 s18, s18, 0x100
	s_addc_u32 s19, s19, 0
	s_add_u32 s15, s15, 0x100
	s_addc_u32 s36, s36, 0
	s_cmp_gt_u32 s37, 5
	s_cbranch_scc1 .Lpeel_done_3
.LBB0_1201:
	s_add_u32 s20, s18, 0xfff80080
	s_addc_u32 s21, s19, -1
	s_add_i32 s47, 0, 0x10000
	s_cmp_eq_u32 s37, 4
	s_cselect_b32 s23, s11, s21
	s_cselect_b32 s22, s10, s20
	s_cselect_b32 s21, s7, s36
	s_cselect_b32 s20, s9, s15
	s_add_i32 s50, 0, 0x14000
	v_add_u32_e32 v142, s47, v171
	v_add_u32_e32 v168, s50, v171
	ds_read_b128 v[130:133], v142
	ds_read_b128 v[134:137], v142 offset:1024
	ds_read_b128 v[138:141], v142 offset:2048
	ds_read_b128 v[142:145], v142 offset:3072
	ds_read_b128 v[156:159], v168
	ds_read_b128 v[160:163], v168 offset:1024
	ds_read_b128 v[164:167], v168 offset:2048
	ds_read_b128 v[174:177], v168 offset:3072
	v_lshl_add_u64 v[168:169], s[18:19], 0, v[152:153]
	s_add_i32 m0, s17, 0xc000
	ds_read_b128 v[178:181], v173
	ds_read_b128 v[182:185], v173 offset:1024
	ds_read_b128 v[186:189], v173 offset:2048
	ds_read_b128 v[190:193], v173 offset:3072
	ds_read_b128 v[194:197], v173 offset:4096
	ds_read_b128 v[198:201], v173 offset:5120
	ds_read_b128 v[202:205], v173 offset:6144
	ds_read_b128 v[206:209], v173 offset:7168
	global_load_lds_dwordx4 v[168:169], off
	v_lshl_add_u64 v[168:169], s[18:19], 0, v[154:155]
	s_add_i32 m0, s17, 0xe000
	s_nop 0
	global_load_lds_dwordx4 v[168:169], off
	s_waitcnt vmcnt(8)
	s_waitcnt lgkmcnt(0)
	s_setprio 1
	s_barrier
	v_mfma_f32_16x16x32_bf16 v[126:129], v[130:133], v[178:181], v[126:129]
	v_mfma_f32_16x16x32_bf16 v[122:125], v[138:141], v[178:181], v[122:125]
	v_mfma_f32_16x16x32_bf16 v[118:121], v[130:133], v[186:189], v[118:121]
	v_mfma_f32_16x16x32_bf16 v[106:109], v[138:141], v[186:189], v[106:109]
	v_mfma_f32_16x16x32_bf16 v[98:101], v[130:133], v[194:197], v[98:101]
	v_mfma_f32_16x16x32_bf16 v[90:93], v[138:141], v[194:197], v[90:93]
	v_mfma_f32_16x16x32_bf16 v[82:85], v[130:133], v[202:205], v[82:85]
	v_mfma_f32_16x16x32_bf16 v[74:77], v[138:141], v[202:205], v[74:77]
	v_mfma_f32_16x16x32_bf16 v[126:129], v[134:137], v[182:185], v[126:129]
	v_mfma_f32_16x16x32_bf16 v[122:125], v[142:145], v[182:185], v[122:125]
	v_mfma_f32_16x16x32_bf16 v[118:121], v[134:137], v[190:193], v[118:121]
	v_mfma_f32_16x16x32_bf16 v[106:109], v[142:145], v[190:193], v[106:109]
	v_mfma_f32_16x16x32_bf16 v[98:101], v[134:137], v[198:201], v[98:101]
	v_mfma_f32_16x16x32_bf16 v[90:93], v[142:145], v[198:201], v[90:93]
	v_mfma_f32_16x16x32_bf16 v[82:85], v[134:137], v[206:209], v[82:85]
	v_mfma_f32_16x16x32_bf16 v[74:77], v[142:145], v[206:209], v[74:77]
	s_setprio 0
	s_setprio 1
	v_mfma_f32_16x16x32_bf16 v[114:117], v[156:159], v[178:181], v[114:117]
	v_mfma_f32_16x16x32_bf16 v[110:113], v[164:167], v[178:181], v[110:113]
	v_mfma_f32_16x16x32_bf16 v[102:105], v[156:159], v[186:189], v[102:105]
	v_mfma_f32_16x16x32_bf16 v[94:97], v[164:167], v[186:189], v[94:97]
	v_mfma_f32_16x16x32_bf16 v[86:89], v[156:159], v[194:197], v[86:89]
	v_mfma_f32_16x16x32_bf16 v[78:81], v[164:167], v[194:197], v[78:81]
	v_mfma_f32_16x16x32_bf16 v[70:73], v[156:159], v[202:205], v[70:73]
	v_mfma_f32_16x16x32_bf16 v[66:69], v[164:167], v[202:205], v[66:69]
	v_mfma_f32_16x16x32_bf16 v[114:117], v[160:163], v[182:185], v[114:117]
	v_mfma_f32_16x16x32_bf16 v[110:113], v[174:177], v[182:185], v[110:113]
	v_mfma_f32_16x16x32_bf16 v[102:105], v[160:163], v[190:193], v[102:105]
	v_mfma_f32_16x16x32_bf16 v[94:97], v[174:177], v[190:193], v[94:97]
	v_mfma_f32_16x16x32_bf16 v[86:89], v[160:163], v[198:201], v[86:89]
	v_mfma_f32_16x16x32_bf16 v[78:81], v[174:177], v[198:201], v[78:81]
	v_mfma_f32_16x16x32_bf16 v[70:73], v[160:163], v[206:209], v[70:73]
	v_mfma_f32_16x16x32_bf16 v[66:69], v[174:177], v[206:209], v[66:69]
	s_barrier
	s_setprio 0
	s_add_i32 s47, s47, s38
	v_lshl_add_u64 v[168:169], s[20:21], 0, v[0:1]
	s_mov_b32 m0, s47
	ds_read_b128 v[178:181], v173 offset:16384
	ds_read_b128 v[182:185], v173 offset:17408
	ds_read_b128 v[186:189], v173 offset:18432
	ds_read_b128 v[190:193], v173 offset:19456
	ds_read_b128 v[194:197], v173 offset:20480
	ds_read_b128 v[198:201], v173 offset:21504
	ds_read_b128 v[202:205], v173 offset:22528
	ds_read_b128 v[206:209], v173 offset:23552
	global_load_lds_dwordx4 v[168:169], off
	s_add_i32 m0, s47, 0x2000
	s_add_u32 s48, s20, 0x20000
	v_lshl_add_u64 v[216:217], s[20:21], 0, v[146:147]
	s_addc_u32 s49, s21, 0
	s_add_i32 s47, s50, s38
	global_load_lds_dwordx4 v[216:217], off
	v_lshl_add_u64 v[220:221], s[48:49], 0, v[0:1]
	s_mov_b32 m0, s47
	v_lshl_add_u64 v[222:223], s[22:23], 0, v[148:149]
	global_load_lds_dwordx4 v[220:221], off
	v_lshl_add_u64 v[220:221], s[48:49], 0, v[146:147]
	s_add_i32 m0, s47, 0x2000
	s_nop 0
	global_load_lds_dwordx4 v[220:221], off
	v_lshl_add_u64 v[220:221], s[22:23], 0, v[150:151]
	s_mov_b32 m0, s17
	s_nop 0
	global_load_lds_dwordx4 v[220:221], off
	s_mov_b32 m0, s40
	s_nop 0
	global_load_lds_dwordx4 v[222:223], off
	s_waitcnt vmcnt(8)
	s_waitcnt lgkmcnt(0)
	s_setprio 1
	s_barrier
	v_mfma_f32_16x16x32_bf16 v[62:65], v[130:133], v[178:181], v[62:65]
	v_mfma_f32_16x16x32_bf16 v[58:61], v[138:141], v[178:181], v[58:61]
	v_mfma_f32_16x16x32_bf16 v[50:53], v[130:133], v[186:189], v[50:53]
	v_mfma_f32_16x16x32_bf16 v[42:45], v[138:141], v[186:189], v[42:45]
	v_mfma_f32_16x16x32_bf16 v[34:37], v[130:133], v[194:197], v[34:37]
	v_mfma_f32_16x16x32_bf16 v[26:29], v[138:141], v[194:197], v[26:29]
	v_mfma_f32_16x16x32_bf16 v[18:21], v[130:133], v[202:205], v[18:21]
	v_mfma_f32_16x16x32_bf16 v[10:13], v[138:141], v[202:205], v[10:13]
	v_mfma_f32_16x16x32_bf16 v[62:65], v[134:137], v[182:185], v[62:65]
	v_mfma_f32_16x16x32_bf16 v[58:61], v[142:145], v[182:185], v[58:61]
	v_mfma_f32_16x16x32_bf16 v[50:53], v[134:137], v[190:193], v[50:53]
	v_mfma_f32_16x16x32_bf16 v[42:45], v[142:145], v[190:193], v[42:45]
	v_mfma_f32_16x16x32_bf16 v[34:37], v[134:137], v[198:201], v[34:37]
	v_mfma_f32_16x16x32_bf16 v[26:29], v[142:145], v[198:201], v[26:29]
	v_mfma_f32_16x16x32_bf16 v[18:21], v[134:137], v[206:209], v[18:21]
	v_mfma_f32_16x16x32_bf16 v[10:13], v[142:145], v[206:209], v[10:13]
	s_setprio 0
	s_setprio 1
	v_mfma_f32_16x16x32_bf16 v[54:57], v[156:159], v[178:181], v[54:57]
	v_mfma_f32_16x16x32_bf16 v[46:49], v[164:167], v[178:181], v[46:49]
	v_mfma_f32_16x16x32_bf16 v[38:41], v[156:159], v[186:189], v[38:41]
	v_mfma_f32_16x16x32_bf16 v[30:33], v[164:167], v[186:189], v[30:33]
	v_mfma_f32_16x16x32_bf16 v[22:25], v[156:159], v[194:197], v[22:25]
	v_mfma_f32_16x16x32_bf16 v[14:17], v[164:167], v[194:197], v[14:17]
	v_mfma_f32_16x16x32_bf16 v[6:9], v[156:159], v[202:205], v[6:9]
	v_mfma_f32_16x16x32_bf16 v[2:5], v[164:167], v[202:205], v[2:5]
	v_mfma_f32_16x16x32_bf16 v[54:57], v[160:163], v[182:185], v[54:57]
	v_mfma_f32_16x16x32_bf16 v[46:49], v[174:177], v[182:185], v[46:49]
	v_mfma_f32_16x16x32_bf16 v[38:41], v[160:163], v[190:193], v[38:41]
	v_mfma_f32_16x16x32_bf16 v[30:33], v[174:177], v[190:193], v[30:33]
	v_mfma_f32_16x16x32_bf16 v[22:25], v[160:163], v[198:201], v[22:25]
	v_mfma_f32_16x16x32_bf16 v[14:17], v[174:177], v[198:201], v[14:17]
	v_mfma_f32_16x16x32_bf16 v[6:9], v[160:163], v[206:209], v[6:9]
	v_mfma_f32_16x16x32_bf16 v[2:5], v[174:177], v[206:209], v[2:5]
	s_barrier
	s_setprio 0
	s_add_i32 s47, 0, 0x18000
	s_add_i32 s48, 0, 0x1c000
	v_add_u32_e32 v142, s47, v171
	v_add_u32_e32 v174, s48, v171
	ds_read_b128 v[130:133], v142
	ds_read_b128 v[134:137], v142 offset:1024
	ds_read_b128 v[138:141], v142 offset:2048
	ds_read_b128 v[142:145], v142 offset:3072
	ds_read_b128 v[156:159], v174
	ds_read_b128 v[160:163], v174 offset:1024
	ds_read_b128 v[164:167], v174 offset:2048
	ds_read_b128 v[174:177], v174 offset:3072
	s_add_u32 s22, s22, 0x80000
	s_addc_u32 s23, s23, 0
	s_mov_b32 m0, s41
	v_lshl_add_u64 v[224:225], s[22:23], 0, v[150:151]
	ds_read_b128 v[178:181], v173 offset:32768
	ds_read_b128 v[182:185], v173 offset:33792
	ds_read_b128 v[186:189], v173 offset:34816
	ds_read_b128 v[190:193], v173 offset:35840
	ds_read_b128 v[194:197], v173 offset:36864
	ds_read_b128 v[198:201], v173 offset:37888
	ds_read_b128 v[202:205], v173 offset:38912
	ds_read_b128 v[206:209], v173 offset:39936
	global_load_lds_dwordx4 v[224:225], off
	v_lshl_add_u64 v[224:225], s[22:23], 0, v[148:149]
	s_mov_b32 m0, s42
	s_nop 0
	global_load_lds_dwordx4 v[224:225], off
	s_waitcnt vmcnt(8)
	s_waitcnt lgkmcnt(0)
	s_setprio 1
	s_barrier
	v_mfma_f32_16x16x32_bf16 v[126:129], v[130:133], v[178:181], v[126:129]
	v_mfma_f32_16x16x32_bf16 v[122:125], v[138:141], v[178:181], v[122:125]
	v_mfma_f32_16x16x32_bf16 v[118:121], v[130:133], v[186:189], v[118:121]
	v_mfma_f32_16x16x32_bf16 v[106:109], v[138:141], v[186:189], v[106:109]
	v_mfma_f32_16x16x32_bf16 v[98:101], v[130:133], v[194:197], v[98:101]
	v_mfma_f32_16x16x32_bf16 v[90:93], v[138:141], v[194:197], v[90:93]
	v_mfma_f32_16x16x32_bf16 v[82:85], v[130:133], v[202:205], v[82:85]
	v_mfma_f32_16x16x32_bf16 v[74:77], v[138:141], v[202:205], v[74:77]
	v_mfma_f32_16x16x32_bf16 v[126:129], v[134:137], v[182:185], v[126:129]
	v_mfma_f32_16x16x32_bf16 v[122:125], v[142:145], v[182:185], v[122:125]
	v_mfma_f32_16x16x32_bf16 v[118:121], v[134:137], v[190:193], v[118:121]
	v_mfma_f32_16x16x32_bf16 v[106:109], v[142:145], v[190:193], v[106:109]
	v_mfma_f32_16x16x32_bf16 v[98:101], v[134:137], v[198:201], v[98:101]
	v_mfma_f32_16x16x32_bf16 v[90:93], v[142:145], v[198:201], v[90:93]
	v_mfma_f32_16x16x32_bf16 v[82:85], v[134:137], v[206:209], v[82:85]
	v_mfma_f32_16x16x32_bf16 v[74:77], v[142:145], v[206:209], v[74:77]
	s_setprio 0
	s_setprio 1
	v_mfma_f32_16x16x32_bf16 v[114:117], v[156:159], v[178:181], v[114:117]
	v_mfma_f32_16x16x32_bf16 v[110:113], v[164:167], v[178:181], v[110:113]
	v_mfma_f32_16x16x32_bf16 v[102:105], v[156:159], v[186:189], v[102:105]
	v_mfma_f32_16x16x32_bf16 v[94:97], v[164:167], v[186:189], v[94:97]
	v_mfma_f32_16x16x32_bf16 v[86:89], v[156:159], v[194:197], v[86:89]
	v_mfma_f32_16x16x32_bf16 v[78:81], v[164:167], v[194:197], v[78:81]
	v_mfma_f32_16x16x32_bf16 v[70:73], v[156:159], v[202:205], v[70:73]
	v_mfma_f32_16x16x32_bf16 v[66:69], v[164:167], v[202:205], v[66:69]
	v_mfma_f32_16x16x32_bf16 v[114:117], v[160:163], v[182:185], v[114:117]
	v_mfma_f32_16x16x32_bf16 v[110:113], v[174:177], v[182:185], v[110:113]
	v_mfma_f32_16x16x32_bf16 v[102:105], v[160:163], v[190:193], v[102:105]
	v_mfma_f32_16x16x32_bf16 v[94:97], v[174:177], v[190:193], v[94:97]
	v_mfma_f32_16x16x32_bf16 v[86:89], v[160:163], v[198:201], v[86:89]
	v_mfma_f32_16x16x32_bf16 v[78:81], v[174:177], v[198:201], v[78:81]
	v_mfma_f32_16x16x32_bf16 v[70:73], v[160:163], v[206:209], v[70:73]
	v_mfma_f32_16x16x32_bf16 v[66:69], v[174:177], v[206:209], v[66:69]
	s_barrier
	s_setprio 0
	s_add_i32 s22, s47, s38
	v_lshl_add_u64 v[168:169], v[168:169], 0, s[2:3]
	s_mov_b32 m0, s22
	ds_read_b128 v[178:181], v173 offset:49152
	ds_read_b128 v[182:185], v173 offset:50176
	ds_read_b128 v[186:189], v173 offset:51200
	ds_read_b128 v[190:193], v173 offset:52224
	ds_read_b128 v[194:197], v173 offset:53248
	ds_read_b128 v[198:201], v173 offset:54272
	ds_read_b128 v[202:205], v173 offset:55296
	ds_read_b128 v[206:209], v173 offset:56320
	global_load_lds_dwordx4 v[168:169], off
	s_add_i32 m0, s22, 0x2000
	s_add_u32 s20, s20, 0x20080
	v_lshl_add_u64 v[168:169], v[216:217], 0, s[2:3]
	s_addc_u32 s21, s21, 0
	s_add_i32 s22, s48, s38
	global_load_lds_dwordx4 v[168:169], off
	v_lshl_add_u64 v[168:169], s[20:21], 0, v[0:1]
	s_mov_b32 m0, s22
	s_nop 0
	global_load_lds_dwordx4 v[168:169], off
	v_lshl_add_u64 v[168:169], s[20:21], 0, v[146:147]
	s_add_i32 m0, s22, 0x2000
	s_nop 0
	global_load_lds_dwordx4 v[168:169], off
	v_lshl_add_u64 v[168:169], v[220:221], 0, s[2:3]
	s_mov_b32 m0, s43
	s_nop 0
	global_load_lds_dwordx4 v[168:169], off
	v_lshl_add_u64 v[168:169], v[222:223], 0, s[2:3]
	s_mov_b32 m0, s44
	s_nop 0
	global_load_lds_dwordx4 v[168:169], off
	s_nop 0
	s_waitcnt vmcnt(8)
	s_waitcnt lgkmcnt(0)
	s_setprio 1
	s_barrier
	v_mfma_f32_16x16x32_bf16 v[62:65], v[130:133], v[178:181], v[62:65]
	v_mfma_f32_16x16x32_bf16 v[58:61], v[138:141], v[178:181], v[58:61]
	v_mfma_f32_16x16x32_bf16 v[50:53], v[130:133], v[186:189], v[50:53]
	v_mfma_f32_16x16x32_bf16 v[42:45], v[138:141], v[186:189], v[42:45]
	v_mfma_f32_16x16x32_bf16 v[34:37], v[130:133], v[194:197], v[34:37]
	v_mfma_f32_16x16x32_bf16 v[26:29], v[138:141], v[194:197], v[26:29]
	v_mfma_f32_16x16x32_bf16 v[18:21], v[130:133], v[202:205], v[18:21]
	v_mfma_f32_16x16x32_bf16 v[10:13], v[138:141], v[202:205], v[10:13]
	v_mfma_f32_16x16x32_bf16 v[62:65], v[134:137], v[182:185], v[62:65]
	v_mfma_f32_16x16x32_bf16 v[58:61], v[142:145], v[182:185], v[58:61]
	v_mfma_f32_16x16x32_bf16 v[50:53], v[134:137], v[190:193], v[50:53]
	v_mfma_f32_16x16x32_bf16 v[42:45], v[142:145], v[190:193], v[42:45]
	v_mfma_f32_16x16x32_bf16 v[34:37], v[134:137], v[198:201], v[34:37]
	v_mfma_f32_16x16x32_bf16 v[26:29], v[142:145], v[198:201], v[26:29]
	v_mfma_f32_16x16x32_bf16 v[18:21], v[134:137], v[206:209], v[18:21]
	v_mfma_f32_16x16x32_bf16 v[10:13], v[142:145], v[206:209], v[10:13]
	s_setprio 0
	s_setprio 1
	v_mfma_f32_16x16x32_bf16 v[54:57], v[156:159], v[178:181], v[54:57]
	v_mfma_f32_16x16x32_bf16 v[46:49], v[164:167], v[178:181], v[46:49]
	v_mfma_f32_16x16x32_bf16 v[38:41], v[156:159], v[186:189], v[38:41]
	v_mfma_f32_16x16x32_bf16 v[30:33], v[164:167], v[186:189], v[30:33]
	v_mfma_f32_16x16x32_bf16 v[22:25], v[156:159], v[194:197], v[22:25]
	v_mfma_f32_16x16x32_bf16 v[14:17], v[164:167], v[194:197], v[14:17]
	v_mfma_f32_16x16x32_bf16 v[6:9], v[156:159], v[202:205], v[6:9]
	v_mfma_f32_16x16x32_bf16 v[2:5], v[164:167], v[202:205], v[2:5]
	v_mfma_f32_16x16x32_bf16 v[54:57], v[160:163], v[182:185], v[54:57]
	v_mfma_f32_16x16x32_bf16 v[46:49], v[174:177], v[182:185], v[46:49]
	v_mfma_f32_16x16x32_bf16 v[38:41], v[160:163], v[190:193], v[38:41]
	v_mfma_f32_16x16x32_bf16 v[30:33], v[174:177], v[190:193], v[30:33]
	v_mfma_f32_16x16x32_bf16 v[22:25], v[160:163], v[198:201], v[22:25]
	v_mfma_f32_16x16x32_bf16 v[14:17], v[174:177], v[198:201], v[14:17]
	v_mfma_f32_16x16x32_bf16 v[6:9], v[160:163], v[206:209], v[6:9]
	v_mfma_f32_16x16x32_bf16 v[2:5], v[174:177], v[206:209], v[2:5]
	s_barrier
	s_setprio 0
	s_add_i32 s37, s37, 2
	s_add_u32 s18, s18, 0x100
	s_addc_u32 s19, s19, 0
	s_add_u32 s15, s15, 0x100
	s_addc_u32 s36, s36, 0
	s_cmp_gt_u32 s37, 5
	s_cbranch_scc0 .LBB0_1201

.LBB0_1564:
	s_ashr_i32 s9, s8, 31
	s_lshl_b64 s[10:11], s[8:9], 20
	v_readlane_b32 s12, v253, 25
	v_readlane_b32 s13, v253, 26
	s_add_u32 s10, s12, s10
	s_addc_u32 s11, s13, s11
	s_and_b64 s[12:13], s[34:35], exec
	s_cselect_b32 s9, s11, s19
	s_cselect_b32 s15, s10, s18
	s_ashr_i32 s7, s6, 31
	s_lshl_b64 s[12:13], s[6:7], 20
	s_add_u32 s12, s37, s12
	s_addc_u32 s13, s38, s13
	s_and_b64 s[22:23], s[34:35], exec
	s_cselect_b32 s7, s13, s21
	s_cselect_b32 s50, s12, s20
	s_add_u32 s18, s18, 0x80080
	s_addc_u32 s19, s19, 0
	s_add_u32 s51, s20, 0x100
	s_addc_u32 s52, s21, 0
	s_mov_b32 s53, -2
	s_add_u32 s20, s18, 0xfff80080
	s_addc_u32 s21, s19, -1
	s_add_i32 s54, 0, 0x10000
	s_cmp_eq_u32 s53, 28
	s_cselect_b32 s23, s9, s21
	s_cselect_b32 s22, s15, s20
	v_add_u32_e32 v158, s54, v160
	s_cselect_b32 s21, s7, s52
	s_cselect_b32 s20, s50, s51
	s_add_i32 s56, 0, 0x14000
	ds_read_b128 v[164:167], v158
	ds_read_b128 v[168:171], v158 offset:1024
	ds_read_b128 v[172:175], v158 offset:2048
	ds_read_b128 v[176:179], v158 offset:3072
	v_add_u32_e32 v158, s56, v160
	ds_read_b128 v[180:183], v158
	ds_read_b128 v[184:187], v158 offset:1024
	ds_read_b128 v[188:191], v158 offset:2048
	ds_read_b128 v[192:195], v158 offset:3072
	v_lshl_add_u64 v[158:159], s[18:19], 0, v[154:155]
	s_add_i32 m0, s17, 0xc000
	ds_read_b128 v[196:199], v162
	ds_read_b128 v[200:203], v162 offset:1024
	ds_read_b128 v[204:207], v162 offset:2048
	ds_read_b128 v[220:223], v162 offset:3072
	ds_read_b128 v[224:227], v162 offset:4096
	ds_read_b128 v[228:231], v162 offset:5120
	ds_read_b128 v[232:235], v162 offset:6144
	ds_read_b128 v[236:239], v162 offset:7168
	global_load_lds_dwordx4 v[158:159], off
	v_lshl_add_u64 v[158:159], s[18:19], 0, v[156:157]
	s_add_i32 m0, s17, 0xe000
	s_nop 0
	global_load_lds_dwordx4 v[158:159], off
	s_nop 0
	s_waitcnt vmcnt(8)
	s_waitcnt lgkmcnt(0)
	s_setprio 1
	s_barrier
	v_mfma_f32_16x16x32_bf16 v[122:125], v[164:167], v[196:199], 0
	v_mfma_f32_16x16x32_bf16 v[114:117], v[172:175], v[196:199], 0
	v_mfma_f32_16x16x32_bf16 v[106:109], v[164:167], v[204:207], 0
	v_mfma_f32_16x16x32_bf16 v[98:101], v[172:175], v[204:207], 0
	v_mfma_f32_16x16x32_bf16 v[90:93], v[164:167], v[224:227], 0
	v_mfma_f32_16x16x32_bf16 v[82:85], v[172:175], v[224:227], 0
	v_mfma_f32_16x16x32_bf16 v[74:77], v[164:167], v[232:235], 0
	v_mfma_f32_16x16x32_bf16 v[66:69], v[172:175], v[232:235], 0
	v_mfma_f32_16x16x32_bf16 v[122:125], v[168:171], v[200:203], v[122:125]
	v_mfma_f32_16x16x32_bf16 v[114:117], v[176:179], v[200:203], v[114:117]
	v_mfma_f32_16x16x32_bf16 v[106:109], v[168:171], v[220:223], v[106:109]
	v_mfma_f32_16x16x32_bf16 v[98:101], v[176:179], v[220:223], v[98:101]
	v_mfma_f32_16x16x32_bf16 v[90:93], v[168:171], v[228:231], v[90:93]
	v_mfma_f32_16x16x32_bf16 v[82:85], v[176:179], v[228:231], v[82:85]
	v_mfma_f32_16x16x32_bf16 v[74:77], v[168:171], v[236:239], v[74:77]
	v_mfma_f32_16x16x32_bf16 v[66:69], v[176:179], v[236:239], v[66:69]
	s_setprio 0
	s_setprio 1
	v_mfma_f32_16x16x32_bf16 v[126:129], v[180:183], v[196:199], 0
	v_mfma_f32_16x16x32_bf16 v[118:121], v[188:191], v[196:199], 0
	v_mfma_f32_16x16x32_bf16 v[110:113], v[180:183], v[204:207], 0
	v_mfma_f32_16x16x32_bf16 v[102:105], v[188:191], v[204:207], 0
	v_mfma_f32_16x16x32_bf16 v[94:97], v[180:183], v[224:227], 0
	v_mfma_f32_16x16x32_bf16 v[86:89], v[188:191], v[224:227], 0
	v_mfma_f32_16x16x32_bf16 v[78:81], v[180:183], v[232:235], 0
	v_mfma_f32_16x16x32_bf16 v[70:73], v[188:191], v[232:235], 0
	v_mfma_f32_16x16x32_bf16 v[126:129], v[184:187], v[200:203], v[126:129]
	v_mfma_f32_16x16x32_bf16 v[118:121], v[192:195], v[200:203], v[118:121]
	v_mfma_f32_16x16x32_bf16 v[110:113], v[184:187], v[220:223], v[110:113]
	v_mfma_f32_16x16x32_bf16 v[102:105], v[192:195], v[220:223], v[102:105]
	v_mfma_f32_16x16x32_bf16 v[94:97], v[184:187], v[228:231], v[94:97]
	v_mfma_f32_16x16x32_bf16 v[86:89], v[192:195], v[228:231], v[86:89]
	v_mfma_f32_16x16x32_bf16 v[78:81], v[184:187], v[236:239], v[78:81]
	v_mfma_f32_16x16x32_bf16 v[70:73], v[192:195], v[236:239], v[70:73]
	s_barrier
	s_setprio 0
	s_add_i32 s54, s54, s41
	v_lshl_add_u64 v[158:159], s[20:21], 0, v[0:1]
	s_mov_b32 m0, s54
	ds_read_b128 v[196:199], v162 offset:16384
	ds_read_b128 v[200:203], v162 offset:17408
	ds_read_b128 v[204:207], v162 offset:18432
	ds_read_b128 v[220:223], v162 offset:19456
	ds_read_b128 v[224:227], v162 offset:20480
	ds_read_b128 v[228:231], v162 offset:21504
	ds_read_b128 v[232:235], v162 offset:22528
	ds_read_b128 v[236:239], v162 offset:23552
	global_load_lds_dwordx4 v[158:159], off
	s_add_i32 m0, s54, 0x2000
	s_add_u32 s54, s20, 0x80000
	v_lshl_add_u64 v[208:209], s[20:21], 0, v[130:131]
	s_addc_u32 s55, s21, 0
	s_add_i32 s56, s56, s41
	global_load_lds_dwordx4 v[208:209], off
	v_lshl_add_u64 v[216:217], s[54:55], 0, v[0:1]
	s_mov_b32 m0, s56
	v_lshl_add_u64 v[244:245], s[22:23], 0, v[132:133]
	global_load_lds_dwordx4 v[216:217], off
	v_lshl_add_u64 v[216:217], s[54:55], 0, v[130:131]
	s_add_i32 m0, s56, 0x2000
	s_nop 0
	global_load_lds_dwordx4 v[216:217], off
	v_lshl_add_u64 v[216:217], s[22:23], 0, v[134:135]
	s_mov_b32 m0, s17
	s_nop 0
	global_load_lds_dwordx4 v[216:217], off
	s_mov_b32 m0, s43
	s_nop 0
	global_load_lds_dwordx4 v[244:245], off
	s_waitcnt vmcnt(8)
	s_waitcnt lgkmcnt(0)
	s_setprio 1
	s_barrier
	v_mfma_f32_16x16x32_bf16 v[58:61], v[164:167], v[196:199], 0
	v_mfma_f32_16x16x32_bf16 v[50:53], v[172:175], v[196:199], 0
	v_mfma_f32_16x16x32_bf16 v[42:45], v[164:167], v[204:207], 0
	v_mfma_f32_16x16x32_bf16 v[34:37], v[172:175], v[204:207], 0
	v_mfma_f32_16x16x32_bf16 v[26:29], v[164:167], v[224:227], 0
	v_mfma_f32_16x16x32_bf16 v[18:21], v[172:175], v[224:227], 0
	v_mfma_f32_16x16x32_bf16 v[10:13], v[164:167], v[232:235], 0
	v_mfma_f32_16x16x32_bf16 v[2:5], v[172:175], v[232:235], 0
	v_mfma_f32_16x16x32_bf16 v[58:61], v[168:171], v[200:203], v[58:61]
	v_mfma_f32_16x16x32_bf16 v[50:53], v[176:179], v[200:203], v[50:53]
	v_mfma_f32_16x16x32_bf16 v[42:45], v[168:171], v[220:223], v[42:45]
	v_mfma_f32_16x16x32_bf16 v[34:37], v[176:179], v[220:223], v[34:37]
	v_mfma_f32_16x16x32_bf16 v[26:29], v[168:171], v[228:231], v[26:29]
	v_mfma_f32_16x16x32_bf16 v[18:21], v[176:179], v[228:231], v[18:21]
	v_mfma_f32_16x16x32_bf16 v[10:13], v[168:171], v[236:239], v[10:13]
	v_mfma_f32_16x16x32_bf16 v[2:5], v[176:179], v[236:239], v[2:5]
	s_setprio 0
	s_setprio 1
	v_mfma_f32_16x16x32_bf16 v[62:65], v[180:183], v[196:199], 0
	v_mfma_f32_16x16x32_bf16 v[54:57], v[188:191], v[196:199], 0
	v_mfma_f32_16x16x32_bf16 v[46:49], v[180:183], v[204:207], 0
	v_mfma_f32_16x16x32_bf16 v[38:41], v[188:191], v[204:207], 0
	v_mfma_f32_16x16x32_bf16 v[30:33], v[180:183], v[224:227], 0
	v_mfma_f32_16x16x32_bf16 v[22:25], v[188:191], v[224:227], 0
	v_mfma_f32_16x16x32_bf16 v[14:17], v[180:183], v[232:235], 0
	v_mfma_f32_16x16x32_bf16 v[6:9], v[188:191], v[232:235], 0
	v_mfma_f32_16x16x32_bf16 v[62:65], v[184:187], v[200:203], v[62:65]
	v_mfma_f32_16x16x32_bf16 v[54:57], v[192:195], v[200:203], v[54:57]
	v_mfma_f32_16x16x32_bf16 v[46:49], v[184:187], v[220:223], v[46:49]
	v_mfma_f32_16x16x32_bf16 v[38:41], v[192:195], v[220:223], v[38:41]
	v_mfma_f32_16x16x32_bf16 v[30:33], v[184:187], v[228:231], v[30:33]
	v_mfma_f32_16x16x32_bf16 v[22:25], v[192:195], v[228:231], v[22:25]
	v_mfma_f32_16x16x32_bf16 v[14:17], v[184:187], v[236:239], v[14:17]
	v_mfma_f32_16x16x32_bf16 v[6:9], v[192:195], v[236:239], v[6:9]
	s_barrier
	s_setprio 0
	s_add_i32 s54, 0, 0x18000
	v_add_u32_e32 v163, s54, v160
	s_add_i32 s55, 0, 0x1c000
	ds_read_b128 v[164:167], v163
	ds_read_b128 v[168:171], v163 offset:1024
	ds_read_b128 v[172:175], v163 offset:2048
	ds_read_b128 v[176:179], v163 offset:3072
	v_add_u32_e32 v163, s55, v160
	ds_read_b128 v[180:183], v163
	ds_read_b128 v[184:187], v163 offset:1024
	ds_read_b128 v[188:191], v163 offset:2048
	ds_read_b128 v[192:195], v163 offset:3072
	s_add_u32 s22, s22, 0x80000
	s_addc_u32 s23, s23, 0
	s_mov_b32 m0, s44
	v_lshl_add_u64 v[246:247], s[22:23], 0, v[134:135]
	ds_read_b128 v[196:199], v162 offset:32768
	ds_read_b128 v[200:203], v162 offset:33792
	ds_read_b128 v[204:207], v162 offset:34816
	ds_read_b128 v[220:223], v162 offset:35840
	ds_read_b128 v[224:227], v162 offset:36864
	ds_read_b128 v[228:231], v162 offset:37888
	ds_read_b128 v[232:235], v162 offset:38912
	ds_read_b128 v[236:239], v162 offset:39936
	global_load_lds_dwordx4 v[246:247], off
	v_lshl_add_u64 v[246:247], s[22:23], 0, v[132:133]
	s_mov_b32 m0, s45
	s_nop 0
	global_load_lds_dwordx4 v[246:247], off
	s_waitcnt vmcnt(8)
	s_waitcnt lgkmcnt(0)
	s_setprio 1
	s_barrier
	v_mfma_f32_16x16x32_bf16 v[122:125], v[164:167], v[196:199], v[122:125]
	v_mfma_f32_16x16x32_bf16 v[114:117], v[172:175], v[196:199], v[114:117]
	v_mfma_f32_16x16x32_bf16 v[106:109], v[164:167], v[204:207], v[106:109]
	v_mfma_f32_16x16x32_bf16 v[98:101], v[172:175], v[204:207], v[98:101]
	v_mfma_f32_16x16x32_bf16 v[90:93], v[164:167], v[224:227], v[90:93]
	v_mfma_f32_16x16x32_bf16 v[82:85], v[172:175], v[224:227], v[82:85]
	v_mfma_f32_16x16x32_bf16 v[74:77], v[164:167], v[232:235], v[74:77]
	v_mfma_f32_16x16x32_bf16 v[66:69], v[172:175], v[232:235], v[66:69]
	v_mfma_f32_16x16x32_bf16 v[122:125], v[168:171], v[200:203], v[122:125]
	v_mfma_f32_16x16x32_bf16 v[114:117], v[176:179], v[200:203], v[114:117]
	v_mfma_f32_16x16x32_bf16 v[106:109], v[168:171], v[220:223], v[106:109]
	v_mfma_f32_16x16x32_bf16 v[98:101], v[176:179], v[220:223], v[98:101]
	v_mfma_f32_16x16x32_bf16 v[90:93], v[168:171], v[228:231], v[90:93]
	v_mfma_f32_16x16x32_bf16 v[82:85], v[176:179], v[228:231], v[82:85]
	v_mfma_f32_16x16x32_bf16 v[74:77], v[168:171], v[236:239], v[74:77]
	v_mfma_f32_16x16x32_bf16 v[66:69], v[176:179], v[236:239], v[66:69]
	s_setprio 0
	s_setprio 1
	v_mfma_f32_16x16x32_bf16 v[126:129], v[180:183], v[196:199], v[126:129]
	v_mfma_f32_16x16x32_bf16 v[118:121], v[188:191], v[196:199], v[118:121]
	v_mfma_f32_16x16x32_bf16 v[110:113], v[180:183], v[204:207], v[110:113]
	v_mfma_f32_16x16x32_bf16 v[102:105], v[188:191], v[204:207], v[102:105]
	v_mfma_f32_16x16x32_bf16 v[94:97], v[180:183], v[224:227], v[94:97]
	v_mfma_f32_16x16x32_bf16 v[86:89], v[188:191], v[224:227], v[86:89]
	v_mfma_f32_16x16x32_bf16 v[78:81], v[180:183], v[232:235], v[78:81]
	v_mfma_f32_16x16x32_bf16 v[70:73], v[188:191], v[232:235], v[70:73]
	v_mfma_f32_16x16x32_bf16 v[126:129], v[184:187], v[200:203], v[126:129]
	v_mfma_f32_16x16x32_bf16 v[118:121], v[192:195], v[200:203], v[118:121]
	v_mfma_f32_16x16x32_bf16 v[110:113], v[184:187], v[220:223], v[110:113]
	v_mfma_f32_16x16x32_bf16 v[102:105], v[192:195], v[220:223], v[102:105]
	v_mfma_f32_16x16x32_bf16 v[94:97], v[184:187], v[228:231], v[94:97]
	v_mfma_f32_16x16x32_bf16 v[86:89], v[192:195], v[228:231], v[86:89]
	v_mfma_f32_16x16x32_bf16 v[78:81], v[184:187], v[236:239], v[78:81]
	v_mfma_f32_16x16x32_bf16 v[70:73], v[192:195], v[236:239], v[70:73]
	s_barrier
	s_setprio 0
	s_add_i32 s22, s54, s41
	v_lshl_add_u64 v[158:159], v[158:159], 0, s[2:3]
	s_mov_b32 m0, s22
	ds_read_b128 v[196:199], v162 offset:49152
	ds_read_b128 v[200:203], v162 offset:50176
	ds_read_b128 v[204:207], v162 offset:51200
	ds_read_b128 v[220:223], v162 offset:52224
	ds_read_b128 v[224:227], v162 offset:53248
	ds_read_b128 v[228:231], v162 offset:54272
	ds_read_b128 v[232:235], v162 offset:55296
	ds_read_b128 v[236:239], v162 offset:56320
	global_load_lds_dwordx4 v[158:159], off
	s_add_i32 m0, s22, 0x2000
	s_add_u32 s20, s20, 0x80080
	v_lshl_add_u64 v[158:159], v[208:209], 0, s[2:3]
	s_addc_u32 s21, s21, 0
	s_add_i32 s22, s55, s41
	global_load_lds_dwordx4 v[158:159], off
	v_lshl_add_u64 v[158:159], s[20:21], 0, v[0:1]
	s_mov_b32 m0, s22
	s_nop 0
	global_load_lds_dwordx4 v[158:159], off
	v_lshl_add_u64 v[158:159], s[20:21], 0, v[130:131]
	s_add_i32 m0, s22, 0x2000
	s_nop 0
	global_load_lds_dwordx4 v[158:159], off
	v_lshl_add_u64 v[158:159], v[216:217], 0, s[2:3]
	s_mov_b32 m0, s46
	s_nop 0
	global_load_lds_dwordx4 v[158:159], off
	v_lshl_add_u64 v[158:159], v[244:245], 0, s[2:3]
	s_mov_b32 m0, s47
	s_nop 0
	global_load_lds_dwordx4 v[158:159], off
	s_nop 0
	s_waitcnt vmcnt(8)
	s_waitcnt lgkmcnt(0)
	s_setprio 1
	s_barrier
	v_mfma_f32_16x16x32_bf16 v[58:61], v[164:167], v[196:199], v[58:61]
	v_mfma_f32_16x16x32_bf16 v[50:53], v[172:175], v[196:199], v[50:53]
	v_mfma_f32_16x16x32_bf16 v[42:45], v[164:167], v[204:207], v[42:45]
	v_mfma_f32_16x16x32_bf16 v[34:37], v[172:175], v[204:207], v[34:37]
	v_mfma_f32_16x16x32_bf16 v[26:29], v[164:167], v[224:227], v[26:29]
	v_mfma_f32_16x16x32_bf16 v[18:21], v[172:175], v[224:227], v[18:21]
	v_mfma_f32_16x16x32_bf16 v[10:13], v[164:167], v[232:235], v[10:13]
	v_mfma_f32_16x16x32_bf16 v[2:5], v[172:175], v[232:235], v[2:5]
	v_mfma_f32_16x16x32_bf16 v[58:61], v[168:171], v[200:203], v[58:61]
	v_mfma_f32_16x16x32_bf16 v[50:53], v[176:179], v[200:203], v[50:53]
	v_mfma_f32_16x16x32_bf16 v[42:45], v[168:171], v[220:223], v[42:45]
	v_mfma_f32_16x16x32_bf16 v[34:37], v[176:179], v[220:223], v[34:37]
	v_mfma_f32_16x16x32_bf16 v[26:29], v[168:171], v[228:231], v[26:29]
	v_mfma_f32_16x16x32_bf16 v[18:21], v[176:179], v[228:231], v[18:21]
	v_mfma_f32_16x16x32_bf16 v[10:13], v[168:171], v[236:239], v[10:13]
	v_mfma_f32_16x16x32_bf16 v[2:5], v[176:179], v[236:239], v[2:5]
	s_setprio 0
	s_setprio 1
	v_mfma_f32_16x16x32_bf16 v[62:65], v[180:183], v[196:199], v[62:65]
	v_mfma_f32_16x16x32_bf16 v[54:57], v[188:191], v[196:199], v[54:57]
	v_mfma_f32_16x16x32_bf16 v[46:49], v[180:183], v[204:207], v[46:49]
	v_mfma_f32_16x16x32_bf16 v[38:41], v[188:191], v[204:207], v[38:41]
	v_mfma_f32_16x16x32_bf16 v[30:33], v[180:183], v[224:227], v[30:33]
	v_mfma_f32_16x16x32_bf16 v[22:25], v[188:191], v[224:227], v[22:25]
	v_mfma_f32_16x16x32_bf16 v[14:17], v[180:183], v[232:235], v[14:17]
	v_mfma_f32_16x16x32_bf16 v[6:9], v[188:191], v[232:235], v[6:9]
	v_mfma_f32_16x16x32_bf16 v[62:65], v[184:187], v[200:203], v[62:65]
	v_mfma_f32_16x16x32_bf16 v[54:57], v[192:195], v[200:203], v[54:57]
	v_mfma_f32_16x16x32_bf16 v[46:49], v[184:187], v[220:223], v[46:49]
	v_mfma_f32_16x16x32_bf16 v[38:41], v[192:195], v[220:223], v[38:41]
	v_mfma_f32_16x16x32_bf16 v[30:33], v[184:187], v[228:231], v[30:33]
	v_mfma_f32_16x16x32_bf16 v[22:25], v[192:195], v[228:231], v[22:25]
	v_mfma_f32_16x16x32_bf16 v[14:17], v[184:187], v[236:239], v[14:17]
	v_mfma_f32_16x16x32_bf16 v[6:9], v[192:195], v[236:239], v[6:9]
	s_barrier
	s_setprio 0
	s_add_i32 s53, s53, 2
	s_add_u32 s18, s18, 0x100
	s_addc_u32 s19, s19, 0
	s_add_u32 s51, s51, 0x100
	s_addc_u32 s52, s52, 0
	s_cmp_gt_u32 s53, 29
	s_cbranch_scc1 .Lpeel_done_4
.LBB0_1565:
	s_add_u32 s20, s18, 0xfff80080
	s_addc_u32 s21, s19, -1
	s_cmp_eq_u32 s53, 28
	s_cselect_b32 s23, s9, s21
	s_cselect_b32 s22, s15, s20
	s_cselect_b32 s21, s7, s52
	s_cselect_b32 s20, s50, s51
	s_add_i32 s54, 0, 0x10000
	s_add_i32 s56, 0, 0x14000
	v_add_u32_e32 v158, 0x10000, v160
	ds_read_b128 v[164:167], v158
	ds_read_b128 v[168:171], v158 offset:1024
	ds_read_b128 v[172:175], v158 offset:2048
	ds_read_b128 v[176:179], v158 offset:3072
	ds_read_b128 v[180:183], v158 offset:16384
	ds_read_b128 v[184:187], v158 offset:17408
	ds_read_b128 v[188:191], v158 offset:18432
	ds_read_b128 v[192:195], v158 offset:19456
	s_add_i32 m0, s17, 0xc000
	ds_read_b128 v[196:199], v162
	ds_read_b128 v[200:203], v162 offset:1024
	ds_read_b128 v[204:207], v162 offset:2048
	ds_read_b128 v[220:223], v162 offset:3072
	ds_read_b128 v[224:227], v162 offset:4096
	ds_read_b128 v[228:231], v162 offset:5120
	ds_read_b128 v[232:235], v162 offset:6144
	ds_read_b128 v[236:239], v162 offset:7168
	global_load_lds_dwordx4 v154, s[18:19]
	s_add_i32 m0, s17, 0xe000
	s_nop 0
	global_load_lds_dwordx4 v156, s[18:19]
	s_waitcnt vmcnt(8)
	s_waitcnt lgkmcnt(0)
	s_setprio 1
	s_barrier
	v_mfma_f32_16x16x32_bf16 v[122:125], v[164:167], v[196:199], v[122:125]
	v_mfma_f32_16x16x32_bf16 v[114:117], v[172:175], v[196:199], v[114:117]
	v_mfma_f32_16x16x32_bf16 v[106:109], v[164:167], v[204:207], v[106:109]
	v_mfma_f32_16x16x32_bf16 v[98:101], v[172:175], v[204:207], v[98:101]
	v_mfma_f32_16x16x32_bf16 v[90:93], v[164:167], v[224:227], v[90:93]
	v_mfma_f32_16x16x32_bf16 v[82:85], v[172:175], v[224:227], v[82:85]
	v_mfma_f32_16x16x32_bf16 v[74:77], v[164:167], v[232:235], v[74:77]
	v_mfma_f32_16x16x32_bf16 v[66:69], v[172:175], v[232:235], v[66:69]
	v_mfma_f32_16x16x32_bf16 v[122:125], v[168:171], v[200:203], v[122:125]
	v_mfma_f32_16x16x32_bf16 v[114:117], v[176:179], v[200:203], v[114:117]
	v_mfma_f32_16x16x32_bf16 v[106:109], v[168:171], v[220:223], v[106:109]
	v_mfma_f32_16x16x32_bf16 v[98:101], v[176:179], v[220:223], v[98:101]
	v_mfma_f32_16x16x32_bf16 v[90:93], v[168:171], v[228:231], v[90:93]
	v_mfma_f32_16x16x32_bf16 v[82:85], v[176:179], v[228:231], v[82:85]
	v_mfma_f32_16x16x32_bf16 v[74:77], v[168:171], v[236:239], v[74:77]
	v_mfma_f32_16x16x32_bf16 v[66:69], v[176:179], v[236:239], v[66:69]
	s_setprio 0
	s_setprio 1
	v_mfma_f32_16x16x32_bf16 v[126:129], v[180:183], v[196:199], v[126:129]
	v_mfma_f32_16x16x32_bf16 v[118:121], v[188:191], v[196:199], v[118:121]
	v_mfma_f32_16x16x32_bf16 v[110:113], v[180:183], v[204:207], v[110:113]
	v_mfma_f32_16x16x32_bf16 v[102:105], v[188:191], v[204:207], v[102:105]
	v_mfma_f32_16x16x32_bf16 v[94:97], v[180:183], v[224:227], v[94:97]
	v_mfma_f32_16x16x32_bf16 v[86:89], v[188:191], v[224:227], v[86:89]
	v_mfma_f32_16x16x32_bf16 v[78:81], v[180:183], v[232:235], v[78:81]
	v_mfma_f32_16x16x32_bf16 v[70:73], v[188:191], v[232:235], v[70:73]
	v_mfma_f32_16x16x32_bf16 v[126:129], v[184:187], v[200:203], v[126:129]
	v_mfma_f32_16x16x32_bf16 v[118:121], v[192:195], v[200:203], v[118:121]
	v_mfma_f32_16x16x32_bf16 v[110:113], v[184:187], v[220:223], v[110:113]
	v_mfma_f32_16x16x32_bf16 v[102:105], v[192:195], v[220:223], v[102:105]
	v_mfma_f32_16x16x32_bf16 v[94:97], v[184:187], v[228:231], v[94:97]
	v_mfma_f32_16x16x32_bf16 v[86:89], v[192:195], v[228:231], v[86:89]
	v_mfma_f32_16x16x32_bf16 v[78:81], v[184:187], v[236:239], v[78:81]
	v_mfma_f32_16x16x32_bf16 v[70:73], v[192:195], v[236:239], v[70:73]
	s_barrier
	s_setprio 0
	s_add_i32 s54, s54, s41
	s_mov_b32 m0, s54
	ds_read_b128 v[196:199], v162 offset:16384
	ds_read_b128 v[200:203], v162 offset:17408
	ds_read_b128 v[204:207], v162 offset:18432
	ds_read_b128 v[220:223], v162 offset:19456
	ds_read_b128 v[224:227], v162 offset:20480
	ds_read_b128 v[228:231], v162 offset:21504
	ds_read_b128 v[232:235], v162 offset:22528
	ds_read_b128 v[236:239], v162 offset:23552
	global_load_lds_dwordx4 v0, s[20:21]
	s_add_i32 m0, s54, 0x2000
	s_add_u32 s54, s20, 0x80000
	s_addc_u32 s55, s21, 0
	s_add_i32 s56, s56, s41
	global_load_lds_dwordx4 v130, s[20:21]
	s_mov_b32 m0, s56
	s_nop 0
	global_load_lds_dwordx4 v0, s[54:55]
	s_add_i32 m0, s56, 0x2000
	s_nop 0
	global_load_lds_dwordx4 v130, s[54:55]
	s_mov_b32 m0, s17
	s_nop 0
	global_load_lds_dwordx4 v134, s[22:23]
	s_mov_b32 m0, s43
	s_nop 0
	global_load_lds_dwordx4 v132, s[22:23]
	s_nop 0
	s_waitcnt vmcnt(8)
	s_waitcnt lgkmcnt(0)
	s_setprio 1
	s_barrier
	v_mfma_f32_16x16x32_bf16 v[58:61], v[164:167], v[196:199], v[58:61]
	v_mfma_f32_16x16x32_bf16 v[50:53], v[172:175], v[196:199], v[50:53]
	v_mfma_f32_16x16x32_bf16 v[42:45], v[164:167], v[204:207], v[42:45]
	v_mfma_f32_16x16x32_bf16 v[34:37], v[172:175], v[204:207], v[34:37]
	v_mfma_f32_16x16x32_bf16 v[26:29], v[164:167], v[224:227], v[26:29]
	v_mfma_f32_16x16x32_bf16 v[18:21], v[172:175], v[224:227], v[18:21]
	v_mfma_f32_16x16x32_bf16 v[10:13], v[164:167], v[232:235], v[10:13]
	v_mfma_f32_16x16x32_bf16 v[2:5], v[172:175], v[232:235], v[2:5]
	v_mfma_f32_16x16x32_bf16 v[58:61], v[168:171], v[200:203], v[58:61]
	v_mfma_f32_16x16x32_bf16 v[50:53], v[176:179], v[200:203], v[50:53]
	v_mfma_f32_16x16x32_bf16 v[42:45], v[168:171], v[220:223], v[42:45]
	v_mfma_f32_16x16x32_bf16 v[34:37], v[176:179], v[220:223], v[34:37]
	v_mfma_f32_16x16x32_bf16 v[26:29], v[168:171], v[228:231], v[26:29]
	v_mfma_f32_16x16x32_bf16 v[18:21], v[176:179], v[228:231], v[18:21]
	v_mfma_f32_16x16x32_bf16 v[10:13], v[168:171], v[236:239], v[10:13]
	v_mfma_f32_16x16x32_bf16 v[2:5], v[176:179], v[236:239], v[2:5]
	s_setprio 0
	s_setprio 1
	v_mfma_f32_16x16x32_bf16 v[62:65], v[180:183], v[196:199], v[62:65]
	v_mfma_f32_16x16x32_bf16 v[54:57], v[188:191], v[196:199], v[54:57]
	v_mfma_f32_16x16x32_bf16 v[46:49], v[180:183], v[204:207], v[46:49]
	v_mfma_f32_16x16x32_bf16 v[38:41], v[188:191], v[204:207], v[38:41]
	v_mfma_f32_16x16x32_bf16 v[30:33], v[180:183], v[224:227], v[30:33]
	v_mfma_f32_16x16x32_bf16 v[22:25], v[188:191], v[224:227], v[22:25]
	v_mfma_f32_16x16x32_bf16 v[14:17], v[180:183], v[232:235], v[14:17]
	v_mfma_f32_16x16x32_bf16 v[6:9], v[188:191], v[232:235], v[6:9]
	v_mfma_f32_16x16x32_bf16 v[62:65], v[184:187], v[200:203], v[62:65]
	v_mfma_f32_16x16x32_bf16 v[54:57], v[192:195], v[200:203], v[54:57]
	v_mfma_f32_16x16x32_bf16 v[46:49], v[184:187], v[220:223], v[46:49]
	v_mfma_f32_16x16x32_bf16 v[38:41], v[192:195], v[220:223], v[38:41]
	v_mfma_f32_16x16x32_bf16 v[30:33], v[184:187], v[228:231], v[30:33]
	v_mfma_f32_16x16x32_bf16 v[22:25], v[192:195], v[228:231], v[22:25]
	v_mfma_f32_16x16x32_bf16 v[14:17], v[184:187], v[236:239], v[14:17]
	v_mfma_f32_16x16x32_bf16 v[6:9], v[192:195], v[236:239], v[6:9]
	s_barrier
	s_setprio 0
	ds_read_b128 v[164:167], v158 offset:32768
	ds_read_b128 v[168:171], v158 offset:33792
	ds_read_b128 v[172:175], v158 offset:34816
	ds_read_b128 v[176:179], v158 offset:35840
	ds_read_b128 v[180:183], v158 offset:49152
	ds_read_b128 v[184:187], v158 offset:50176
	ds_read_b128 v[188:191], v158 offset:51200
	ds_read_b128 v[192:195], v158 offset:52224
	s_add_i32 s54, 0, 0x18000
	s_add_i32 s55, 0, 0x1c000
	s_add_u32 s22, s22, 0x80000
	s_addc_u32 s23, s23, 0
	s_mov_b32 m0, s44
	ds_read_b128 v[196:199], v162 offset:32768
	ds_read_b128 v[200:203], v162 offset:33792
	ds_read_b128 v[204:207], v162 offset:34816
	ds_read_b128 v[220:223], v162 offset:35840
	ds_read_b128 v[224:227], v162 offset:36864
	ds_read_b128 v[228:231], v162 offset:37888
	ds_read_b128 v[232:235], v162 offset:38912
	ds_read_b128 v[236:239], v162 offset:39936
	global_load_lds_dwordx4 v134, s[22:23]
	s_mov_b32 m0, s45
	s_nop 0
	global_load_lds_dwordx4 v132, s[22:23]
	s_waitcnt vmcnt(8)
	s_waitcnt lgkmcnt(0)
	s_setprio 1
	s_barrier
	v_mfma_f32_16x16x32_bf16 v[122:125], v[164:167], v[196:199], v[122:125]
	v_mfma_f32_16x16x32_bf16 v[114:117], v[172:175], v[196:199], v[114:117]
	v_mfma_f32_16x16x32_bf16 v[106:109], v[164:167], v[204:207], v[106:109]
	v_mfma_f32_16x16x32_bf16 v[98:101], v[172:175], v[204:207], v[98:101]
	v_mfma_f32_16x16x32_bf16 v[90:93], v[164:167], v[224:227], v[90:93]
	v_mfma_f32_16x16x32_bf16 v[82:85], v[172:175], v[224:227], v[82:85]
	v_mfma_f32_16x16x32_bf16 v[74:77], v[164:167], v[232:235], v[74:77]
	v_mfma_f32_16x16x32_bf16 v[66:69], v[172:175], v[232:235], v[66:69]
	v_mfma_f32_16x16x32_bf16 v[122:125], v[168:171], v[200:203], v[122:125]
	v_mfma_f32_16x16x32_bf16 v[114:117], v[176:179], v[200:203], v[114:117]
	v_mfma_f32_16x16x32_bf16 v[106:109], v[168:171], v[220:223], v[106:109]
	v_mfma_f32_16x16x32_bf16 v[98:101], v[176:179], v[220:223], v[98:101]
	v_mfma_f32_16x16x32_bf16 v[90:93], v[168:171], v[228:231], v[90:93]
	v_mfma_f32_16x16x32_bf16 v[82:85], v[176:179], v[228:231], v[82:85]
	v_mfma_f32_16x16x32_bf16 v[74:77], v[168:171], v[236:239], v[74:77]
	v_mfma_f32_16x16x32_bf16 v[66:69], v[176:179], v[236:239], v[66:69]
	s_setprio 0
	s_setprio 1
	v_mfma_f32_16x16x32_bf16 v[126:129], v[180:183], v[196:199], v[126:129]
	v_mfma_f32_16x16x32_bf16 v[118:121], v[188:191], v[196:199], v[118:121]
	v_mfma_f32_16x16x32_bf16 v[110:113], v[180:183], v[204:207], v[110:113]
	v_mfma_f32_16x16x32_bf16 v[102:105], v[188:191], v[204:207], v[102:105]
	v_mfma_f32_16x16x32_bf16 v[94:97], v[180:183], v[224:227], v[94:97]
	v_mfma_f32_16x16x32_bf16 v[86:89], v[188:191], v[224:227], v[86:89]
	v_mfma_f32_16x16x32_bf16 v[78:81], v[180:183], v[232:235], v[78:81]
	v_mfma_f32_16x16x32_bf16 v[70:73], v[188:191], v[232:235], v[70:73]
	v_mfma_f32_16x16x32_bf16 v[126:129], v[184:187], v[200:203], v[126:129]
	v_mfma_f32_16x16x32_bf16 v[118:121], v[192:195], v[200:203], v[118:121]
	v_mfma_f32_16x16x32_bf16 v[110:113], v[184:187], v[220:223], v[110:113]
	v_mfma_f32_16x16x32_bf16 v[102:105], v[192:195], v[220:223], v[102:105]
	v_mfma_f32_16x16x32_bf16 v[94:97], v[184:187], v[228:231], v[94:97]
	v_mfma_f32_16x16x32_bf16 v[86:89], v[192:195], v[228:231], v[86:89]
	v_mfma_f32_16x16x32_bf16 v[78:81], v[184:187], v[236:239], v[78:81]
	v_mfma_f32_16x16x32_bf16 v[70:73], v[192:195], v[236:239], v[70:73]
	s_barrier
	s_setprio 0
	s_add_u32 vcc_lo, s22, 0xfff80080
	s_addc_u32 vcc_hi, s23, -1
	s_add_i32 s22, s54, s41
	s_add_i32 s56, s55, s41
	s_add_u32 s54, s20, 0x80
	s_addc_u32 s55, s21, 0
	s_add_u32 s20, s20, 0x80080
	s_addc_u32 s21, s21, 0
	s_mov_b32 m0, s22
	ds_read_b128 v[196:199], v162 offset:49152
	ds_read_b128 v[200:203], v162 offset:50176
	ds_read_b128 v[204:207], v162 offset:51200
	ds_read_b128 v[220:223], v162 offset:52224
	ds_read_b128 v[224:227], v162 offset:53248
	ds_read_b128 v[228:231], v162 offset:54272
	ds_read_b128 v[232:235], v162 offset:55296
	ds_read_b128 v[236:239], v162 offset:56320
	global_load_lds_dwordx4 v0, s[54:55]
	s_add_i32 m0, s22, 0x2000
	s_nop 0
	global_load_lds_dwordx4 v130, s[54:55]
	s_mov_b32 m0, s56
	s_nop 0
	global_load_lds_dwordx4 v0, s[20:21]
	s_add_i32 m0, s56, 0x2000
	s_nop 0
	global_load_lds_dwordx4 v130, s[20:21]
	s_mov_b32 m0, s46
	s_nop 0
	global_load_lds_dwordx4 v134, vcc
	s_mov_b32 m0, s47
	s_nop 0
	global_load_lds_dwordx4 v132, vcc
	s_waitcnt vmcnt(8)
	s_waitcnt lgkmcnt(0)
	s_setprio 1
	s_barrier
	v_mfma_f32_16x16x32_bf16 v[58:61], v[164:167], v[196:199], v[58:61]
	v_mfma_f32_16x16x32_bf16 v[50:53], v[172:175], v[196:199], v[50:53]
	v_mfma_f32_16x16x32_bf16 v[42:45], v[164:167], v[204:207], v[42:45]
	v_mfma_f32_16x16x32_bf16 v[34:37], v[172:175], v[204:207], v[34:37]
	v_mfma_f32_16x16x32_bf16 v[26:29], v[164:167], v[224:227], v[26:29]
	v_mfma_f32_16x16x32_bf16 v[18:21], v[172:175], v[224:227], v[18:21]
	v_mfma_f32_16x16x32_bf16 v[10:13], v[164:167], v[232:235], v[10:13]
	v_mfma_f32_16x16x32_bf16 v[2:5], v[172:175], v[232:235], v[2:5]
	v_mfma_f32_16x16x32_bf16 v[58:61], v[168:171], v[200:203], v[58:61]
	v_mfma_f32_16x16x32_bf16 v[50:53], v[176:179], v[200:203], v[50:53]
	v_mfma_f32_16x16x32_bf16 v[42:45], v[168:171], v[220:223], v[42:45]
	v_mfma_f32_16x16x32_bf16 v[34:37], v[176:179], v[220:223], v[34:37]
	v_mfma_f32_16x16x32_bf16 v[26:29], v[168:171], v[228:231], v[26:29]
	v_mfma_f32_16x16x32_bf16 v[18:21], v[176:179], v[228:231], v[18:21]
	v_mfma_f32_16x16x32_bf16 v[10:13], v[168:171], v[236:239], v[10:13]
	v_mfma_f32_16x16x32_bf16 v[2:5], v[176:179], v[236:239], v[2:5]
	s_setprio 0
	s_setprio 1
	v_mfma_f32_16x16x32_bf16 v[62:65], v[180:183], v[196:199], v[62:65]
	v_mfma_f32_16x16x32_bf16 v[54:57], v[188:191], v[196:199], v[54:57]
	v_mfma_f32_16x16x32_bf16 v[46:49], v[180:183], v[204:207], v[46:49]
	v_mfma_f32_16x16x32_bf16 v[38:41], v[188:191], v[204:207], v[38:41]
	v_mfma_f32_16x16x32_bf16 v[30:33], v[180:183], v[224:227], v[30:33]
	v_mfma_f32_16x16x32_bf16 v[22:25], v[188:191], v[224:227], v[22:25]
	v_mfma_f32_16x16x32_bf16 v[14:17], v[180:183], v[232:235], v[14:17]
	v_mfma_f32_16x16x32_bf16 v[6:9], v[188:191], v[232:235], v[6:9]
	v_mfma_f32_16x16x32_bf16 v[62:65], v[184:187], v[200:203], v[62:65]
	v_mfma_f32_16x16x32_bf16 v[54:57], v[192:195], v[200:203], v[54:57]
	v_mfma_f32_16x16x32_bf16 v[46:49], v[184:187], v[220:223], v[46:49]
	v_mfma_f32_16x16x32_bf16 v[38:41], v[192:195], v[220:223], v[38:41]
	v_mfma_f32_16x16x32_bf16 v[30:33], v[184:187], v[228:231], v[30:33]
	v_mfma_f32_16x16x32_bf16 v[22:25], v[192:195], v[228:231], v[22:25]
	v_mfma_f32_16x16x32_bf16 v[14:17], v[184:187], v[236:239], v[14:17]
	v_mfma_f32_16x16x32_bf16 v[6:9], v[192:195], v[236:239], v[6:9]
	s_barrier
	s_setprio 0
	s_add_i32 s53, s53, 2
	s_add_u32 s18, s18, 0x100
	s_addc_u32 s19, s19, 0
	s_add_u32 s51, s51, 0x100
	s_addc_u32 s52, s52, 0
	s_cmp_gt_u32 s53, 29
	s_cbranch_scc0 .LBB0_1565

.LBB0_1843:
	s_add_u32 s11, s14, 0x100
	s_addc_u32 s36, s15, 0
	s_add_u32 s12, s12, 0xc000
	s_addc_u32 s13, s13, 0
	s_mov_b32 s37, -2
	s_add_u32 s14, s12, 0x4000
	s_addc_u32 s15, s13, 0
	s_cmpk_eq_i32 s37, 0x54
	s_cselect_b32 s18, s6, s14
	s_cselect_b32 s19, s7, s15
	s_cselect_b32 s16, s8, s11
	s_cselect_b32 s17, s9, s36
	s_add_u32 s14, s18, 0x8000
	s_addc_u32 s15, s19, 0
	s_add_i32 s38, 0, 0x10000
	v_add_u32_e32 v0, s38, v246
	s_add_i32 s40, 0, 0x14000
	ds_read_b128 v[130:133], v0
	ds_read_b128 v[134:137], v0 offset:1024
	ds_read_b128 v[138:141], v0 offset:2048
	ds_read_b128 v[142:145], v0 offset:3072
	v_add_u32_e32 v0, s40, v246
	ds_read_b128 v[146:149], v0
	ds_read_b128 v[150:153], v0 offset:1024
	ds_read_b128 v[154:157], v0 offset:2048
	ds_read_b128 v[158:161], v0 offset:3072
	v_lshl_add_u64 v[194:195], s[12:13], 0, v[228:229]
	s_add_i32 m0, s47, 0xc000
	ds_read_b128 v[162:165], v247
	ds_read_b128 v[166:169], v247 offset:1024
	ds_read_b128 v[170:173], v247 offset:2048
	ds_read_b128 v[174:177], v247 offset:3072
	ds_read_b128 v[178:181], v247 offset:4096
	ds_read_b128 v[182:185], v247 offset:5120
	ds_read_b128 v[186:189], v247 offset:6144
	ds_read_b128 v[190:193], v247 offset:7168
	global_load_lds_dwordx4 v[194:195], off
	v_lshl_add_u64 v[194:195], s[12:13], 0, v[230:231]
	s_add_i32 m0, s47, 0xe000
	s_nop 0
	global_load_lds_dwordx4 v[194:195], off
	s_waitcnt vmcnt(8)
	s_waitcnt lgkmcnt(0)
	s_setprio 1
	s_barrier
	v_mfma_f32_16x16x32_bf16 v[126:129], v[130:133], v[162:165], 0
	v_mfma_f32_16x16x32_bf16 v[122:125], v[138:141], v[162:165], 0
	v_mfma_f32_16x16x32_bf16 v[114:117], v[130:133], v[170:173], 0
	v_mfma_f32_16x16x32_bf16 v[106:109], v[138:141], v[170:173], 0
	v_mfma_f32_16x16x32_bf16 v[94:97], v[130:133], v[178:181], 0
	v_mfma_f32_16x16x32_bf16 v[90:93], v[138:141], v[178:181], 0
	v_mfma_f32_16x16x32_bf16 v[86:89], v[130:133], v[186:189], 0
	v_mfma_f32_16x16x32_bf16 v[82:85], v[138:141], v[186:189], 0
	v_mfma_f32_16x16x32_bf16 v[126:129], v[134:137], v[166:169], v[126:129]
	v_mfma_f32_16x16x32_bf16 v[122:125], v[142:145], v[166:169], v[122:125]
	v_mfma_f32_16x16x32_bf16 v[114:117], v[134:137], v[174:177], v[114:117]
	v_mfma_f32_16x16x32_bf16 v[106:109], v[142:145], v[174:177], v[106:109]
	v_mfma_f32_16x16x32_bf16 v[94:97], v[134:137], v[182:185], v[94:97]
	v_mfma_f32_16x16x32_bf16 v[90:93], v[142:145], v[182:185], v[90:93]
	v_mfma_f32_16x16x32_bf16 v[86:89], v[134:137], v[190:193], v[86:89]
	v_mfma_f32_16x16x32_bf16 v[82:85], v[142:145], v[190:193], v[82:85]
	s_setprio 0
	s_setprio 1
	v_mfma_f32_16x16x32_bf16 v[118:121], v[146:149], v[162:165], 0
	v_mfma_f32_16x16x32_bf16 v[110:113], v[154:157], v[162:165], 0
	v_mfma_f32_16x16x32_bf16 v[102:105], v[146:149], v[170:173], 0
	v_mfma_f32_16x16x32_bf16 v[98:101], v[154:157], v[170:173], 0
	v_mfma_f32_16x16x32_bf16 v[78:81], v[146:149], v[178:181], 0
	v_mfma_f32_16x16x32_bf16 v[74:77], v[154:157], v[178:181], 0
	v_mfma_f32_16x16x32_bf16 v[70:73], v[146:149], v[186:189], 0
	v_mfma_f32_16x16x32_bf16 v[66:69], v[154:157], v[186:189], 0
	v_mfma_f32_16x16x32_bf16 v[118:121], v[150:153], v[166:169], v[118:121]
	v_mfma_f32_16x16x32_bf16 v[110:113], v[158:161], v[166:169], v[110:113]
	v_mfma_f32_16x16x32_bf16 v[102:105], v[150:153], v[174:177], v[102:105]
	v_mfma_f32_16x16x32_bf16 v[98:101], v[158:161], v[174:177], v[98:101]
	v_mfma_f32_16x16x32_bf16 v[78:81], v[150:153], v[182:185], v[78:81]
	v_mfma_f32_16x16x32_bf16 v[74:77], v[158:161], v[182:185], v[74:77]
	v_mfma_f32_16x16x32_bf16 v[70:73], v[150:153], v[190:193], v[70:73]
	v_mfma_f32_16x16x32_bf16 v[66:69], v[158:161], v[190:193], v[66:69]
	s_barrier
	s_setprio 0
	s_add_i32 s38, s38, s46
	v_lshl_add_u64 v[194:195], s[16:17], 0, v[222:223]
	s_mov_b32 m0, s38
	ds_read_b128 v[162:165], v247 offset:16384
	ds_read_b128 v[166:169], v247 offset:17408
	ds_read_b128 v[170:173], v247 offset:18432
	ds_read_b128 v[174:177], v247 offset:19456
	ds_read_b128 v[178:181], v247 offset:20480
	ds_read_b128 v[182:185], v247 offset:21504
	ds_read_b128 v[186:189], v247 offset:22528
	ds_read_b128 v[190:193], v247 offset:23552
	global_load_lds_dwordx4 v[194:195], off
	s_add_i32 m0, s38, 0x2000
	s_add_u32 s38, s16, 0x164000
	v_lshl_add_u64 v[196:197], s[16:17], 0, v[226:227]
	s_addc_u32 s39, s17, 0
	s_add_i32 s40, s40, s46
	global_load_lds_dwordx4 v[196:197], off
	v_lshl_add_u64 v[198:199], s[38:39], 0, v[222:223]
	s_mov_b32 m0, s40
	s_nop 0
	global_load_lds_dwordx4 v[198:199], off
	v_lshl_add_u64 v[198:199], s[38:39], 0, v[226:227]
	s_add_i32 m0, s40, 0x2000
	s_nop 0
	global_load_lds_dwordx4 v[198:199], off
	v_lshl_add_u64 v[198:199], s[18:19], 0, v[220:221]
	s_mov_b32 m0, s47
	s_nop 0
	global_load_lds_dwordx4 v[198:199], off
	v_lshl_add_u64 v[198:199], s[18:19], 0, v[224:225]
	s_mov_b32 m0, s74
	s_nop 0
	global_load_lds_dwordx4 v[198:199], off
	s_nop 0
	s_waitcnt vmcnt(8)
	s_waitcnt lgkmcnt(0)
	s_setprio 1
	s_barrier
	v_mfma_f32_16x16x32_bf16 v[62:65], v[130:133], v[162:165], 0
	v_mfma_f32_16x16x32_bf16 v[58:61], v[138:141], v[162:165], 0
	v_mfma_f32_16x16x32_bf16 v[54:57], v[130:133], v[170:173], 0
	v_mfma_f32_16x16x32_bf16 v[50:53], v[138:141], v[170:173], 0
	v_mfma_f32_16x16x32_bf16 v[30:33], v[130:133], v[178:181], 0
	v_mfma_f32_16x16x32_bf16 v[26:29], v[138:141], v[178:181], 0
	v_mfma_f32_16x16x32_bf16 v[22:25], v[130:133], v[186:189], 0
	v_mfma_f32_16x16x32_bf16 v[18:21], v[138:141], v[186:189], 0
	v_mfma_f32_16x16x32_bf16 v[62:65], v[134:137], v[166:169], v[62:65]
	v_mfma_f32_16x16x32_bf16 v[58:61], v[142:145], v[166:169], v[58:61]
	v_mfma_f32_16x16x32_bf16 v[54:57], v[134:137], v[174:177], v[54:57]
	v_mfma_f32_16x16x32_bf16 v[50:53], v[142:145], v[174:177], v[50:53]
	v_mfma_f32_16x16x32_bf16 v[30:33], v[134:137], v[182:185], v[30:33]
	v_mfma_f32_16x16x32_bf16 v[26:29], v[142:145], v[182:185], v[26:29]
	v_mfma_f32_16x16x32_bf16 v[22:25], v[134:137], v[190:193], v[22:25]
	v_mfma_f32_16x16x32_bf16 v[18:21], v[142:145], v[190:193], v[18:21]
	s_setprio 0
	s_setprio 1
	v_mfma_f32_16x16x32_bf16 v[46:49], v[146:149], v[162:165], 0
	v_mfma_f32_16x16x32_bf16 v[42:45], v[154:157], v[162:165], 0
	v_mfma_f32_16x16x32_bf16 v[38:41], v[146:149], v[170:173], 0
	v_mfma_f32_16x16x32_bf16 v[34:37], v[154:157], v[170:173], 0
	v_mfma_f32_16x16x32_bf16 v[14:17], v[146:149], v[178:181], 0
	v_mfma_f32_16x16x32_bf16 v[10:13], v[154:157], v[178:181], 0
	v_mfma_f32_16x16x32_bf16 v[6:9], v[146:149], v[186:189], 0
	v_mfma_f32_16x16x32_bf16 v[2:5], v[154:157], v[186:189], 0
	v_mfma_f32_16x16x32_bf16 v[46:49], v[150:153], v[166:169], v[46:49]
	v_mfma_f32_16x16x32_bf16 v[42:45], v[158:161], v[166:169], v[42:45]
	v_mfma_f32_16x16x32_bf16 v[38:41], v[150:153], v[174:177], v[38:41]
	v_mfma_f32_16x16x32_bf16 v[34:37], v[158:161], v[174:177], v[34:37]
	v_mfma_f32_16x16x32_bf16 v[14:17], v[150:153], v[182:185], v[14:17]
	v_mfma_f32_16x16x32_bf16 v[10:13], v[158:161], v[182:185], v[10:13]
	v_mfma_f32_16x16x32_bf16 v[6:9], v[150:153], v[190:193], v[6:9]
	v_mfma_f32_16x16x32_bf16 v[2:5], v[158:161], v[190:193], v[2:5]
	s_barrier
	s_setprio 0
	s_add_i32 s38, 0, 0x18000
	v_add_u32_e32 v0, s38, v246
	s_add_i32 s39, 0, 0x1c000
	ds_read_b128 v[130:133], v0
	ds_read_b128 v[134:137], v0 offset:1024
	ds_read_b128 v[138:141], v0 offset:2048
	ds_read_b128 v[142:145], v0 offset:3072
	v_add_u32_e32 v0, s39, v246
	ds_read_b128 v[146:149], v0
	ds_read_b128 v[150:153], v0 offset:1024
	ds_read_b128 v[154:157], v0 offset:2048
	ds_read_b128 v[158:161], v0 offset:3072
	s_add_u32 s18, s18, 0x4000
	s_addc_u32 s19, s19, 0
	s_mov_b32 m0, s75
	v_lshl_add_u64 v[198:199], s[18:19], 0, v[220:221]
	ds_read_b128 v[162:165], v247 offset:32768
	ds_read_b128 v[166:169], v247 offset:33792
	ds_read_b128 v[170:173], v247 offset:34816
	ds_read_b128 v[174:177], v247 offset:35840
	ds_read_b128 v[178:181], v247 offset:36864
	ds_read_b128 v[182:185], v247 offset:37888
	ds_read_b128 v[186:189], v247 offset:38912
	ds_read_b128 v[190:193], v247 offset:39936
	global_load_lds_dwordx4 v[198:199], off
	v_lshl_add_u64 v[198:199], s[18:19], 0, v[224:225]
	s_mov_b32 m0, s86
	s_nop 0
	global_load_lds_dwordx4 v[198:199], off
	s_waitcnt vmcnt(8)
	s_waitcnt lgkmcnt(0)
	s_setprio 1
	s_barrier
	v_mfma_f32_16x16x32_bf16 v[126:129], v[130:133], v[162:165], v[126:129]
	v_mfma_f32_16x16x32_bf16 v[122:125], v[138:141], v[162:165], v[122:125]
	v_mfma_f32_16x16x32_bf16 v[114:117], v[130:133], v[170:173], v[114:117]
	v_mfma_f32_16x16x32_bf16 v[106:109], v[138:141], v[170:173], v[106:109]
	v_mfma_f32_16x16x32_bf16 v[94:97], v[130:133], v[178:181], v[94:97]
	v_mfma_f32_16x16x32_bf16 v[90:93], v[138:141], v[178:181], v[90:93]
	v_mfma_f32_16x16x32_bf16 v[86:89], v[130:133], v[186:189], v[86:89]
	v_mfma_f32_16x16x32_bf16 v[82:85], v[138:141], v[186:189], v[82:85]
	v_mfma_f32_16x16x32_bf16 v[126:129], v[134:137], v[166:169], v[126:129]
	v_mfma_f32_16x16x32_bf16 v[122:125], v[142:145], v[166:169], v[122:125]
	v_mfma_f32_16x16x32_bf16 v[114:117], v[134:137], v[174:177], v[114:117]
	v_mfma_f32_16x16x32_bf16 v[106:109], v[142:145], v[174:177], v[106:109]
	v_mfma_f32_16x16x32_bf16 v[94:97], v[134:137], v[182:185], v[94:97]
	v_mfma_f32_16x16x32_bf16 v[90:93], v[142:145], v[182:185], v[90:93]
	v_mfma_f32_16x16x32_bf16 v[86:89], v[134:137], v[190:193], v[86:89]
	v_mfma_f32_16x16x32_bf16 v[82:85], v[142:145], v[190:193], v[82:85]
	s_setprio 0
	s_setprio 1
	v_mfma_f32_16x16x32_bf16 v[118:121], v[146:149], v[162:165], v[118:121]
	v_mfma_f32_16x16x32_bf16 v[110:113], v[154:157], v[162:165], v[110:113]
	v_mfma_f32_16x16x32_bf16 v[102:105], v[146:149], v[170:173], v[102:105]
	v_mfma_f32_16x16x32_bf16 v[98:101], v[154:157], v[170:173], v[98:101]
	v_mfma_f32_16x16x32_bf16 v[78:81], v[146:149], v[178:181], v[78:81]
	v_mfma_f32_16x16x32_bf16 v[74:77], v[154:157], v[178:181], v[74:77]
	v_mfma_f32_16x16x32_bf16 v[70:73], v[146:149], v[186:189], v[70:73]
	v_mfma_f32_16x16x32_bf16 v[66:69], v[154:157], v[186:189], v[66:69]
	v_mfma_f32_16x16x32_bf16 v[118:121], v[150:153], v[166:169], v[118:121]
	v_mfma_f32_16x16x32_bf16 v[110:113], v[158:161], v[166:169], v[110:113]
	v_mfma_f32_16x16x32_bf16 v[102:105], v[150:153], v[174:177], v[102:105]
	v_mfma_f32_16x16x32_bf16 v[98:101], v[158:161], v[174:177], v[98:101]
	v_mfma_f32_16x16x32_bf16 v[78:81], v[150:153], v[182:185], v[78:81]
	v_mfma_f32_16x16x32_bf16 v[74:77], v[158:161], v[182:185], v[74:77]
	v_mfma_f32_16x16x32_bf16 v[70:73], v[150:153], v[190:193], v[70:73]
	v_mfma_f32_16x16x32_bf16 v[66:69], v[158:161], v[190:193], v[66:69]
	s_barrier
	s_setprio 0
	s_add_i32 s18, s38, s46
	v_lshl_add_u64 v[194:195], v[194:195], 0, s[2:3]
	s_mov_b32 m0, s18
	ds_read_b128 v[162:165], v247 offset:49152
	ds_read_b128 v[166:169], v247 offset:50176
	ds_read_b128 v[170:173], v247 offset:51200
	ds_read_b128 v[174:177], v247 offset:52224
	ds_read_b128 v[178:181], v247 offset:53248
	ds_read_b128 v[182:185], v247 offset:54272
	ds_read_b128 v[186:189], v247 offset:55296
	ds_read_b128 v[190:193], v247 offset:56320
	global_load_lds_dwordx4 v[194:195], off
	s_add_i32 m0, s18, 0x2000
	s_add_u32 s16, s16, 0x164080
	v_lshl_add_u64 v[194:195], v[196:197], 0, s[2:3]
	s_addc_u32 s17, s17, 0
	s_add_i32 s18, s39, s46
	global_load_lds_dwordx4 v[194:195], off
	v_lshl_add_u64 v[194:195], s[16:17], 0, v[222:223]
	s_mov_b32 m0, s18
	s_nop 0
	global_load_lds_dwordx4 v[194:195], off
	v_lshl_add_u64 v[194:195], s[16:17], 0, v[226:227]
	s_add_i32 m0, s18, 0x2000
	s_nop 0
	global_load_lds_dwordx4 v[194:195], off
	v_lshl_add_u64 v[194:195], s[14:15], 0, v[220:221]
	s_mov_b32 m0, s50
	s_nop 0
	global_load_lds_dwordx4 v[194:195], off
	v_lshl_add_u64 v[194:195], s[14:15], 0, v[224:225]
	s_mov_b32 m0, s51
	s_nop 0
	global_load_lds_dwordx4 v[194:195], off
	s_nop 0
	s_waitcnt vmcnt(8)
	s_waitcnt lgkmcnt(0)
	s_setprio 1
	s_barrier
	v_mfma_f32_16x16x32_bf16 v[62:65], v[130:133], v[162:165], v[62:65]
	v_mfma_f32_16x16x32_bf16 v[58:61], v[138:141], v[162:165], v[58:61]
	v_mfma_f32_16x16x32_bf16 v[54:57], v[130:133], v[170:173], v[54:57]
	v_mfma_f32_16x16x32_bf16 v[50:53], v[138:141], v[170:173], v[50:53]
	v_mfma_f32_16x16x32_bf16 v[30:33], v[130:133], v[178:181], v[30:33]
	v_mfma_f32_16x16x32_bf16 v[26:29], v[138:141], v[178:181], v[26:29]
	v_mfma_f32_16x16x32_bf16 v[22:25], v[130:133], v[186:189], v[22:25]
	v_mfma_f32_16x16x32_bf16 v[18:21], v[138:141], v[186:189], v[18:21]
	v_mfma_f32_16x16x32_bf16 v[62:65], v[134:137], v[166:169], v[62:65]
	v_mfma_f32_16x16x32_bf16 v[58:61], v[142:145], v[166:169], v[58:61]
	v_mfma_f32_16x16x32_bf16 v[54:57], v[134:137], v[174:177], v[54:57]
	v_mfma_f32_16x16x32_bf16 v[50:53], v[142:145], v[174:177], v[50:53]
	v_mfma_f32_16x16x32_bf16 v[30:33], v[134:137], v[182:185], v[30:33]
	v_mfma_f32_16x16x32_bf16 v[26:29], v[142:145], v[182:185], v[26:29]
	v_mfma_f32_16x16x32_bf16 v[22:25], v[134:137], v[190:193], v[22:25]
	v_mfma_f32_16x16x32_bf16 v[18:21], v[142:145], v[190:193], v[18:21]
	s_setprio 0
	s_setprio 1
	v_mfma_f32_16x16x32_bf16 v[46:49], v[146:149], v[162:165], v[46:49]
	v_mfma_f32_16x16x32_bf16 v[42:45], v[154:157], v[162:165], v[42:45]
	v_mfma_f32_16x16x32_bf16 v[38:41], v[146:149], v[170:173], v[38:41]
	v_mfma_f32_16x16x32_bf16 v[34:37], v[154:157], v[170:173], v[34:37]
	v_mfma_f32_16x16x32_bf16 v[14:17], v[146:149], v[178:181], v[14:17]
	v_mfma_f32_16x16x32_bf16 v[10:13], v[154:157], v[178:181], v[10:13]
	v_mfma_f32_16x16x32_bf16 v[6:9], v[146:149], v[186:189], v[6:9]
	v_mfma_f32_16x16x32_bf16 v[2:5], v[154:157], v[186:189], v[2:5]
	v_mfma_f32_16x16x32_bf16 v[46:49], v[150:153], v[166:169], v[46:49]
	v_mfma_f32_16x16x32_bf16 v[42:45], v[158:161], v[166:169], v[42:45]
	v_mfma_f32_16x16x32_bf16 v[38:41], v[150:153], v[174:177], v[38:41]
	v_mfma_f32_16x16x32_bf16 v[34:37], v[158:161], v[174:177], v[34:37]
	v_mfma_f32_16x16x32_bf16 v[14:17], v[150:153], v[182:185], v[14:17]
	v_mfma_f32_16x16x32_bf16 v[10:13], v[158:161], v[182:185], v[10:13]
	v_mfma_f32_16x16x32_bf16 v[6:9], v[150:153], v[190:193], v[6:9]
	v_mfma_f32_16x16x32_bf16 v[2:5], v[158:161], v[190:193], v[2:5]
	s_barrier
	s_setprio 0
	s_add_i32 s37, s37, 2
	s_add_u32 s11, s11, 0x100
	s_addc_u32 s36, s36, 0
	s_add_u32 s12, s12, 0x10000
	s_addc_u32 s13, s13, 0
	s_cmpk_gt_u32 s37, 0x55
	s_cbranch_scc1 .Lpeel_done_5
.LBB0_1844:
	s_add_u32 s14, s12, 0x4000
	s_addc_u32 s15, s13, 0
	s_cmpk_eq_i32 s37, 0x54
	s_cselect_b32 s18, s6, s14
	s_cselect_b32 s19, s7, s15
	s_cselect_b32 s16, s8, s11
	s_cselect_b32 s17, s9, s36
	s_add_u32 s14, s18, 0x8000
	s_addc_u32 s15, s19, 0
	s_add_i32 s38, 0, 0x10000
	v_add_u32_e32 v0, s38, v246
	s_add_i32 s40, 0, 0x14000
	ds_read_b128 v[130:133], v0
	ds_read_b128 v[134:137], v0 offset:1024
	ds_read_b128 v[138:141], v0 offset:2048
	ds_read_b128 v[142:145], v0 offset:3072
	v_add_u32_e32 v0, s40, v246
	ds_read_b128 v[146:149], v0
	ds_read_b128 v[150:153], v0 offset:1024
	ds_read_b128 v[154:157], v0 offset:2048
	ds_read_b128 v[158:161], v0 offset:3072
	v_lshl_add_u64 v[194:195], s[12:13], 0, v[228:229]
	s_add_i32 m0, s47, 0xc000
	ds_read_b128 v[162:165], v247
	ds_read_b128 v[166:169], v247 offset:1024
	ds_read_b128 v[170:173], v247 offset:2048
	ds_read_b128 v[174:177], v247 offset:3072
	ds_read_b128 v[178:181], v247 offset:4096
	ds_read_b128 v[182:185], v247 offset:5120
	ds_read_b128 v[186:189], v247 offset:6144
	ds_read_b128 v[190:193], v247 offset:7168
	global_load_lds_dwordx4 v[194:195], off
	v_lshl_add_u64 v[194:195], s[12:13], 0, v[230:231]
	s_add_i32 m0, s47, 0xe000
	s_nop 0
	global_load_lds_dwordx4 v[194:195], off
	s_nop 0
	s_waitcnt vmcnt(8)
	s_waitcnt lgkmcnt(0)
	s_setprio 1
	s_barrier
	v_mfma_f32_16x16x32_bf16 v[126:129], v[130:133], v[162:165], v[126:129]
	v_mfma_f32_16x16x32_bf16 v[122:125], v[138:141], v[162:165], v[122:125]
	v_mfma_f32_16x16x32_bf16 v[114:117], v[130:133], v[170:173], v[114:117]
	v_mfma_f32_16x16x32_bf16 v[106:109], v[138:141], v[170:173], v[106:109]
	v_mfma_f32_16x16x32_bf16 v[94:97], v[130:133], v[178:181], v[94:97]
	v_mfma_f32_16x16x32_bf16 v[90:93], v[138:141], v[178:181], v[90:93]
	v_mfma_f32_16x16x32_bf16 v[86:89], v[130:133], v[186:189], v[86:89]
	v_mfma_f32_16x16x32_bf16 v[82:85], v[138:141], v[186:189], v[82:85]
	v_mfma_f32_16x16x32_bf16 v[126:129], v[134:137], v[166:169], v[126:129]
	v_mfma_f32_16x16x32_bf16 v[122:125], v[142:145], v[166:169], v[122:125]
	v_mfma_f32_16x16x32_bf16 v[114:117], v[134:137], v[174:177], v[114:117]
	v_mfma_f32_16x16x32_bf16 v[106:109], v[142:145], v[174:177], v[106:109]
	v_mfma_f32_16x16x32_bf16 v[94:97], v[134:137], v[182:185], v[94:97]
	v_mfma_f32_16x16x32_bf16 v[90:93], v[142:145], v[182:185], v[90:93]
	v_mfma_f32_16x16x32_bf16 v[86:89], v[134:137], v[190:193], v[86:89]
	v_mfma_f32_16x16x32_bf16 v[82:85], v[142:145], v[190:193], v[82:85]
	s_setprio 0
	s_setprio 1
	v_mfma_f32_16x16x32_bf16 v[118:121], v[146:149], v[162:165], v[118:121]
	v_mfma_f32_16x16x32_bf16 v[110:113], v[154:157], v[162:165], v[110:113]
	v_mfma_f32_16x16x32_bf16 v[102:105], v[146:149], v[170:173], v[102:105]
	v_mfma_f32_16x16x32_bf16 v[98:101], v[154:157], v[170:173], v[98:101]
	v_mfma_f32_16x16x32_bf16 v[78:81], v[146:149], v[178:181], v[78:81]
	v_mfma_f32_16x16x32_bf16 v[74:77], v[154:157], v[178:181], v[74:77]
	v_mfma_f32_16x16x32_bf16 v[70:73], v[146:149], v[186:189], v[70:73]
	v_mfma_f32_16x16x32_bf16 v[66:69], v[154:157], v[186:189], v[66:69]
	v_mfma_f32_16x16x32_bf16 v[118:121], v[150:153], v[166:169], v[118:121]
	v_mfma_f32_16x16x32_bf16 v[110:113], v[158:161], v[166:169], v[110:113]
	v_mfma_f32_16x16x32_bf16 v[102:105], v[150:153], v[174:177], v[102:105]
	v_mfma_f32_16x16x32_bf16 v[98:101], v[158:161], v[174:177], v[98:101]
	v_mfma_f32_16x16x32_bf16 v[78:81], v[150:153], v[182:185], v[78:81]
	v_mfma_f32_16x16x32_bf16 v[74:77], v[158:161], v[182:185], v[74:77]
	v_mfma_f32_16x16x32_bf16 v[70:73], v[150:153], v[190:193], v[70:73]
	v_mfma_f32_16x16x32_bf16 v[66:69], v[158:161], v[190:193], v[66:69]
	s_barrier
	s_setprio 0
	s_add_i32 s38, s38, s46
	v_lshl_add_u64 v[194:195], s[16:17], 0, v[222:223]
	s_mov_b32 m0, s38
	ds_read_b128 v[162:165], v247 offset:16384
	ds_read_b128 v[166:169], v247 offset:17408
	ds_read_b128 v[170:173], v247 offset:18432
	ds_read_b128 v[174:177], v247 offset:19456
	ds_read_b128 v[178:181], v247 offset:20480
	ds_read_b128 v[182:185], v247 offset:21504
	ds_read_b128 v[186:189], v247 offset:22528
	ds_read_b128 v[190:193], v247 offset:23552
	global_load_lds_dwordx4 v[194:195], off
	s_add_i32 m0, s38, 0x2000
	s_add_u32 s38, s16, 0x164000
	v_lshl_add_u64 v[196:197], s[16:17], 0, v[226:227]
	s_addc_u32 s39, s17, 0
	s_add_i32 s40, s40, s46
	global_load_lds_dwordx4 v[196:197], off
	v_lshl_add_u64 v[198:199], s[38:39], 0, v[222:223]
	s_mov_b32 m0, s40
	s_nop 0
	global_load_lds_dwordx4 v[198:199], off
	v_lshl_add_u64 v[198:199], s[38:39], 0, v[226:227]
	s_add_i32 m0, s40, 0x2000
	s_nop 0
	global_load_lds_dwordx4 v[198:199], off
	v_lshl_add_u64 v[198:199], s[18:19], 0, v[220:221]
	s_mov_b32 m0, s47
	s_nop 0
	global_load_lds_dwordx4 v[198:199], off
	v_lshl_add_u64 v[198:199], s[18:19], 0, v[224:225]
	s_mov_b32 m0, s74
	s_nop 0
	global_load_lds_dwordx4 v[198:199], off
	s_nop 0
	s_waitcnt vmcnt(8)
	s_waitcnt lgkmcnt(0)
	s_setprio 1
	s_barrier
	v_mfma_f32_16x16x32_bf16 v[62:65], v[130:133], v[162:165], v[62:65]
	v_mfma_f32_16x16x32_bf16 v[58:61], v[138:141], v[162:165], v[58:61]
	v_mfma_f32_16x16x32_bf16 v[54:57], v[130:133], v[170:173], v[54:57]
	v_mfma_f32_16x16x32_bf16 v[50:53], v[138:141], v[170:173], v[50:53]
	v_mfma_f32_16x16x32_bf16 v[30:33], v[130:133], v[178:181], v[30:33]
	v_mfma_f32_16x16x32_bf16 v[26:29], v[138:141], v[178:181], v[26:29]
	v_mfma_f32_16x16x32_bf16 v[22:25], v[130:133], v[186:189], v[22:25]
	v_mfma_f32_16x16x32_bf16 v[18:21], v[138:141], v[186:189], v[18:21]
	v_mfma_f32_16x16x32_bf16 v[62:65], v[134:137], v[166:169], v[62:65]
	v_mfma_f32_16x16x32_bf16 v[58:61], v[142:145], v[166:169], v[58:61]
	v_mfma_f32_16x16x32_bf16 v[54:57], v[134:137], v[174:177], v[54:57]
	v_mfma_f32_16x16x32_bf16 v[50:53], v[142:145], v[174:177], v[50:53]
	v_mfma_f32_16x16x32_bf16 v[30:33], v[134:137], v[182:185], v[30:33]
	v_mfma_f32_16x16x32_bf16 v[26:29], v[142:145], v[182:185], v[26:29]
	v_mfma_f32_16x16x32_bf16 v[22:25], v[134:137], v[190:193], v[22:25]
	v_mfma_f32_16x16x32_bf16 v[18:21], v[142:145], v[190:193], v[18:21]
	s_setprio 0
	s_setprio 1
	v_mfma_f32_16x16x32_bf16 v[46:49], v[146:149], v[162:165], v[46:49]
	v_mfma_f32_16x16x32_bf16 v[42:45], v[154:157], v[162:165], v[42:45]
	v_mfma_f32_16x16x32_bf16 v[38:41], v[146:149], v[170:173], v[38:41]
	v_mfma_f32_16x16x32_bf16 v[34:37], v[154:157], v[170:173], v[34:37]
	v_mfma_f32_16x16x32_bf16 v[14:17], v[146:149], v[178:181], v[14:17]
	v_mfma_f32_16x16x32_bf16 v[10:13], v[154:157], v[178:181], v[10:13]
	v_mfma_f32_16x16x32_bf16 v[6:9], v[146:149], v[186:189], v[6:9]
	v_mfma_f32_16x16x32_bf16 v[2:5], v[154:157], v[186:189], v[2:5]
	v_mfma_f32_16x16x32_bf16 v[46:49], v[150:153], v[166:169], v[46:49]
	v_mfma_f32_16x16x32_bf16 v[42:45], v[158:161], v[166:169], v[42:45]
	v_mfma_f32_16x16x32_bf16 v[38:41], v[150:153], v[174:177], v[38:41]
	v_mfma_f32_16x16x32_bf16 v[34:37], v[158:161], v[174:177], v[34:37]
	v_mfma_f32_16x16x32_bf16 v[14:17], v[150:153], v[182:185], v[14:17]
	v_mfma_f32_16x16x32_bf16 v[10:13], v[158:161], v[182:185], v[10:13]
	v_mfma_f32_16x16x32_bf16 v[6:9], v[150:153], v[190:193], v[6:9]
	v_mfma_f32_16x16x32_bf16 v[2:5], v[158:161], v[190:193], v[2:5]
	s_barrier
	s_setprio 0
	s_add_i32 s38, 0, 0x18000
	v_add_u32_e32 v0, s38, v246
	s_add_i32 s39, 0, 0x1c000
	ds_read_b128 v[130:133], v0
	ds_read_b128 v[134:137], v0 offset:1024
	ds_read_b128 v[138:141], v0 offset:2048
	ds_read_b128 v[142:145], v0 offset:3072
	v_add_u32_e32 v0, s39, v246
	ds_read_b128 v[146:149], v0
	ds_read_b128 v[150:153], v0 offset:1024
	ds_read_b128 v[154:157], v0 offset:2048
	ds_read_b128 v[158:161], v0 offset:3072
	s_add_u32 s18, s18, 0x4000
	s_addc_u32 s19, s19, 0
	s_mov_b32 m0, s75
	v_lshl_add_u64 v[198:199], s[18:19], 0, v[220:221]
	ds_read_b128 v[162:165], v247 offset:32768
	ds_read_b128 v[166:169], v247 offset:33792
	ds_read_b128 v[170:173], v247 offset:34816
	ds_read_b128 v[174:177], v247 offset:35840
	ds_read_b128 v[178:181], v247 offset:36864
	ds_read_b128 v[182:185], v247 offset:37888
	ds_read_b128 v[186:189], v247 offset:38912
	ds_read_b128 v[190:193], v247 offset:39936
	global_load_lds_dwordx4 v[198:199], off
	v_lshl_add_u64 v[198:199], s[18:19], 0, v[224:225]
	s_mov_b32 m0, s86
	s_nop 0
	global_load_lds_dwordx4 v[198:199], off
	s_waitcnt vmcnt(8)
	s_waitcnt lgkmcnt(0)
	s_setprio 1
	s_barrier
	v_mfma_f32_16x16x32_bf16 v[126:129], v[130:133], v[162:165], v[126:129]
	v_mfma_f32_16x16x32_bf16 v[122:125], v[138:141], v[162:165], v[122:125]
	v_mfma_f32_16x16x32_bf16 v[114:117], v[130:133], v[170:173], v[114:117]
	v_mfma_f32_16x16x32_bf16 v[106:109], v[138:141], v[170:173], v[106:109]
	v_mfma_f32_16x16x32_bf16 v[94:97], v[130:133], v[178:181], v[94:97]
	v_mfma_f32_16x16x32_bf16 v[90:93], v[138:141], v[178:181], v[90:93]
	v_mfma_f32_16x16x32_bf16 v[86:89], v[130:133], v[186:189], v[86:89]
	v_mfma_f32_16x16x32_bf16 v[82:85], v[138:141], v[186:189], v[82:85]
	v_mfma_f32_16x16x32_bf16 v[126:129], v[134:137], v[166:169], v[126:129]
	v_mfma_f32_16x16x32_bf16 v[122:125], v[142:145], v[166:169], v[122:125]
	v_mfma_f32_16x16x32_bf16 v[114:117], v[134:137], v[174:177], v[114:117]
	v_mfma_f32_16x16x32_bf16 v[106:109], v[142:145], v[174:177], v[106:109]
	v_mfma_f32_16x16x32_bf16 v[94:97], v[134:137], v[182:185], v[94:97]
	v_mfma_f32_16x16x32_bf16 v[90:93], v[142:145], v[182:185], v[90:93]
	v_mfma_f32_16x16x32_bf16 v[86:89], v[134:137], v[190:193], v[86:89]
	v_mfma_f32_16x16x32_bf16 v[82:85], v[142:145], v[190:193], v[82:85]
	s_setprio 0
	s_setprio 1
	v_mfma_f32_16x16x32_bf16 v[118:121], v[146:149], v[162:165], v[118:121]
	v_mfma_f32_16x16x32_bf16 v[110:113], v[154:157], v[162:165], v[110:113]
	v_mfma_f32_16x16x32_bf16 v[102:105], v[146:149], v[170:173], v[102:105]
	v_mfma_f32_16x16x32_bf16 v[98:101], v[154:157], v[170:173], v[98:101]
	v_mfma_f32_16x16x32_bf16 v[78:81], v[146:149], v[178:181], v[78:81]
	v_mfma_f32_16x16x32_bf16 v[74:77], v[154:157], v[178:181], v[74:77]
	v_mfma_f32_16x16x32_bf16 v[70:73], v[146:149], v[186:189], v[70:73]
	v_mfma_f32_16x16x32_bf16 v[66:69], v[154:157], v[186:189], v[66:69]
	v_mfma_f32_16x16x32_bf16 v[118:121], v[150:153], v[166:169], v[118:121]
	v_mfma_f32_16x16x32_bf16 v[110:113], v[158:161], v[166:169], v[110:113]
	v_mfma_f32_16x16x32_bf16 v[102:105], v[150:153], v[174:177], v[102:105]
	v_mfma_f32_16x16x32_bf16 v[98:101], v[158:161], v[174:177], v[98:101]
	v_mfma_f32_16x16x32_bf16 v[78:81], v[150:153], v[182:185], v[78:81]
	v_mfma_f32_16x16x32_bf16 v[74:77], v[158:161], v[182:185], v[74:77]
	v_mfma_f32_16x16x32_bf16 v[70:73], v[150:153], v[190:193], v[70:73]
	v_mfma_f32_16x16x32_bf16 v[66:69], v[158:161], v[190:193], v[66:69]
	s_barrier
	s_setprio 0
	s_add_i32 s18, s38, s46
	v_lshl_add_u64 v[194:195], v[194:195], 0, s[2:3]
	s_mov_b32 m0, s18
	ds_read_b128 v[162:165], v247 offset:49152
	ds_read_b128 v[166:169], v247 offset:50176
	ds_read_b128 v[170:173], v247 offset:51200
	ds_read_b128 v[174:177], v247 offset:52224
	ds_read_b128 v[178:181], v247 offset:53248
	ds_read_b128 v[182:185], v247 offset:54272
	ds_read_b128 v[186:189], v247 offset:55296
	ds_read_b128 v[190:193], v247 offset:56320
	global_load_lds_dwordx4 v[194:195], off
	s_add_i32 m0, s18, 0x2000
	s_add_u32 s16, s16, 0x164080
	v_lshl_add_u64 v[194:195], v[196:197], 0, s[2:3]
	s_addc_u32 s17, s17, 0
	s_add_i32 s18, s39, s46
	global_load_lds_dwordx4 v[194:195], off
	v_lshl_add_u64 v[194:195], s[16:17], 0, v[222:223]
	s_mov_b32 m0, s18
	s_nop 0
	global_load_lds_dwordx4 v[194:195], off
	v_lshl_add_u64 v[194:195], s[16:17], 0, v[226:227]
	s_add_i32 m0, s18, 0x2000
	s_nop 0
	global_load_lds_dwordx4 v[194:195], off
	v_lshl_add_u64 v[194:195], s[14:15], 0, v[220:221]
	s_mov_b32 m0, s50
	s_nop 0
	global_load_lds_dwordx4 v[194:195], off
	v_lshl_add_u64 v[194:195], s[14:15], 0, v[224:225]
	s_mov_b32 m0, s51
	s_nop 0
	global_load_lds_dwordx4 v[194:195], off
	s_nop 0
	s_waitcnt vmcnt(8)
	s_waitcnt lgkmcnt(0)
	s_setprio 1
	s_barrier
	v_mfma_f32_16x16x32_bf16 v[62:65], v[130:133], v[162:165], v[62:65]
	v_mfma_f32_16x16x32_bf16 v[58:61], v[138:141], v[162:165], v[58:61]
	v_mfma_f32_16x16x32_bf16 v[54:57], v[130:133], v[170:173], v[54:57]
	v_mfma_f32_16x16x32_bf16 v[50:53], v[138:141], v[170:173], v[50:53]
	v_mfma_f32_16x16x32_bf16 v[30:33], v[130:133], v[178:181], v[30:33]
	v_mfma_f32_16x16x32_bf16 v[26:29], v[138:141], v[178:181], v[26:29]
	v_mfma_f32_16x16x32_bf16 v[22:25], v[130:133], v[186:189], v[22:25]
	v_mfma_f32_16x16x32_bf16 v[18:21], v[138:141], v[186:189], v[18:21]
	v_mfma_f32_16x16x32_bf16 v[62:65], v[134:137], v[166:169], v[62:65]
	v_mfma_f32_16x16x32_bf16 v[58:61], v[142:145], v[166:169], v[58:61]
	v_mfma_f32_16x16x32_bf16 v[54:57], v[134:137], v[174:177], v[54:57]
	v_mfma_f32_16x16x32_bf16 v[50:53], v[142:145], v[174:177], v[50:53]
	v_mfma_f32_16x16x32_bf16 v[30:33], v[134:137], v[182:185], v[30:33]
	v_mfma_f32_16x16x32_bf16 v[26:29], v[142:145], v[182:185], v[26:29]
	v_mfma_f32_16x16x32_bf16 v[22:25], v[134:137], v[190:193], v[22:25]
	v_mfma_f32_16x16x32_bf16 v[18:21], v[142:145], v[190:193], v[18:21]
	s_setprio 0
	s_setprio 1
	v_mfma_f32_16x16x32_bf16 v[46:49], v[146:149], v[162:165], v[46:49]
	v_mfma_f32_16x16x32_bf16 v[42:45], v[154:157], v[162:165], v[42:45]
	v_mfma_f32_16x16x32_bf16 v[38:41], v[146:149], v[170:173], v[38:41]
	v_mfma_f32_16x16x32_bf16 v[34:37], v[154:157], v[170:173], v[34:37]
	v_mfma_f32_16x16x32_bf16 v[14:17], v[146:149], v[178:181], v[14:17]
	v_mfma_f32_16x16x32_bf16 v[10:13], v[154:157], v[178:181], v[10:13]
	v_mfma_f32_16x16x32_bf16 v[6:9], v[146:149], v[186:189], v[6:9]
	v_mfma_f32_16x16x32_bf16 v[2:5], v[154:157], v[186:189], v[2:5]
	v_mfma_f32_16x16x32_bf16 v[46:49], v[150:153], v[166:169], v[46:49]
	v_mfma_f32_16x16x32_bf16 v[42:45], v[158:161], v[166:169], v[42:45]
	v_mfma_f32_16x16x32_bf16 v[38:41], v[150:153], v[174:177], v[38:41]
	v_mfma_f32_16x16x32_bf16 v[34:37], v[158:161], v[174:177], v[34:37]
	v_mfma_f32_16x16x32_bf16 v[14:17], v[150:153], v[182:185], v[14:17]
	v_mfma_f32_16x16x32_bf16 v[10:13], v[158:161], v[182:185], v[10:13]
	v_mfma_f32_16x16x32_bf16 v[6:9], v[150:153], v[190:193], v[6:9]
	v_mfma_f32_16x16x32_bf16 v[2:5], v[158:161], v[190:193], v[2:5]
	s_barrier
	s_setprio 0
	s_add_i32 s37, s37, 2
	s_add_u32 s11, s11, 0x100
	s_addc_u32 s36, s36, 0
	s_add_u32 s12, s12, 0x10000
	s_addc_u32 s13, s13, 0
	s_cmpk_gt_u32 s37, 0x55
	s_cbranch_scc0 .LBB0_1844

.LBB0_2016:
	s_add_u32 s36, s12, 0x100
	s_addc_u32 s37, s13, 0
	s_add_u32 s12, s14, 0xc000
	s_addc_u32 s13, s15, 0
	s_mov_b32 s50, -2
	s_add_u32 s14, s12, 0x4000
	s_addc_u32 s15, s13, 0
	s_cmp_eq_u32 s50, 18
	s_cselect_b32 s18, s8, s14
	s_cselect_b32 s19, s9, s15
	s_cselect_b32 s16, s10, s36
	s_cselect_b32 s17, s11, s37
	s_add_u32 s14, s18, 0x8000
	s_addc_u32 s15, s19, 0
	s_add_i32 s51, 0, 0x10000
	s_add_i32 s54, 0, 0x14000
	v_add_u32_e32 v156, s51, v140
	v_add_u32_e32 v172, s54, v140
	ds_read_b128 v[144:147], v156
	ds_read_b128 v[148:151], v156 offset:1024
	ds_read_b128 v[152:155], v156 offset:2048
	ds_read_b128 v[156:159], v156 offset:3072
	ds_read_b128 v[160:163], v172
	ds_read_b128 v[164:167], v172 offset:1024
	ds_read_b128 v[168:171], v172 offset:2048
	ds_read_b128 v[172:175], v172 offset:3072
	v_lshl_add_u64 v[208:209], s[12:13], 0, v[136:137]
	s_add_i32 m0, s38, 0xc000
	ds_read_b128 v[176:179], v143
	ds_read_b128 v[180:183], v143 offset:1024
	ds_read_b128 v[184:187], v143 offset:2048
	ds_read_b128 v[188:191], v143 offset:3072
	ds_read_b128 v[192:195], v143 offset:4096
	ds_read_b128 v[196:199], v143 offset:5120
	ds_read_b128 v[200:203], v143 offset:6144
	ds_read_b128 v[204:207], v143 offset:7168
	global_load_lds_dwordx4 v[208:209], off
	v_lshl_add_u64 v[208:209], s[12:13], 0, v[138:139]
	s_add_i32 m0, s38, 0xe000
	s_nop 0
	global_load_lds_dwordx4 v[208:209], off
	s_waitcnt vmcnt(8)
	s_waitcnt lgkmcnt(0)
	s_setprio 1
	s_barrier
	v_mfma_f32_16x16x32_bf16 v[126:129], v[144:147], v[176:179], 0
	v_mfma_f32_16x16x32_bf16 v[122:125], v[152:155], v[176:179], 0
	v_mfma_f32_16x16x32_bf16 v[118:121], v[144:147], v[184:187], 0
	v_mfma_f32_16x16x32_bf16 v[114:117], v[152:155], v[184:187], 0
	v_mfma_f32_16x16x32_bf16 v[102:105], v[144:147], v[192:195], 0
	v_mfma_f32_16x16x32_bf16 v[98:101], v[152:155], v[192:195], 0
	v_mfma_f32_16x16x32_bf16 v[86:89], v[144:147], v[200:203], 0
	v_mfma_f32_16x16x32_bf16 v[82:85], v[152:155], v[200:203], 0
	v_mfma_f32_16x16x32_bf16 v[126:129], v[148:151], v[180:183], v[126:129]
	v_mfma_f32_16x16x32_bf16 v[122:125], v[156:159], v[180:183], v[122:125]
	v_mfma_f32_16x16x32_bf16 v[118:121], v[148:151], v[188:191], v[118:121]
	v_mfma_f32_16x16x32_bf16 v[114:117], v[156:159], v[188:191], v[114:117]
	v_mfma_f32_16x16x32_bf16 v[102:105], v[148:151], v[196:199], v[102:105]
	v_mfma_f32_16x16x32_bf16 v[98:101], v[156:159], v[196:199], v[98:101]
	v_mfma_f32_16x16x32_bf16 v[86:89], v[148:151], v[204:207], v[86:89]
	v_mfma_f32_16x16x32_bf16 v[82:85], v[156:159], v[204:207], v[82:85]
	s_setprio 0
	s_setprio 1
	v_mfma_f32_16x16x32_bf16 v[110:113], v[160:163], v[176:179], 0
	v_mfma_f32_16x16x32_bf16 v[106:109], v[168:171], v[176:179], 0
	v_mfma_f32_16x16x32_bf16 v[94:97], v[160:163], v[184:187], 0
	v_mfma_f32_16x16x32_bf16 v[90:93], v[168:171], v[184:187], 0
	v_mfma_f32_16x16x32_bf16 v[78:81], v[160:163], v[192:195], 0
	v_mfma_f32_16x16x32_bf16 v[74:77], v[168:171], v[192:195], 0
	v_mfma_f32_16x16x32_bf16 v[70:73], v[160:163], v[200:203], 0
	v_mfma_f32_16x16x32_bf16 v[66:69], v[168:171], v[200:203], 0
	v_mfma_f32_16x16x32_bf16 v[110:113], v[164:167], v[180:183], v[110:113]
	v_mfma_f32_16x16x32_bf16 v[106:109], v[172:175], v[180:183], v[106:109]
	v_mfma_f32_16x16x32_bf16 v[94:97], v[164:167], v[188:191], v[94:97]
	v_mfma_f32_16x16x32_bf16 v[90:93], v[172:175], v[188:191], v[90:93]
	v_mfma_f32_16x16x32_bf16 v[78:81], v[164:167], v[196:199], v[78:81]
	v_mfma_f32_16x16x32_bf16 v[74:77], v[172:175], v[196:199], v[74:77]
	v_mfma_f32_16x16x32_bf16 v[70:73], v[164:167], v[204:207], v[70:73]
	v_mfma_f32_16x16x32_bf16 v[66:69], v[172:175], v[204:207], v[66:69]
	s_barrier
	s_setprio 0
	s_add_i32 s51, s51, s24
	v_lshl_add_u64 v[208:209], s[16:17], 0, v[0:1]
	s_mov_b32 m0, s51
	ds_read_b128 v[176:179], v143 offset:16384
	ds_read_b128 v[180:183], v143 offset:17408
	ds_read_b128 v[184:187], v143 offset:18432
	ds_read_b128 v[188:191], v143 offset:19456
	ds_read_b128 v[192:195], v143 offset:20480
	ds_read_b128 v[196:199], v143 offset:21504
	ds_read_b128 v[200:203], v143 offset:22528
	ds_read_b128 v[204:207], v143 offset:23552
	global_load_lds_dwordx4 v[208:209], off
	s_add_i32 m0, s51, 0x2000
	s_add_u32 s52, s16, 0x164000
	v_lshl_add_u64 v[216:217], s[16:17], 0, v[130:131]
	s_addc_u32 s53, s17, 0
	s_add_i32 s51, s54, s24
	global_load_lds_dwordx4 v[216:217], off
	v_lshl_add_u64 v[220:221], s[52:53], 0, v[0:1]
	s_mov_b32 m0, s51
	s_nop 0
	global_load_lds_dwordx4 v[220:221], off
	v_lshl_add_u64 v[220:221], s[52:53], 0, v[130:131]
	s_add_i32 m0, s51, 0x2000
	s_nop 0
	global_load_lds_dwordx4 v[220:221], off
	v_lshl_add_u64 v[220:221], s[18:19], 0, v[134:135]
	s_mov_b32 m0, s38
	s_nop 0
	global_load_lds_dwordx4 v[220:221], off
	v_lshl_add_u64 v[220:221], s[18:19], 0, v[132:133]
	s_mov_b32 m0, s39
	s_nop 0
	global_load_lds_dwordx4 v[220:221], off
	s_nop 0
	s_waitcnt vmcnt(8)
	s_waitcnt lgkmcnt(0)
	s_setprio 1
	s_barrier
	v_mfma_f32_16x16x32_bf16 v[62:65], v[144:147], v[176:179], 0
	v_mfma_f32_16x16x32_bf16 v[58:61], v[152:155], v[176:179], 0
	v_mfma_f32_16x16x32_bf16 v[54:57], v[144:147], v[184:187], 0
	v_mfma_f32_16x16x32_bf16 v[50:53], v[152:155], v[184:187], 0
	v_mfma_f32_16x16x32_bf16 v[38:41], v[144:147], v[192:195], 0
	v_mfma_f32_16x16x32_bf16 v[34:37], v[152:155], v[192:195], 0
	v_mfma_f32_16x16x32_bf16 v[22:25], v[144:147], v[200:203], 0
	v_mfma_f32_16x16x32_bf16 v[18:21], v[152:155], v[200:203], 0
	v_mfma_f32_16x16x32_bf16 v[62:65], v[148:151], v[180:183], v[62:65]
	v_mfma_f32_16x16x32_bf16 v[58:61], v[156:159], v[180:183], v[58:61]
	v_mfma_f32_16x16x32_bf16 v[54:57], v[148:151], v[188:191], v[54:57]
	v_mfma_f32_16x16x32_bf16 v[50:53], v[156:159], v[188:191], v[50:53]
	v_mfma_f32_16x16x32_bf16 v[38:41], v[148:151], v[196:199], v[38:41]
	v_mfma_f32_16x16x32_bf16 v[34:37], v[156:159], v[196:199], v[34:37]
	v_mfma_f32_16x16x32_bf16 v[22:25], v[148:151], v[204:207], v[22:25]
	v_mfma_f32_16x16x32_bf16 v[18:21], v[156:159], v[204:207], v[18:21]
	s_setprio 0
	s_setprio 1
	v_mfma_f32_16x16x32_bf16 v[46:49], v[160:163], v[176:179], 0
	v_mfma_f32_16x16x32_bf16 v[42:45], v[168:171], v[176:179], 0
	v_mfma_f32_16x16x32_bf16 v[30:33], v[160:163], v[184:187], 0
	v_mfma_f32_16x16x32_bf16 v[26:29], v[168:171], v[184:187], 0
	v_mfma_f32_16x16x32_bf16 v[14:17], v[160:163], v[192:195], 0
	v_mfma_f32_16x16x32_bf16 v[10:13], v[168:171], v[192:195], 0
	v_mfma_f32_16x16x32_bf16 v[6:9], v[160:163], v[200:203], 0
	v_mfma_f32_16x16x32_bf16 v[2:5], v[168:171], v[200:203], 0
	v_mfma_f32_16x16x32_bf16 v[46:49], v[164:167], v[180:183], v[46:49]
	v_mfma_f32_16x16x32_bf16 v[42:45], v[172:175], v[180:183], v[42:45]
	v_mfma_f32_16x16x32_bf16 v[30:33], v[164:167], v[188:191], v[30:33]
	v_mfma_f32_16x16x32_bf16 v[26:29], v[172:175], v[188:191], v[26:29]
	v_mfma_f32_16x16x32_bf16 v[14:17], v[164:167], v[196:199], v[14:17]
	v_mfma_f32_16x16x32_bf16 v[10:13], v[172:175], v[196:199], v[10:13]
	v_mfma_f32_16x16x32_bf16 v[6:9], v[164:167], v[204:207], v[6:9]
	v_mfma_f32_16x16x32_bf16 v[2:5], v[172:175], v[204:207], v[2:5]
	s_barrier
	s_setprio 0
	s_add_i32 s51, 0, 0x18000
	s_add_i32 s52, 0, 0x1c000
	v_add_u32_e32 v156, s51, v140
	v_add_u32_e32 v172, s52, v140
	ds_read_b128 v[144:147], v156
	ds_read_b128 v[148:151], v156 offset:1024
	ds_read_b128 v[152:155], v156 offset:2048
	ds_read_b128 v[156:159], v156 offset:3072
	ds_read_b128 v[160:163], v172
	ds_read_b128 v[164:167], v172 offset:1024
	ds_read_b128 v[168:171], v172 offset:2048
	ds_read_b128 v[172:175], v172 offset:3072
	s_add_u32 s18, s18, 0x4000
	s_addc_u32 s19, s19, 0
	s_mov_b32 m0, s40
	v_lshl_add_u64 v[220:221], s[18:19], 0, v[134:135]
	ds_read_b128 v[176:179], v143 offset:32768
	ds_read_b128 v[180:183], v143 offset:33792
	ds_read_b128 v[184:187], v143 offset:34816
	ds_read_b128 v[188:191], v143 offset:35840
	ds_read_b128 v[192:195], v143 offset:36864
	ds_read_b128 v[196:199], v143 offset:37888
	ds_read_b128 v[200:203], v143 offset:38912
	ds_read_b128 v[204:207], v143 offset:39936
	global_load_lds_dwordx4 v[220:221], off
	v_lshl_add_u64 v[220:221], s[18:19], 0, v[132:133]
	s_mov_b32 m0, s41
	s_nop 0
	global_load_lds_dwordx4 v[220:221], off
	s_waitcnt vmcnt(8)
	s_waitcnt lgkmcnt(0)
	s_setprio 1
	s_barrier
	v_mfma_f32_16x16x32_bf16 v[126:129], v[144:147], v[176:179], v[126:129]
	v_mfma_f32_16x16x32_bf16 v[122:125], v[152:155], v[176:179], v[122:125]
	v_mfma_f32_16x16x32_bf16 v[118:121], v[144:147], v[184:187], v[118:121]
	v_mfma_f32_16x16x32_bf16 v[114:117], v[152:155], v[184:187], v[114:117]
	v_mfma_f32_16x16x32_bf16 v[102:105], v[144:147], v[192:195], v[102:105]
	v_mfma_f32_16x16x32_bf16 v[98:101], v[152:155], v[192:195], v[98:101]
	v_mfma_f32_16x16x32_bf16 v[86:89], v[144:147], v[200:203], v[86:89]
	v_mfma_f32_16x16x32_bf16 v[82:85], v[152:155], v[200:203], v[82:85]
	v_mfma_f32_16x16x32_bf16 v[126:129], v[148:151], v[180:183], v[126:129]
	v_mfma_f32_16x16x32_bf16 v[122:125], v[156:159], v[180:183], v[122:125]
	v_mfma_f32_16x16x32_bf16 v[118:121], v[148:151], v[188:191], v[118:121]
	v_mfma_f32_16x16x32_bf16 v[114:117], v[156:159], v[188:191], v[114:117]
	v_mfma_f32_16x16x32_bf16 v[102:105], v[148:151], v[196:199], v[102:105]
	v_mfma_f32_16x16x32_bf16 v[98:101], v[156:159], v[196:199], v[98:101]
	v_mfma_f32_16x16x32_bf16 v[86:89], v[148:151], v[204:207], v[86:89]
	v_mfma_f32_16x16x32_bf16 v[82:85], v[156:159], v[204:207], v[82:85]
	s_setprio 0
	s_setprio 1
	v_mfma_f32_16x16x32_bf16 v[110:113], v[160:163], v[176:179], v[110:113]
	v_mfma_f32_16x16x32_bf16 v[106:109], v[168:171], v[176:179], v[106:109]
	v_mfma_f32_16x16x32_bf16 v[94:97], v[160:163], v[184:187], v[94:97]
	v_mfma_f32_16x16x32_bf16 v[90:93], v[168:171], v[184:187], v[90:93]
	v_mfma_f32_16x16x32_bf16 v[78:81], v[160:163], v[192:195], v[78:81]
	v_mfma_f32_16x16x32_bf16 v[74:77], v[168:171], v[192:195], v[74:77]
	v_mfma_f32_16x16x32_bf16 v[70:73], v[160:163], v[200:203], v[70:73]
	v_mfma_f32_16x16x32_bf16 v[66:69], v[168:171], v[200:203], v[66:69]
	v_mfma_f32_16x16x32_bf16 v[110:113], v[164:167], v[180:183], v[110:113]
	v_mfma_f32_16x16x32_bf16 v[106:109], v[172:175], v[180:183], v[106:109]
	v_mfma_f32_16x16x32_bf16 v[94:97], v[164:167], v[188:191], v[94:97]
	v_mfma_f32_16x16x32_bf16 v[90:93], v[172:175], v[188:191], v[90:93]
	v_mfma_f32_16x16x32_bf16 v[78:81], v[164:167], v[196:199], v[78:81]
	v_mfma_f32_16x16x32_bf16 v[74:77], v[172:175], v[196:199], v[74:77]
	v_mfma_f32_16x16x32_bf16 v[70:73], v[164:167], v[204:207], v[70:73]
	v_mfma_f32_16x16x32_bf16 v[66:69], v[172:175], v[204:207], v[66:69]
	s_barrier
	s_setprio 0
	s_add_i32 s18, s51, s24
	v_lshl_add_u64 v[208:209], v[208:209], 0, s[2:3]
	s_mov_b32 m0, s18
	ds_read_b128 v[176:179], v143 offset:49152
	ds_read_b128 v[180:183], v143 offset:50176
	ds_read_b128 v[184:187], v143 offset:51200
	ds_read_b128 v[188:191], v143 offset:52224
	ds_read_b128 v[192:195], v143 offset:53248
	ds_read_b128 v[196:199], v143 offset:54272
	ds_read_b128 v[200:203], v143 offset:55296
	ds_read_b128 v[204:207], v143 offset:56320
	global_load_lds_dwordx4 v[208:209], off
	s_add_i32 m0, s18, 0x2000
	s_add_u32 s16, s16, 0x164080
	v_lshl_add_u64 v[208:209], v[216:217], 0, s[2:3]
	s_addc_u32 s17, s17, 0
	s_add_i32 s18, s52, s24
	global_load_lds_dwordx4 v[208:209], off
	v_lshl_add_u64 v[208:209], s[16:17], 0, v[0:1]
	s_mov_b32 m0, s18
	s_nop 0
	global_load_lds_dwordx4 v[208:209], off
	v_lshl_add_u64 v[208:209], s[16:17], 0, v[130:131]
	s_add_i32 m0, s18, 0x2000
	s_nop 0
	global_load_lds_dwordx4 v[208:209], off
	v_lshl_add_u64 v[208:209], s[14:15], 0, v[134:135]
	s_mov_b32 m0, s42
	s_nop 0
	global_load_lds_dwordx4 v[208:209], off
	v_lshl_add_u64 v[208:209], s[14:15], 0, v[132:133]
	s_mov_b32 m0, s43
	s_nop 0
	global_load_lds_dwordx4 v[208:209], off
	s_nop 0
	s_waitcnt vmcnt(8)
	s_waitcnt lgkmcnt(0)
	s_setprio 1
	s_barrier
	v_mfma_f32_16x16x32_bf16 v[62:65], v[144:147], v[176:179], v[62:65]
	v_mfma_f32_16x16x32_bf16 v[58:61], v[152:155], v[176:179], v[58:61]
	v_mfma_f32_16x16x32_bf16 v[54:57], v[144:147], v[184:187], v[54:57]
	v_mfma_f32_16x16x32_bf16 v[50:53], v[152:155], v[184:187], v[50:53]
	v_mfma_f32_16x16x32_bf16 v[38:41], v[144:147], v[192:195], v[38:41]
	v_mfma_f32_16x16x32_bf16 v[34:37], v[152:155], v[192:195], v[34:37]
	v_mfma_f32_16x16x32_bf16 v[22:25], v[144:147], v[200:203], v[22:25]
	v_mfma_f32_16x16x32_bf16 v[18:21], v[152:155], v[200:203], v[18:21]
	v_mfma_f32_16x16x32_bf16 v[62:65], v[148:151], v[180:183], v[62:65]
	v_mfma_f32_16x16x32_bf16 v[58:61], v[156:159], v[180:183], v[58:61]
	v_mfma_f32_16x16x32_bf16 v[54:57], v[148:151], v[188:191], v[54:57]
	v_mfma_f32_16x16x32_bf16 v[50:53], v[156:159], v[188:191], v[50:53]
	v_mfma_f32_16x16x32_bf16 v[38:41], v[148:151], v[196:199], v[38:41]
	v_mfma_f32_16x16x32_bf16 v[34:37], v[156:159], v[196:199], v[34:37]
	v_mfma_f32_16x16x32_bf16 v[22:25], v[148:151], v[204:207], v[22:25]
	v_mfma_f32_16x16x32_bf16 v[18:21], v[156:159], v[204:207], v[18:21]
	s_setprio 0
	s_setprio 1
	v_mfma_f32_16x16x32_bf16 v[46:49], v[160:163], v[176:179], v[46:49]
	v_mfma_f32_16x16x32_bf16 v[42:45], v[168:171], v[176:179], v[42:45]
	v_mfma_f32_16x16x32_bf16 v[30:33], v[160:163], v[184:187], v[30:33]
	v_mfma_f32_16x16x32_bf16 v[26:29], v[168:171], v[184:187], v[26:29]
	v_mfma_f32_16x16x32_bf16 v[14:17], v[160:163], v[192:195], v[14:17]
	v_mfma_f32_16x16x32_bf16 v[10:13], v[168:171], v[192:195], v[10:13]
	v_mfma_f32_16x16x32_bf16 v[6:9], v[160:163], v[200:203], v[6:9]
	v_mfma_f32_16x16x32_bf16 v[2:5], v[168:171], v[200:203], v[2:5]
	v_mfma_f32_16x16x32_bf16 v[46:49], v[164:167], v[180:183], v[46:49]
	v_mfma_f32_16x16x32_bf16 v[42:45], v[172:175], v[180:183], v[42:45]
	v_mfma_f32_16x16x32_bf16 v[30:33], v[164:167], v[188:191], v[30:33]
	v_mfma_f32_16x16x32_bf16 v[26:29], v[172:175], v[188:191], v[26:29]
	v_mfma_f32_16x16x32_bf16 v[14:17], v[164:167], v[196:199], v[14:17]
	v_mfma_f32_16x16x32_bf16 v[10:13], v[172:175], v[196:199], v[10:13]
	v_mfma_f32_16x16x32_bf16 v[6:9], v[164:167], v[204:207], v[6:9]
	v_mfma_f32_16x16x32_bf16 v[2:5], v[172:175], v[204:207], v[2:5]
	s_barrier
	s_setprio 0
	s_add_i32 s50, s50, 2
	s_add_u32 s36, s36, 0x100
	s_addc_u32 s37, s37, 0
	s_add_u32 s12, s12, 0x10000
	s_addc_u32 s13, s13, 0
	s_cmp_gt_u32 s50, 19
	s_cbranch_scc1 .Lpeel_done_6
.LBB0_2017:
	s_add_u32 s14, s12, 0x4000
	s_addc_u32 s15, s13, 0
	s_cmp_eq_u32 s50, 18
	s_cselect_b32 s18, s8, s14
	s_cselect_b32 s19, s9, s15
	s_cselect_b32 s16, s10, s36
	s_cselect_b32 s17, s11, s37
	s_add_u32 s14, s18, 0x8000
	s_addc_u32 s15, s19, 0
	s_add_i32 s51, 0, 0x10000
	s_add_i32 s54, 0, 0x14000
	v_add_u32_e32 v156, s51, v140
	v_add_u32_e32 v172, s54, v140
	ds_read_b128 v[144:147], v156
	ds_read_b128 v[148:151], v156 offset:1024
	ds_read_b128 v[152:155], v156 offset:2048
	ds_read_b128 v[156:159], v156 offset:3072
	ds_read_b128 v[160:163], v172
	ds_read_b128 v[164:167], v172 offset:1024
	ds_read_b128 v[168:171], v172 offset:2048
	ds_read_b128 v[172:175], v172 offset:3072
	v_lshl_add_u64 v[208:209], s[12:13], 0, v[136:137]
	s_add_i32 m0, s38, 0xc000
	ds_read_b128 v[176:179], v143
	ds_read_b128 v[180:183], v143 offset:1024
	ds_read_b128 v[184:187], v143 offset:2048
	ds_read_b128 v[188:191], v143 offset:3072
	ds_read_b128 v[192:195], v143 offset:4096
	ds_read_b128 v[196:199], v143 offset:5120
	ds_read_b128 v[200:203], v143 offset:6144
	ds_read_b128 v[204:207], v143 offset:7168
	global_load_lds_dwordx4 v[208:209], off
	v_lshl_add_u64 v[208:209], s[12:13], 0, v[138:139]
	s_add_i32 m0, s38, 0xe000
	s_nop 0
	global_load_lds_dwordx4 v[208:209], off
	s_nop 0
	s_waitcnt vmcnt(8)
	s_waitcnt lgkmcnt(0)
	s_setprio 1
	s_barrier
	v_mfma_f32_16x16x32_bf16 v[126:129], v[144:147], v[176:179], v[126:129]
	v_mfma_f32_16x16x32_bf16 v[122:125], v[152:155], v[176:179], v[122:125]
	v_mfma_f32_16x16x32_bf16 v[118:121], v[144:147], v[184:187], v[118:121]
	v_mfma_f32_16x16x32_bf16 v[114:117], v[152:155], v[184:187], v[114:117]
	v_mfma_f32_16x16x32_bf16 v[102:105], v[144:147], v[192:195], v[102:105]
	v_mfma_f32_16x16x32_bf16 v[98:101], v[152:155], v[192:195], v[98:101]
	v_mfma_f32_16x16x32_bf16 v[86:89], v[144:147], v[200:203], v[86:89]
	v_mfma_f32_16x16x32_bf16 v[82:85], v[152:155], v[200:203], v[82:85]
	v_mfma_f32_16x16x32_bf16 v[126:129], v[148:151], v[180:183], v[126:129]
	v_mfma_f32_16x16x32_bf16 v[122:125], v[156:159], v[180:183], v[122:125]
	v_mfma_f32_16x16x32_bf16 v[118:121], v[148:151], v[188:191], v[118:121]
	v_mfma_f32_16x16x32_bf16 v[114:117], v[156:159], v[188:191], v[114:117]
	v_mfma_f32_16x16x32_bf16 v[102:105], v[148:151], v[196:199], v[102:105]
	v_mfma_f32_16x16x32_bf16 v[98:101], v[156:159], v[196:199], v[98:101]
	v_mfma_f32_16x16x32_bf16 v[86:89], v[148:151], v[204:207], v[86:89]
	v_mfma_f32_16x16x32_bf16 v[82:85], v[156:159], v[204:207], v[82:85]
	s_setprio 0
	s_setprio 1
	v_mfma_f32_16x16x32_bf16 v[110:113], v[160:163], v[176:179], v[110:113]
	v_mfma_f32_16x16x32_bf16 v[106:109], v[168:171], v[176:179], v[106:109]
	v_mfma_f32_16x16x32_bf16 v[94:97], v[160:163], v[184:187], v[94:97]
	v_mfma_f32_16x16x32_bf16 v[90:93], v[168:171], v[184:187], v[90:93]
	v_mfma_f32_16x16x32_bf16 v[78:81], v[160:163], v[192:195], v[78:81]
	v_mfma_f32_16x16x32_bf16 v[74:77], v[168:171], v[192:195], v[74:77]
	v_mfma_f32_16x16x32_bf16 v[70:73], v[160:163], v[200:203], v[70:73]
	v_mfma_f32_16x16x32_bf16 v[66:69], v[168:171], v[200:203], v[66:69]
	v_mfma_f32_16x16x32_bf16 v[110:113], v[164:167], v[180:183], v[110:113]
	v_mfma_f32_16x16x32_bf16 v[106:109], v[172:175], v[180:183], v[106:109]
	v_mfma_f32_16x16x32_bf16 v[94:97], v[164:167], v[188:191], v[94:97]
	v_mfma_f32_16x16x32_bf16 v[90:93], v[172:175], v[188:191], v[90:93]
	v_mfma_f32_16x16x32_bf16 v[78:81], v[164:167], v[196:199], v[78:81]
	v_mfma_f32_16x16x32_bf16 v[74:77], v[172:175], v[196:199], v[74:77]
	v_mfma_f32_16x16x32_bf16 v[70:73], v[164:167], v[204:207], v[70:73]
	v_mfma_f32_16x16x32_bf16 v[66:69], v[172:175], v[204:207], v[66:69]
	s_barrier
	s_setprio 0
	s_add_i32 s51, s51, s24
	v_lshl_add_u64 v[208:209], s[16:17], 0, v[0:1]
	s_mov_b32 m0, s51
	ds_read_b128 v[176:179], v143 offset:16384
	ds_read_b128 v[180:183], v143 offset:17408
	ds_read_b128 v[184:187], v143 offset:18432
	ds_read_b128 v[188:191], v143 offset:19456
	ds_read_b128 v[192:195], v143 offset:20480
	ds_read_b128 v[196:199], v143 offset:21504
	ds_read_b128 v[200:203], v143 offset:22528
	ds_read_b128 v[204:207], v143 offset:23552
	global_load_lds_dwordx4 v[208:209], off
	s_add_i32 m0, s51, 0x2000
	s_add_u32 s52, s16, 0x164000
	v_lshl_add_u64 v[216:217], s[16:17], 0, v[130:131]
	s_addc_u32 s53, s17, 0
	s_add_i32 s51, s54, s24
	global_load_lds_dwordx4 v[216:217], off
	v_lshl_add_u64 v[220:221], s[52:53], 0, v[0:1]
	s_mov_b32 m0, s51
	s_nop 0
	global_load_lds_dwordx4 v[220:221], off
	v_lshl_add_u64 v[220:221], s[52:53], 0, v[130:131]
	s_add_i32 m0, s51, 0x2000
	s_nop 0
	global_load_lds_dwordx4 v[220:221], off
	v_lshl_add_u64 v[220:221], s[18:19], 0, v[134:135]
	s_mov_b32 m0, s38
	s_nop 0
	global_load_lds_dwordx4 v[220:221], off
	v_lshl_add_u64 v[220:221], s[18:19], 0, v[132:133]
	s_mov_b32 m0, s39
	s_nop 0
	global_load_lds_dwordx4 v[220:221], off
	s_nop 0
	s_waitcnt vmcnt(8)
	s_waitcnt lgkmcnt(0)
	s_setprio 1
	s_barrier
	v_mfma_f32_16x16x32_bf16 v[62:65], v[144:147], v[176:179], v[62:65]
	v_mfma_f32_16x16x32_bf16 v[58:61], v[152:155], v[176:179], v[58:61]
	v_mfma_f32_16x16x32_bf16 v[54:57], v[144:147], v[184:187], v[54:57]
	v_mfma_f32_16x16x32_bf16 v[50:53], v[152:155], v[184:187], v[50:53]
	v_mfma_f32_16x16x32_bf16 v[38:41], v[144:147], v[192:195], v[38:41]
	v_mfma_f32_16x16x32_bf16 v[34:37], v[152:155], v[192:195], v[34:37]
	v_mfma_f32_16x16x32_bf16 v[22:25], v[144:147], v[200:203], v[22:25]
	v_mfma_f32_16x16x32_bf16 v[18:21], v[152:155], v[200:203], v[18:21]
	v_mfma_f32_16x16x32_bf16 v[62:65], v[148:151], v[180:183], v[62:65]
	v_mfma_f32_16x16x32_bf16 v[58:61], v[156:159], v[180:183], v[58:61]
	v_mfma_f32_16x16x32_bf16 v[54:57], v[148:151], v[188:191], v[54:57]
	v_mfma_f32_16x16x32_bf16 v[50:53], v[156:159], v[188:191], v[50:53]
	v_mfma_f32_16x16x32_bf16 v[38:41], v[148:151], v[196:199], v[38:41]
	v_mfma_f32_16x16x32_bf16 v[34:37], v[156:159], v[196:199], v[34:37]
	v_mfma_f32_16x16x32_bf16 v[22:25], v[148:151], v[204:207], v[22:25]
	v_mfma_f32_16x16x32_bf16 v[18:21], v[156:159], v[204:207], v[18:21]
	s_setprio 0
	s_setprio 1
	v_mfma_f32_16x16x32_bf16 v[46:49], v[160:163], v[176:179], v[46:49]
	v_mfma_f32_16x16x32_bf16 v[42:45], v[168:171], v[176:179], v[42:45]
	v_mfma_f32_16x16x32_bf16 v[30:33], v[160:163], v[184:187], v[30:33]
	v_mfma_f32_16x16x32_bf16 v[26:29], v[168:171], v[184:187], v[26:29]
	v_mfma_f32_16x16x32_bf16 v[14:17], v[160:163], v[192:195], v[14:17]
	v_mfma_f32_16x16x32_bf16 v[10:13], v[168:171], v[192:195], v[10:13]
	v_mfma_f32_16x16x32_bf16 v[6:9], v[160:163], v[200:203], v[6:9]
	v_mfma_f32_16x16x32_bf16 v[2:5], v[168:171], v[200:203], v[2:5]
	v_mfma_f32_16x16x32_bf16 v[46:49], v[164:167], v[180:183], v[46:49]
	v_mfma_f32_16x16x32_bf16 v[42:45], v[172:175], v[180:183], v[42:45]
	v_mfma_f32_16x16x32_bf16 v[30:33], v[164:167], v[188:191], v[30:33]
	v_mfma_f32_16x16x32_bf16 v[26:29], v[172:175], v[188:191], v[26:29]
	v_mfma_f32_16x16x32_bf16 v[14:17], v[164:167], v[196:199], v[14:17]
	v_mfma_f32_16x16x32_bf16 v[10:13], v[172:175], v[196:199], v[10:13]
	v_mfma_f32_16x16x32_bf16 v[6:9], v[164:167], v[204:207], v[6:9]
	v_mfma_f32_16x16x32_bf16 v[2:5], v[172:175], v[204:207], v[2:5]
	s_barrier
	s_setprio 0
	s_add_i32 s51, 0, 0x18000
	s_add_i32 s52, 0, 0x1c000
	v_add_u32_e32 v156, s51, v140
	v_add_u32_e32 v172, s52, v140
	ds_read_b128 v[144:147], v156
	ds_read_b128 v[148:151], v156 offset:1024
	ds_read_b128 v[152:155], v156 offset:2048
	ds_read_b128 v[156:159], v156 offset:3072
	ds_read_b128 v[160:163], v172
	ds_read_b128 v[164:167], v172 offset:1024
	ds_read_b128 v[168:171], v172 offset:2048
	ds_read_b128 v[172:175], v172 offset:3072
	s_add_u32 s18, s18, 0x4000
	s_addc_u32 s19, s19, 0
	s_mov_b32 m0, s40
	v_lshl_add_u64 v[220:221], s[18:19], 0, v[134:135]
	ds_read_b128 v[176:179], v143 offset:32768
	ds_read_b128 v[180:183], v143 offset:33792
	ds_read_b128 v[184:187], v143 offset:34816
	ds_read_b128 v[188:191], v143 offset:35840
	ds_read_b128 v[192:195], v143 offset:36864
	ds_read_b128 v[196:199], v143 offset:37888
	ds_read_b128 v[200:203], v143 offset:38912
	ds_read_b128 v[204:207], v143 offset:39936
	global_load_lds_dwordx4 v[220:221], off
	v_lshl_add_u64 v[220:221], s[18:19], 0, v[132:133]
	s_mov_b32 m0, s41
	s_nop 0
	global_load_lds_dwordx4 v[220:221], off
	s_waitcnt vmcnt(8)
	s_waitcnt lgkmcnt(0)
	s_setprio 1
	s_barrier
	v_mfma_f32_16x16x32_bf16 v[126:129], v[144:147], v[176:179], v[126:129]
	v_mfma_f32_16x16x32_bf16 v[122:125], v[152:155], v[176:179], v[122:125]
	v_mfma_f32_16x16x32_bf16 v[118:121], v[144:147], v[184:187], v[118:121]
	v_mfma_f32_16x16x32_bf16 v[114:117], v[152:155], v[184:187], v[114:117]
	v_mfma_f32_16x16x32_bf16 v[102:105], v[144:147], v[192:195], v[102:105]
	v_mfma_f32_16x16x32_bf16 v[98:101], v[152:155], v[192:195], v[98:101]
	v_mfma_f32_16x16x32_bf16 v[86:89], v[144:147], v[200:203], v[86:89]
	v_mfma_f32_16x16x32_bf16 v[82:85], v[152:155], v[200:203], v[82:85]
	v_mfma_f32_16x16x32_bf16 v[126:129], v[148:151], v[180:183], v[126:129]
	v_mfma_f32_16x16x32_bf16 v[122:125], v[156:159], v[180:183], v[122:125]
	v_mfma_f32_16x16x32_bf16 v[118:121], v[148:151], v[188:191], v[118:121]
	v_mfma_f32_16x16x32_bf16 v[114:117], v[156:159], v[188:191], v[114:117]
	v_mfma_f32_16x16x32_bf16 v[102:105], v[148:151], v[196:199], v[102:105]
	v_mfma_f32_16x16x32_bf16 v[98:101], v[156:159], v[196:199], v[98:101]
	v_mfma_f32_16x16x32_bf16 v[86:89], v[148:151], v[204:207], v[86:89]
	v_mfma_f32_16x16x32_bf16 v[82:85], v[156:159], v[204:207], v[82:85]
	s_setprio 0
	s_setprio 1
	v_mfma_f32_16x16x32_bf16 v[110:113], v[160:163], v[176:179], v[110:113]
	v_mfma_f32_16x16x32_bf16 v[106:109], v[168:171], v[176:179], v[106:109]
	v_mfma_f32_16x16x32_bf16 v[94:97], v[160:163], v[184:187], v[94:97]
	v_mfma_f32_16x16x32_bf16 v[90:93], v[168:171], v[184:187], v[90:93]
	v_mfma_f32_16x16x32_bf16 v[78:81], v[160:163], v[192:195], v[78:81]
	v_mfma_f32_16x16x32_bf16 v[74:77], v[168:171], v[192:195], v[74:77]
	v_mfma_f32_16x16x32_bf16 v[70:73], v[160:163], v[200:203], v[70:73]
	v_mfma_f32_16x16x32_bf16 v[66:69], v[168:171], v[200:203], v[66:69]
	v_mfma_f32_16x16x32_bf16 v[110:113], v[164:167], v[180:183], v[110:113]
	v_mfma_f32_16x16x32_bf16 v[106:109], v[172:175], v[180:183], v[106:109]
	v_mfma_f32_16x16x32_bf16 v[94:97], v[164:167], v[188:191], v[94:97]
	v_mfma_f32_16x16x32_bf16 v[90:93], v[172:175], v[188:191], v[90:93]
	v_mfma_f32_16x16x32_bf16 v[78:81], v[164:167], v[196:199], v[78:81]
	v_mfma_f32_16x16x32_bf16 v[74:77], v[172:175], v[196:199], v[74:77]
	v_mfma_f32_16x16x32_bf16 v[70:73], v[164:167], v[204:207], v[70:73]
	v_mfma_f32_16x16x32_bf16 v[66:69], v[172:175], v[204:207], v[66:69]
	s_barrier
	s_setprio 0
	s_add_i32 s18, s51, s24
	v_lshl_add_u64 v[208:209], v[208:209], 0, s[2:3]
	s_mov_b32 m0, s18
	ds_read_b128 v[176:179], v143 offset:49152
	ds_read_b128 v[180:183], v143 offset:50176
	ds_read_b128 v[184:187], v143 offset:51200
	ds_read_b128 v[188:191], v143 offset:52224
	ds_read_b128 v[192:195], v143 offset:53248
	ds_read_b128 v[196:199], v143 offset:54272
	ds_read_b128 v[200:203], v143 offset:55296
	ds_read_b128 v[204:207], v143 offset:56320
	global_load_lds_dwordx4 v[208:209], off
	s_add_i32 m0, s18, 0x2000
	s_add_u32 s16, s16, 0x164080
	v_lshl_add_u64 v[208:209], v[216:217], 0, s[2:3]
	s_addc_u32 s17, s17, 0
	s_add_i32 s18, s52, s24
	global_load_lds_dwordx4 v[208:209], off
	v_lshl_add_u64 v[208:209], s[16:17], 0, v[0:1]
	s_mov_b32 m0, s18
	s_nop 0
	global_load_lds_dwordx4 v[208:209], off
	v_lshl_add_u64 v[208:209], s[16:17], 0, v[130:131]
	s_add_i32 m0, s18, 0x2000
	s_nop 0
	global_load_lds_dwordx4 v[208:209], off
	v_lshl_add_u64 v[208:209], s[14:15], 0, v[134:135]
	s_mov_b32 m0, s42
	s_nop 0
	global_load_lds_dwordx4 v[208:209], off
	v_lshl_add_u64 v[208:209], s[14:15], 0, v[132:133]
	s_mov_b32 m0, s43
	s_nop 0
	global_load_lds_dwordx4 v[208:209], off
	s_nop 0
	s_waitcnt vmcnt(8)
	s_waitcnt lgkmcnt(0)
	s_setprio 1
	s_barrier
	v_mfma_f32_16x16x32_bf16 v[62:65], v[144:147], v[176:179], v[62:65]
	v_mfma_f32_16x16x32_bf16 v[58:61], v[152:155], v[176:179], v[58:61]
	v_mfma_f32_16x16x32_bf16 v[54:57], v[144:147], v[184:187], v[54:57]
	v_mfma_f32_16x16x32_bf16 v[50:53], v[152:155], v[184:187], v[50:53]
	v_mfma_f32_16x16x32_bf16 v[38:41], v[144:147], v[192:195], v[38:41]
	v_mfma_f32_16x16x32_bf16 v[34:37], v[152:155], v[192:195], v[34:37]
	v_mfma_f32_16x16x32_bf16 v[22:25], v[144:147], v[200:203], v[22:25]
	v_mfma_f32_16x16x32_bf16 v[18:21], v[152:155], v[200:203], v[18:21]
	v_mfma_f32_16x16x32_bf16 v[62:65], v[148:151], v[180:183], v[62:65]
	v_mfma_f32_16x16x32_bf16 v[58:61], v[156:159], v[180:183], v[58:61]
	v_mfma_f32_16x16x32_bf16 v[54:57], v[148:151], v[188:191], v[54:57]
	v_mfma_f32_16x16x32_bf16 v[50:53], v[156:159], v[188:191], v[50:53]
	v_mfma_f32_16x16x32_bf16 v[38:41], v[148:151], v[196:199], v[38:41]
	v_mfma_f32_16x16x32_bf16 v[34:37], v[156:159], v[196:199], v[34:37]
	v_mfma_f32_16x16x32_bf16 v[22:25], v[148:151], v[204:207], v[22:25]
	v_mfma_f32_16x16x32_bf16 v[18:21], v[156:159], v[204:207], v[18:21]
	s_setprio 0
	s_setprio 1
	v_mfma_f32_16x16x32_bf16 v[46:49], v[160:163], v[176:179], v[46:49]
	v_mfma_f32_16x16x32_bf16 v[42:45], v[168:171], v[176:179], v[42:45]
	v_mfma_f32_16x16x32_bf16 v[30:33], v[160:163], v[184:187], v[30:33]
	v_mfma_f32_16x16x32_bf16 v[26:29], v[168:171], v[184:187], v[26:29]
	v_mfma_f32_16x16x32_bf16 v[14:17], v[160:163], v[192:195], v[14:17]
	v_mfma_f32_16x16x32_bf16 v[10:13], v[168:171], v[192:195], v[10:13]
	v_mfma_f32_16x16x32_bf16 v[6:9], v[160:163], v[200:203], v[6:9]
	v_mfma_f32_16x16x32_bf16 v[2:5], v[168:171], v[200:203], v[2:5]
	v_mfma_f32_16x16x32_bf16 v[46:49], v[164:167], v[180:183], v[46:49]
	v_mfma_f32_16x16x32_bf16 v[42:45], v[172:175], v[180:183], v[42:45]
	v_mfma_f32_16x16x32_bf16 v[30:33], v[164:167], v[188:191], v[30:33]
	v_mfma_f32_16x16x32_bf16 v[26:29], v[172:175], v[188:191], v[26:29]
	v_mfma_f32_16x16x32_bf16 v[14:17], v[164:167], v[196:199], v[14:17]
	v_mfma_f32_16x16x32_bf16 v[10:13], v[172:175], v[196:199], v[10:13]
	v_mfma_f32_16x16x32_bf16 v[6:9], v[164:167], v[204:207], v[6:9]
	v_mfma_f32_16x16x32_bf16 v[2:5], v[172:175], v[204:207], v[2:5]
	s_barrier
	s_setprio 0
	s_add_i32 s50, s50, 2
	s_add_u32 s36, s36, 0x100
	s_addc_u32 s37, s37, 0
	s_add_u32 s12, s12, 0x10000
	s_addc_u32 s13, s13, 0
	s_cmp_gt_u32 s50, 19
	s_cbranch_scc0 .LBB0_2017
